# attention: next head's sink load issued ahead of the previous head's stores, wait counts the stores (vmcnt(2))
# baseline (speedup 1.0000x reference)
.LBB0_497:
	v_mov_b32_e32 v0, v173
	s_add_i32 s4, s36, s18
	s_lshl_b32 s2, s80, 4
	s_or_b32 s5, s2, 0x4000
	v_and_b32_e32 v177, 15, v0
	v_or_b32_e32 v181, s4, v177
	v_add_u32_e32 v1, s82, v181
	v_or_b32_e32 v92, s5, v177
	v_cndmask_b32_e64 v176, v1, v92, s[38:39]
	v_lshlrev_b32_e32 v92, 1, v0
	v_and_or_b32 v92, v92, 30, s21
	s_movk_i32 s8, 0xd0
	v_mul_lo_u32 v92, v92, s8
	v_and_b32_e32 v179, -16, v0
	v_add3_u32 v168, 0, v92, v179
	ds_read_b128 v[92:95], v168
	ds_read_b128 v[96:99], v168 offset:64
	ds_read_b128 v[100:103], v168 offset:208
	ds_read_b128 v[104:107], v168 offset:272
	ds_read_b128 v[108:111], v168 offset:6656
	ds_read_b128 v[112:115], v168 offset:6720
	ds_read_b128 v[116:119], v168 offset:6864
	ds_read_b128 v[120:123], v168 offset:6928
	ds_read_b128 v[124:127], v168 offset:13312
	ds_read_b128 v[128:131], v168 offset:13376
	ds_read_b128 v[132:135], v168 offset:13520
	ds_read_b128 v[136:139], v168 offset:13584
	s_lshl_b32 s42, s37, 2
	s_add_i32 s3, s36, 0xffffff80
	v_ashrrev_i32_e32 v1, 4, v0
	s_waitcnt vmcnt(7) lgkmcnt(11)
	v_mfma_f32_16x16x32_bf16 v[92:95], v[92:95], v[88:91], 0
	s_waitcnt vmcnt(6) lgkmcnt(10)
	v_mfma_f32_16x16x32_bf16 v[184:187], v[96:99], v[84:87], v[92:95]
	s_waitcnt lgkmcnt(9)
	v_mfma_f32_16x16x32_bf16 v[92:95], v[100:103], v[88:91], 0
	s_waitcnt lgkmcnt(8)
	v_mfma_f32_16x16x32_bf16 v[192:195], v[104:107], v[84:87], v[92:95]
	s_waitcnt lgkmcnt(7)
	v_mfma_f32_16x16x32_bf16 v[92:95], v[108:111], v[88:91], 0
	s_waitcnt lgkmcnt(6)
	v_mfma_f32_16x16x32_bf16 v[160:163], v[112:115], v[84:87], v[92:95]
	s_waitcnt lgkmcnt(5)
	v_mfma_f32_16x16x32_bf16 v[92:95], v[116:119], v[88:91], 0
	s_waitcnt lgkmcnt(4)
	v_mfma_f32_16x16x32_bf16 v[156:159], v[120:123], v[84:87], v[92:95]
	s_waitcnt lgkmcnt(3)
	v_mfma_f32_16x16x32_bf16 v[92:95], v[124:127], v[88:91], 0
	s_waitcnt lgkmcnt(2)
	v_mfma_f32_16x16x32_bf16 v[152:155], v[128:131], v[84:87], v[92:95]
	s_waitcnt lgkmcnt(1)
	v_mfma_f32_16x16x32_bf16 v[92:95], v[132:135], v[88:91], 0
	s_waitcnt lgkmcnt(0)
	v_mfma_f32_16x16x32_bf16 v[148:151], v[136:139], v[84:87], v[92:95]
	s_nop 5
	ds_read_b128 v[92:95], v168 offset:19968
	ds_read_b128 v[96:99], v168 offset:20032
	ds_read_b128 v[100:103], v168 offset:20176
	ds_read_b128 v[104:107], v168 offset:20240
	ds_read_b128 v[108:111], v168 offset:26624
	ds_read_b128 v[112:115], v168 offset:26688
	ds_read_b128 v[116:119], v168 offset:26832
	ds_read_b128 v[120:123], v168 offset:26896
	ds_read_b128 v[124:127], v168 offset:33280
	ds_read_b128 v[128:131], v168 offset:33344
	ds_read_b128 v[188:191], v168 offset:33488
	ds_read_b128 v[196:199], v168 offset:33552
	s_waitcnt lgkmcnt(11)
	v_mfma_f32_16x16x32_bf16 v[92:95], v[92:95], v[88:91], 0
	s_waitcnt lgkmcnt(10)
	v_mfma_f32_16x16x32_bf16 v[144:147], v[96:99], v[84:87], v[92:95]
	s_waitcnt lgkmcnt(9)
	v_mfma_f32_16x16x32_bf16 v[92:95], v[100:103], v[88:91], 0
	s_waitcnt lgkmcnt(8)
	v_mfma_f32_16x16x32_bf16 v[140:143], v[104:107], v[84:87], v[92:95]
	s_waitcnt lgkmcnt(7)
	v_mfma_f32_16x16x32_bf16 v[92:95], v[108:111], v[88:91], 0
	s_waitcnt lgkmcnt(6)
	v_mfma_f32_16x16x32_bf16 v[136:139], v[112:115], v[84:87], v[92:95]
	s_waitcnt lgkmcnt(5)
	v_mfma_f32_16x16x32_bf16 v[92:95], v[116:119], v[88:91], 0
	s_waitcnt lgkmcnt(4)
	v_mfma_f32_16x16x32_bf16 v[132:135], v[120:123], v[84:87], v[92:95]
	s_waitcnt lgkmcnt(3)
	v_mfma_f32_16x16x32_bf16 v[92:95], v[124:127], v[88:91], 0
	s_waitcnt lgkmcnt(2)
	v_mfma_f32_16x16x32_bf16 v[128:131], v[128:131], v[84:87], v[92:95]
	s_waitcnt lgkmcnt(1)
	v_mfma_f32_16x16x32_bf16 v[92:95], v[188:191], v[88:91], 0
	s_waitcnt lgkmcnt(0)
	v_mfma_f32_16x16x32_bf16 v[124:127], v[196:199], v[84:87], v[92:95]
	s_nop 5
	ds_read_b128 v[92:95], v168 offset:39936
	ds_read_b128 v[96:99], v168 offset:40000
	ds_read_b128 v[100:103], v168 offset:40144
	ds_read_b128 v[104:107], v168 offset:40208
	ds_read_b128 v[108:111], v168 offset:46592
	ds_read_b128 v[112:115], v168 offset:46656
	ds_read_b128 v[188:191], v168 offset:46800
	ds_read_b128 v[196:199], v168 offset:46864
	ds_read_b128 v[200:203], v168 offset:53248
	ds_read_b128 v[204:207], v168 offset:53312
	ds_read_b128 v[208:211], v168 offset:53456
	ds_read_b128 v[220:223], v168 offset:53520
	s_waitcnt lgkmcnt(11)
	v_mfma_f32_16x16x32_bf16 v[92:95], v[92:95], v[88:91], 0
	s_waitcnt lgkmcnt(10)
	v_mfma_f32_16x16x32_bf16 v[120:123], v[96:99], v[84:87], v[92:95]
	s_waitcnt lgkmcnt(9)
	v_mfma_f32_16x16x32_bf16 v[92:95], v[100:103], v[88:91], 0
	s_waitcnt lgkmcnt(8)
	v_mfma_f32_16x16x32_bf16 v[116:119], v[104:107], v[84:87], v[92:95]
	s_waitcnt lgkmcnt(7)
	v_mfma_f32_16x16x32_bf16 v[92:95], v[108:111], v[88:91], 0
	s_waitcnt lgkmcnt(6)
	v_mfma_f32_16x16x32_bf16 v[112:115], v[112:115], v[84:87], v[92:95]
	s_waitcnt lgkmcnt(5)
	v_mfma_f32_16x16x32_bf16 v[92:95], v[188:191], v[88:91], 0
	s_waitcnt lgkmcnt(4)
	v_mfma_f32_16x16x32_bf16 v[108:111], v[196:199], v[84:87], v[92:95]
	s_waitcnt lgkmcnt(3)
	v_mfma_f32_16x16x32_bf16 v[92:95], v[200:203], v[88:91], 0
	s_waitcnt lgkmcnt(2)
	v_mfma_f32_16x16x32_bf16 v[104:107], v[204:207], v[84:87], v[92:95]
	s_waitcnt lgkmcnt(1)
	v_mfma_f32_16x16x32_bf16 v[92:95], v[208:211], v[88:91], 0
	s_waitcnt lgkmcnt(0)
	v_mfma_f32_16x16x32_bf16 v[100:103], v[220:223], v[84:87], v[92:95]
	s_ashr_i32 s43, s42, 31
	s_lshl_b64 s[0:1], s[42:43], 2
	s_nop 3
	v_mad_u32_u24 v92, v177, s8, 0
	s_mov_b32 s46, 0x13800
	s_add_u32 s44, s16, s0
	v_add3_u32 v92, v92, v179, s46
	s_addc_u32 s45, s17, s1
	ds_read_b128 v[96:99], v92
	ds_read_b128 v[92:95], v92 offset:64
	global_load_dword v180, v3, s[44:45]
	v_lshlrev_b32_e32 v178, 3, v1
	v_add_u32_e32 v190, s3, v178
	v_add_u32_e32 v168, s21, v190
	v_sub_u32_e32 v169, v181, v168
	v_add_u32_e32 v182, 0x80, v169
	v_add_u32_e32 v169, 0x7f, v169
	v_cmp_gt_u32_e32 vcc, s33, v168
	v_cmp_gt_u32_e64 s[0:1], s34, v182
	v_cmp_gt_u32_e64 s[40:41], s34, v169
	s_and_b64 s[0:1], vcc, s[0:1]
	s_and_b64 s[40:41], vcc, s[40:41]
	v_cndmask_b32_e64 v184, v231, v184, s[0:1]
	v_cndmask_b32_e64 v182, v231, v192, s[40:41]
	v_max_f32_e32 v169, v182, v182
	v_max_f32_e32 v183, v184, v184
	v_max_f32_e32 v169, v183, v169
	v_or_b32_e32 v183, 2, v168
	v_sub_u32_e32 v183, v181, v183
	v_add_u32_e32 v188, 0x80, v183
	v_add_u32_e32 v183, 0x7f, v183
	v_cmp_gt_u32_e64 s[0:1], s34, v188
	v_cmp_gt_u32_e64 s[40:41], s34, v183
	s_and_b64 s[0:1], vcc, s[0:1]
	s_and_b64 s[40:41], vcc, s[40:41]
	v_cndmask_b32_e64 v188, v231, v185, s[0:1]
	v_cndmask_b32_e64 v185, v231, v193, s[40:41]
	v_max_f32_e32 v183, v185, v185
	v_max_f32_e32 v189, v188, v188
	v_max_f32_e32 v183, v189, v183
	s_waitcnt lgkmcnt(1)
	v_mfma_f32_16x16x32_bf16 v[88:91], v[96:99], v[88:91], 0
	s_waitcnt vmcnt(0)
	v_max3_f32 v169, v180, v169, v183
	v_or_b32_e32 v183, 4, v168
	v_sub_u32_e32 v183, v181, v183
	v_add_u32_e32 v189, 0x80, v183
	v_add_u32_e32 v183, 0x7f, v183
	v_cmp_gt_u32_e64 s[0:1], s34, v189
	v_cmp_gt_u32_e64 s[40:41], s34, v183
	s_and_b64 s[0:1], vcc, s[0:1]
	s_and_b64 s[40:41], vcc, s[40:41]
	v_cndmask_b32_e64 v186, v231, v186, s[0:1]
	v_cndmask_b32_e64 v183, v231, v194, s[40:41]
	v_or_b32_e32 v168, 6, v168
	v_max_f32_e32 v189, v183, v183
	v_max_f32_e32 v191, v186, v186
	v_sub_u32_e32 v168, v181, v168
	v_max_f32_e32 v191, v191, v189
	v_add_u32_e32 v189, 0x80, v168
	v_add_u32_e32 v168, 0x7f, v168
	v_cmp_gt_u32_e64 s[0:1], s34, v189
	v_cmp_gt_u32_e64 s[40:41], s34, v168
	s_and_b64 s[0:1], vcc, s[0:1]
	s_and_b64 vcc, vcc, s[40:41]
	v_cndmask_b32_e64 v189, v231, v187, s[0:1]
	v_cndmask_b32_e32 v187, v231, v195, vcc
	v_max_f32_e32 v168, v187, v187
	v_max_f32_e32 v192, v189, v189
	v_max_f32_e32 v168, v192, v168
	v_max3_f32 v193, v169, v191, v168
	v_add_u32_e32 v168, s22, v190
	v_sub_u32_e32 v169, v181, v168
	v_add_u32_e32 v191, 0x80, v169
	v_add_u32_e32 v169, 0x7f, v169
	v_cmp_gt_u32_e32 vcc, s33, v168
	v_cmp_gt_u32_e64 s[0:1], s34, v191
	v_cmp_gt_u32_e64 s[40:41], s34, v169
	s_and_b64 s[0:1], vcc, s[0:1]
	s_and_b64 s[40:41], vcc, s[40:41]
	v_cndmask_b32_e64 v191, v231, v160, s[0:1]
	v_cndmask_b32_e64 v160, v231, v156, s[40:41]
	v_max_f32_e32 v156, v160, v160
	v_max_f32_e32 v169, v191, v191
	v_max_f32_e32 v156, v169, v156
	v_or_b32_e32 v169, 2, v168
	v_sub_u32_e32 v169, v181, v169
	v_add_u32_e32 v192, 0x80, v169
	v_cmp_gt_u32_e64 s[0:1], s34, v192
	v_add_u32_e32 v169, 0x7f, v169
	s_and_b64 s[40:41], vcc, s[0:1]
	v_cmp_gt_u32_e64 s[0:1], s34, v169
	s_and_b64 s[0:1], vcc, s[0:1]
	v_cndmask_b32_e64 v161, v231, v161, s[40:41]
	v_cndmask_b32_e64 v192, v231, v157, s[0:1]
	v_max_f32_e32 v157, v192, v192
	v_max_f32_e32 v169, v161, v161
	v_max_f32_e32 v157, v169, v157
	v_max3_f32 v156, v193, v156, v157
	v_or_b32_e32 v157, 4, v168
	v_sub_u32_e32 v157, v181, v157
	v_add_u32_e32 v169, 0x80, v157
	v_add_u32_e32 v157, 0x7f, v157
	v_cmp_gt_u32_e64 s[0:1], s34, v169
	v_cmp_gt_u32_e64 s[40:41], s34, v157
	s_and_b64 s[0:1], vcc, s[0:1]
	s_and_b64 s[40:41], vcc, s[40:41]
	v_cndmask_b32_e64 v162, v231, v162, s[0:1]
	v_cndmask_b32_e64 v158, v231, v158, s[40:41]
	v_or_b32_e32 v168, 6, v168
	v_max_f32_e32 v157, v158, v158
	v_max_f32_e32 v169, v162, v162
	v_sub_u32_e32 v168, v181, v168
	v_max_f32_e32 v157, v169, v157
	v_add_u32_e32 v169, 0x80, v168
	v_add_u32_e32 v168, 0x7f, v168
	v_cmp_gt_u32_e64 s[0:1], s34, v169
	v_cmp_gt_u32_e64 s[40:41], s34, v168
	s_and_b64 s[0:1], vcc, s[0:1]
	s_and_b64 vcc, vcc, s[40:41]
	v_cndmask_b32_e64 v163, v231, v163, s[0:1]
	v_cndmask_b32_e32 v159, v231, v159, vcc
	v_max_f32_e32 v168, v159, v159
	v_max_f32_e32 v169, v163, v163
	v_max_f32_e32 v168, v169, v168
	v_max3_f32 v156, v156, v157, v168
	v_add_u32_e32 v157, s23, v190
	v_sub_u32_e32 v168, v181, v157
	v_add_u32_e32 v169, 0x80, v168
	v_add_u32_e32 v168, 0x7f, v168
	v_cmp_gt_u32_e32 vcc, s33, v157
	v_cmp_gt_u32_e64 s[0:1], s34, v169
	v_cmp_gt_u32_e64 s[40:41], s34, v168
	s_and_b64 s[0:1], vcc, s[0:1]
	s_and_b64 s[40:41], vcc, s[40:41]
	v_cndmask_b32_e64 v152, v231, v152, s[0:1]
	v_cndmask_b32_e64 v148, v231, v148, s[40:41]
	v_max_f32_e32 v168, v148, v148
	v_max_f32_e32 v169, v152, v152
	v_max_f32_e32 v168, v169, v168
	v_or_b32_e32 v169, 2, v157
	v_sub_u32_e32 v169, v181, v169
	v_add_u32_e32 v193, 0x80, v169
	v_add_u32_e32 v169, 0x7f, v169
	v_cmp_gt_u32_e64 s[0:1], s34, v193
	v_cmp_gt_u32_e64 s[40:41], s34, v169
	s_and_b64 s[0:1], vcc, s[0:1]
	s_and_b64 s[40:41], vcc, s[40:41]
	v_cndmask_b32_e64 v153, v231, v153, s[0:1]
	v_cndmask_b32_e64 v149, v231, v149, s[40:41]
	v_max_f32_e32 v169, v149, v149
	v_max_f32_e32 v193, v153, v153
	v_max_f32_e32 v169, v193, v169
	v_max3_f32 v156, v156, v168, v169
	v_or_b32_e32 v168, 4, v157
	v_sub_u32_e32 v168, v181, v168
	v_add_u32_e32 v169, 0x80, v168
	v_add_u32_e32 v168, 0x7f, v168
	v_cmp_gt_u32_e64 s[0:1], s34, v169
	v_cmp_gt_u32_e64 s[40:41], s34, v168
	s_and_b64 s[0:1], vcc, s[0:1]
	s_and_b64 s[40:41], vcc, s[40:41]
	v_cndmask_b32_e64 v154, v231, v154, s[0:1]
	v_cndmask_b32_e64 v150, v231, v150, s[40:41]
	v_or_b32_e32 v157, 6, v157
	v_max_f32_e32 v168, v150, v150
	v_max_f32_e32 v169, v154, v154
	v_sub_u32_e32 v157, v181, v157
	v_max_f32_e32 v168, v169, v168
	v_add_u32_e32 v169, 0x80, v157
	v_add_u32_e32 v157, 0x7f, v157
	v_cmp_gt_u32_e64 s[0:1], s34, v169
	v_cmp_gt_u32_e64 s[40:41], s34, v157
	s_and_b64 s[0:1], vcc, s[0:1]
	s_and_b64 vcc, vcc, s[40:41]
	v_cndmask_b32_e64 v155, v231, v155, s[0:1]
	v_cndmask_b32_e32 v151, v231, v151, vcc
	v_max_f32_e32 v157, v151, v151
	v_max_f32_e32 v169, v155, v155
	v_max_f32_e32 v157, v169, v157
	v_max3_f32 v156, v156, v168, v157
	v_add_u32_e32 v157, s26, v190
	v_sub_u32_e32 v168, v181, v157
	v_add_u32_e32 v169, 0x80, v168
	v_add_u32_e32 v168, 0x7f, v168
	v_cmp_gt_u32_e32 vcc, s33, v157
	v_cmp_gt_u32_e64 s[0:1], s34, v169
	v_cmp_gt_u32_e64 s[40:41], s34, v168
	s_and_b64 s[0:1], vcc, s[0:1]
	s_and_b64 s[40:41], vcc, s[40:41]
	v_cndmask_b32_e64 v144, v231, v144, s[0:1]
	v_cndmask_b32_e64 v140, v231, v140, s[40:41]
	v_max_f32_e32 v168, v140, v140
	v_max_f32_e32 v169, v144, v144
	v_max_f32_e32 v168, v169, v168
	v_or_b32_e32 v169, 2, v157
	v_sub_u32_e32 v169, v181, v169
	v_add_u32_e32 v193, 0x80, v169
	v_add_u32_e32 v169, 0x7f, v169
	v_cmp_gt_u32_e64 s[0:1], s34, v193
	v_cmp_gt_u32_e64 s[40:41], s34, v169
	s_and_b64 s[0:1], vcc, s[0:1]
	s_and_b64 s[40:41], vcc, s[40:41]
	v_cndmask_b32_e64 v145, v231, v145, s[0:1]
	v_cndmask_b32_e64 v141, v231, v141, s[40:41]
	v_max_f32_e32 v169, v141, v141
	v_max_f32_e32 v193, v145, v145
	v_max_f32_e32 v169, v193, v169
	v_max3_f32 v156, v156, v168, v169
	v_or_b32_e32 v168, 4, v157
	v_sub_u32_e32 v168, v181, v168
	v_add_u32_e32 v169, 0x80, v168
	v_add_u32_e32 v168, 0x7f, v168
	v_cmp_gt_u32_e64 s[0:1], s34, v169
	v_cmp_gt_u32_e64 s[40:41], s34, v168
	s_and_b64 s[0:1], vcc, s[0:1]
	s_and_b64 s[40:41], vcc, s[40:41]
	v_cndmask_b32_e64 v146, v231, v146, s[0:1]
	v_cndmask_b32_e64 v142, v231, v142, s[40:41]
	v_or_b32_e32 v157, 6, v157
	v_max_f32_e32 v168, v142, v142
	v_max_f32_e32 v169, v146, v146
	v_sub_u32_e32 v157, v181, v157
	v_max_f32_e32 v168, v169, v168
	v_add_u32_e32 v169, 0x80, v157
	v_add_u32_e32 v157, 0x7f, v157
	v_cmp_gt_u32_e64 s[0:1], s34, v169
	v_cmp_gt_u32_e64 s[40:41], s34, v157
	s_and_b64 s[0:1], vcc, s[0:1]
	s_and_b64 vcc, vcc, s[40:41]
	v_cndmask_b32_e64 v147, v231, v147, s[0:1]
	v_cndmask_b32_e32 v143, v231, v143, vcc
	v_max_f32_e32 v157, v143, v143
	v_max_f32_e32 v169, v147, v147
	v_max_f32_e32 v157, v169, v157
	v_max3_f32 v156, v156, v168, v157
	v_add_u32_e32 v157, s27, v190
	v_sub_u32_e32 v168, v181, v157
	v_add_u32_e32 v169, 0x80, v168
	v_add_u32_e32 v168, 0x7f, v168
	v_cmp_gt_u32_e32 vcc, s33, v157
	v_cmp_gt_u32_e64 s[0:1], s34, v169
	v_cmp_gt_u32_e64 s[40:41], s34, v168
	s_and_b64 s[0:1], vcc, s[0:1]
	s_and_b64 s[40:41], vcc, s[40:41]
	v_cndmask_b32_e64 v136, v231, v136, s[0:1]
	v_cndmask_b32_e64 v132, v231, v132, s[40:41]
	v_max_f32_e32 v168, v132, v132
	v_max_f32_e32 v169, v136, v136
	v_max_f32_e32 v168, v169, v168
	v_or_b32_e32 v169, 2, v157
	v_sub_u32_e32 v169, v181, v169
	v_add_u32_e32 v193, 0x80, v169
	v_add_u32_e32 v169, 0x7f, v169
	v_cmp_gt_u32_e64 s[0:1], s34, v193
	v_cmp_gt_u32_e64 s[40:41], s34, v169
	s_and_b64 s[0:1], vcc, s[0:1]
	s_and_b64 s[40:41], vcc, s[40:41]
	v_cndmask_b32_e64 v137, v231, v137, s[0:1]
	v_cndmask_b32_e64 v133, v231, v133, s[40:41]
	v_max_f32_e32 v169, v133, v133
	v_max_f32_e32 v193, v137, v137
	v_max_f32_e32 v169, v193, v169
	v_max3_f32 v156, v156, v168, v169
	v_or_b32_e32 v168, 4, v157
	v_sub_u32_e32 v168, v181, v168
	v_add_u32_e32 v169, 0x80, v168
	v_add_u32_e32 v168, 0x7f, v168
	v_cmp_gt_u32_e64 s[0:1], s34, v169
	v_cmp_gt_u32_e64 s[40:41], s34, v168
	s_and_b64 s[0:1], vcc, s[0:1]
	s_and_b64 s[40:41], vcc, s[40:41]
	v_cndmask_b32_e64 v138, v231, v138, s[0:1]
	v_cndmask_b32_e64 v134, v231, v134, s[40:41]
	v_or_b32_e32 v157, 6, v157
	v_max_f32_e32 v168, v134, v134
	v_max_f32_e32 v169, v138, v138
	v_sub_u32_e32 v157, v181, v157
	v_max_f32_e32 v168, v169, v168
	v_add_u32_e32 v169, 0x80, v157
	v_add_u32_e32 v157, 0x7f, v157
	v_cmp_gt_u32_e64 s[0:1], s34, v169
	v_cmp_gt_u32_e64 s[40:41], s34, v157
	s_and_b64 s[0:1], vcc, s[0:1]
	s_and_b64 vcc, vcc, s[40:41]
	v_cndmask_b32_e64 v139, v231, v139, s[0:1]
	v_cndmask_b32_e32 v193, v231, v135, vcc
	v_max_f32_e32 v135, v193, v193
	v_max_f32_e32 v157, v139, v139
	v_max_f32_e32 v135, v157, v135
	v_add_u32_e32 v157, s30, v190
	v_max3_f32 v156, v156, v168, v135
	v_sub_u32_e32 v135, v181, v157
	v_add_u32_e32 v168, 0x80, v135
	v_add_u32_e32 v135, 0x7f, v135
	v_cmp_gt_u32_e32 vcc, s33, v157
	v_cmp_gt_u32_e64 s[0:1], s34, v168
	v_cmp_gt_u32_e64 s[40:41], s34, v135
	s_and_b64 s[0:1], vcc, s[0:1]
	s_and_b64 s[40:41], vcc, s[40:41]
	v_cndmask_b32_e64 v128, v231, v128, s[0:1]
	v_cndmask_b32_e64 v124, v231, v124, s[40:41]
	v_max_f32_e32 v135, v124, v124
	v_max_f32_e32 v168, v128, v128
	v_max_f32_e32 v168, v168, v135
	v_or_b32_e32 v135, 2, v157
	v_sub_u32_e32 v135, v181, v135
	v_add_u32_e32 v169, 0x80, v135
	v_add_u32_e32 v135, 0x7f, v135
	v_cmp_gt_u32_e64 s[0:1], s34, v169
	v_cmp_gt_u32_e64 s[40:41], s34, v135
	s_and_b64 s[0:1], vcc, s[0:1]
	s_and_b64 s[40:41], vcc, s[40:41]
	v_cndmask_b32_e64 v129, v231, v129, s[0:1]
	v_cndmask_b32_e64 v135, v231, v125, s[40:41]
	v_max_f32_e32 v125, v135, v135
	v_max_f32_e32 v169, v129, v129
	v_max_f32_e32 v125, v169, v125
	v_max3_f32 v125, v156, v168, v125
	v_or_b32_e32 v156, 4, v157
	v_sub_u32_e32 v156, v181, v156
	v_add_u32_e32 v168, 0x80, v156
	v_add_u32_e32 v156, 0x7f, v156
	v_cmp_gt_u32_e64 s[0:1], s34, v168
	v_cmp_gt_u32_e64 s[40:41], s34, v156
	s_and_b64 s[0:1], vcc, s[0:1]
	s_and_b64 s[40:41], vcc, s[40:41]
	v_cndmask_b32_e64 v130, v231, v130, s[0:1]
	v_cndmask_b32_e64 v126, v231, v126, s[40:41]
	v_or_b32_e32 v157, 6, v157
	v_max_f32_e32 v156, v126, v126
	v_max_f32_e32 v168, v130, v130
	v_sub_u32_e32 v157, v181, v157
	v_max_f32_e32 v156, v168, v156
	v_add_u32_e32 v168, 0x80, v157
	v_add_u32_e32 v157, 0x7f, v157
	v_cmp_gt_u32_e64 s[0:1], s34, v168
	v_cmp_gt_u32_e64 s[40:41], s34, v157
	s_and_b64 s[0:1], vcc, s[0:1]
	s_and_b64 vcc, vcc, s[40:41]
	v_cndmask_b32_e64 v194, v231, v131, s[0:1]
	v_cndmask_b32_e32 v195, v231, v127, vcc
	v_max_f32_e32 v127, v195, v195
	v_max_f32_e32 v131, v194, v194
	v_max_f32_e32 v127, v131, v127
	v_max3_f32 v131, v125, v156, v127
	v_add_u32_e32 v156, s31, v190
	v_sub_u32_e32 v125, v181, v156
	v_add_u32_e32 v127, 0x80, v125
	v_add_u32_e32 v125, 0x7f, v125
	v_cmp_gt_u32_e32 vcc, s33, v156
	v_cmp_gt_u32_e64 s[0:1], s34, v127
	v_cmp_gt_u32_e64 s[40:41], s34, v125
	s_and_b64 s[0:1], vcc, s[0:1]
	s_and_b64 s[40:41], vcc, s[40:41]
	v_cndmask_b32_e64 v125, v231, v120, s[0:1]
	v_cndmask_b32_e64 v116, v231, v116, s[40:41]
	v_max_f32_e32 v120, v116, v116
	v_max_f32_e32 v127, v125, v125
	v_max_f32_e32 v120, v127, v120
	v_or_b32_e32 v127, 2, v156
	v_sub_u32_e32 v127, v181, v127
	v_add_u32_e32 v157, 0x80, v127
	v_add_u32_e32 v127, 0x7f, v127
	v_cmp_gt_u32_e64 s[0:1], s34, v157
	v_cmp_gt_u32_e64 s[40:41], s34, v127
	s_and_b64 s[0:1], vcc, s[0:1]
	s_and_b64 s[40:41], vcc, s[40:41]
	v_cndmask_b32_e64 v121, v231, v121, s[0:1]
	v_cndmask_b32_e64 v127, v231, v117, s[40:41]
	v_max_f32_e32 v117, v127, v127
	v_max_f32_e32 v157, v121, v121
	v_max_f32_e32 v117, v157, v117
	v_max3_f32 v117, v131, v120, v117
	v_or_b32_e32 v120, 4, v156
	v_sub_u32_e32 v120, v181, v120
	v_add_u32_e32 v131, 0x80, v120
	v_add_u32_e32 v120, 0x7f, v120
	v_cmp_gt_u32_e64 s[0:1], s34, v131
	v_cmp_gt_u32_e64 s[40:41], s34, v120
	s_and_b64 s[0:1], vcc, s[0:1]
	s_and_b64 s[40:41], vcc, s[40:41]
	v_cndmask_b32_e64 v122, v231, v122, s[0:1]
	v_cndmask_b32_e64 v131, v231, v118, s[40:41]
	v_max_f32_e32 v118, v131, v131
	v_max_f32_e32 v120, v122, v122
	v_max_f32_e32 v118, v120, v118
	v_or_b32_e32 v120, 6, v156
	v_sub_u32_e32 v120, v181, v120
	v_add_u32_e32 v156, 0x80, v120
	v_add_u32_e32 v120, 0x7f, v120
	v_cmp_gt_u32_e64 s[0:1], s34, v156
	v_cmp_gt_u32_e64 s[40:41], s34, v120
	s_and_b64 s[0:1], vcc, s[0:1]
	s_and_b64 vcc, vcc, s[40:41]
	v_cndmask_b32_e64 v199, v231, v123, s[0:1]
	v_cndmask_b32_e32 v200, v231, v119, vcc
	v_max_f32_e32 v119, v200, v200
	v_max_f32_e32 v120, v199, v199
	v_max_f32_e32 v119, v120, v119
	v_add_u32_e32 v123, s76, v190
	v_max3_f32 v120, v117, v118, v119
	v_sub_u32_e32 v117, v181, v123
	v_add_u32_e32 v118, 0x80, v117
	v_add_u32_e32 v117, 0x7f, v117
	v_cmp_gt_u32_e32 vcc, s33, v123
	v_cmp_gt_u32_e64 s[0:1], s34, v118
	v_cmp_gt_u32_e64 s[40:41], s34, v117
	s_and_b64 s[0:1], vcc, s[0:1]
	s_and_b64 s[40:41], vcc, s[40:41]
	v_cndmask_b32_e64 v117, v231, v112, s[0:1]
	v_cndmask_b32_e64 v118, v231, v108, s[40:41]
	v_max_f32_e32 v108, v118, v118
	v_max_f32_e32 v112, v117, v117
	v_max_f32_e32 v108, v112, v108
	v_or_b32_e32 v112, 2, v123
	v_sub_u32_e32 v112, v181, v112
	v_add_u32_e32 v119, 0x80, v112
	v_add_u32_e32 v112, 0x7f, v112
	v_cmp_gt_u32_e64 s[0:1], s34, v119
	v_cmp_gt_u32_e64 s[40:41], s34, v112
	s_and_b64 s[0:1], vcc, s[0:1]
	s_and_b64 s[40:41], vcc, s[40:41]
	v_cndmask_b32_e64 v119, v231, v113, s[0:1]
	v_cndmask_b32_e64 v196, v231, v109, s[40:41]
	v_max_f32_e32 v109, v196, v196
	v_max_f32_e32 v112, v119, v119
	v_max_f32_e32 v109, v112, v109
	v_max3_f32 v108, v120, v108, v109
	v_or_b32_e32 v109, 4, v123
	v_sub_u32_e32 v109, v181, v109
	v_add_u32_e32 v112, 0x80, v109
	v_add_u32_e32 v109, 0x7f, v109
	v_cmp_gt_u32_e64 s[0:1], s34, v112
	v_cmp_gt_u32_e64 s[40:41], s34, v109
	s_and_b64 s[0:1], vcc, s[0:1]
	s_and_b64 s[40:41], vcc, s[40:41]
	v_cndmask_b32_e64 v197, v231, v114, s[0:1]
	v_cndmask_b32_e64 v198, v231, v110, s[40:41]
	v_max_f32_e32 v109, v198, v198
	v_max_f32_e32 v110, v197, v197
	v_max_f32_e32 v109, v110, v109
	v_or_b32_e32 v110, 6, v123
	v_sub_u32_e32 v110, v181, v110
	v_add_u32_e32 v112, 0x80, v110
	v_add_u32_e32 v110, 0x7f, v110
	v_cmp_gt_u32_e64 s[0:1], s34, v112
	v_cmp_gt_u32_e64 s[40:41], s34, v110
	s_and_b64 s[0:1], vcc, s[0:1]
	s_and_b64 vcc, vcc, s[40:41]
	v_cndmask_b32_e64 v205, v231, v115, s[0:1]
	v_cndmask_b32_e32 v206, v231, v111, vcc
	v_max_f32_e32 v110, v206, v206
	v_max_f32_e32 v111, v205, v205
	v_max_f32_e32 v110, v111, v110
	v_max3_f32 v108, v108, v109, v110
	v_add_u32_e32 v109, s77, v190
	v_sub_u32_e32 v110, v181, v109
	v_add_u32_e32 v111, 0x80, v110
	v_add_u32_e32 v110, 0x7f, v110
	v_cmp_gt_u32_e32 vcc, s33, v109
	v_cmp_gt_u32_e64 s[0:1], s34, v111
	v_cmp_gt_u32_e64 s[40:41], s34, v110
	s_and_b64 s[0:1], vcc, s[0:1]
	s_and_b64 s[40:41], vcc, s[40:41]
	v_cndmask_b32_e64 v123, v231, v104, s[0:1]
	v_cndmask_b32_e64 v190, v231, v100, s[40:41]
	v_max_f32_e32 v100, v190, v190
	v_max_f32_e32 v104, v123, v123
	v_max_f32_e32 v100, v104, v100
	v_or_b32_e32 v104, 2, v109
	v_sub_u32_e32 v104, v181, v104
	v_add_u32_e32 v110, 0x80, v104
	v_add_u32_e32 v104, 0x7f, v104
	v_cmp_gt_u32_e64 s[0:1], s34, v110
	v_cmp_gt_u32_e64 s[40:41], s34, v104
	s_and_b64 s[0:1], vcc, s[0:1]
	s_and_b64 s[40:41], vcc, s[40:41]
	v_cndmask_b32_e64 v201, v231, v105, s[0:1]
	v_cndmask_b32_e64 v202, v231, v101, s[40:41]
	v_max_f32_e32 v101, v202, v202
	v_max_f32_e32 v104, v201, v201
	v_max_f32_e32 v101, v104, v101
	v_max3_f32 v100, v108, v100, v101
	v_or_b32_e32 v101, 4, v109
	v_sub_u32_e32 v101, v181, v101
	v_add_u32_e32 v104, 0x80, v101
	v_add_u32_e32 v101, 0x7f, v101
	v_cmp_gt_u32_e64 s[0:1], s34, v104
	v_cmp_gt_u32_e64 s[40:41], s34, v101
	s_and_b64 s[0:1], vcc, s[0:1]
	s_and_b64 s[40:41], vcc, s[40:41]
	v_cndmask_b32_e64 v203, v231, v106, s[0:1]
	v_cndmask_b32_e64 v204, v231, v102, s[40:41]
	v_max_f32_e32 v101, v204, v204
	v_max_f32_e32 v102, v203, v203
	v_max_f32_e32 v101, v102, v101
	v_or_b32_e32 v102, 6, v109
	v_sub_u32_e32 v102, v181, v102
	v_add_u32_e32 v104, 0x80, v102
	v_add_u32_e32 v102, 0x7f, v102
	v_cmp_gt_u32_e64 s[0:1], s34, v104
	v_cmp_gt_u32_e64 s[40:41], s34, v102
	s_and_b64 s[0:1], vcc, s[0:1]
	s_and_b64 vcc, vcc, s[40:41]
	v_cndmask_b32_e64 v181, v231, v107, s[0:1]
	v_cndmask_b32_e32 v207, v231, v103, vcc
	s_waitcnt lgkmcnt(0)
	v_mfma_f32_16x16x32_bf16 v[88:91], v[92:95], v[84:87], v[88:91]
	v_max_f32_e32 v102, v207, v207
	v_max_f32_e32 v103, v181, v181
	v_and_b32_e32 v86, 64, v217
	v_max_f32_e32 v102, v103, v102
	v_xor_b32_e32 v85, 16, v217
	v_add_u32_e32 v86, 64, v86
	v_max3_f32 v100, v100, v101, v102
	v_cmp_lt_i32_e32 vcc, v85, v86
	v_max3_f32 v84, v100, v88, v89
	v_max3_f32 v84, v84, v90, v91
	v_cndmask_b32_e32 v85, v217, v85, vcc
	v_lshlrev_b32_e32 v157, 2, v85
	ds_bpermute_b32 v85, v157, v84
	v_mov_b32_e32 v93, v3
	s_waitcnt lgkmcnt(0)
	v_max_f32_e32 v85, v85, v85
	v_max_f32_e32 v84, v84, v85
	v_xor_b32_e32 v85, 32, v217
	v_cmp_lt_i32_e32 vcc, v85, v86
	s_nop 1
	v_cndmask_b32_e32 v85, v217, v85, vcc
	v_lshlrev_b32_e32 v156, 2, v85
	ds_bpermute_b32 v85, v156, v84
	s_waitcnt lgkmcnt(0)
	v_max_f32_e32 v85, v85, v85
	v_max_f32_e32 v120, v84, v85
	v_sub_f32_e32 v84, v184, v120
	v_mul_f32_e32 v84, 0x3fb8aa3b, v84
	v_exp_f32_e32 v100, v84
	v_sub_f32_e32 v84, v182, v120
	v_mul_f32_e32 v84, 0x3fb8aa3b, v84
	v_exp_f32_e32 v101, v84
	v_sub_f32_e32 v84, v188, v120
	v_mul_f32_e32 v84, 0x3fb8aa3b, v84
	v_exp_f32_e32 v86, v84
	v_sub_f32_e32 v84, v185, v120
	v_mul_f32_e32 v84, 0x3fb8aa3b, v84
	v_exp_f32_e32 v92, v84
	v_add_f32_e32 v87, v100, v101
	v_sub_f32_e32 v88, v88, v120
	v_mul_f32_e32 v88, 0x3fb8aa3b, v88
	v_pk_add_f32 v[84:85], v[86:87], v[92:93]
	v_sub_f32_e32 v89, v89, v120
	v_pk_add_f32 v[94:95], v[84:85], v[84:85] op_sel_hi:[0,1]
	v_sub_f32_e32 v84, v186, v120
	v_mul_f32_e32 v84, 0x3fb8aa3b, v84
	v_exp_f32_e32 v87, v84
	v_sub_f32_e32 v84, v183, v120
	v_mul_f32_e32 v84, 0x3fb8aa3b, v84
	v_exp_f32_e32 v93, v84
	v_sub_f32_e32 v84, v189, v120
	v_mul_f32_e32 v84, 0x3fb8aa3b, v84
	v_exp_f32_e32 v96, v84
	v_sub_f32_e32 v84, v187, v120
	v_mul_f32_e32 v84, 0x3fb8aa3b, v84
	v_exp_f32_e32 v94, v84
	v_add_f32_e32 v97, v87, v93
	v_exp_f32_e32 v88, v88
	v_mul_f32_e32 v89, 0x3fb8aa3b, v89
	v_pk_add_f32 v[84:85], v[96:97], v[94:95]
	v_sub_f32_e32 v90, v90, v120
	v_pk_add_f32 v[98:99], v[84:85], v[84:85] op_sel_hi:[0,1]
	v_cvt_pk_bf16_f32 v85, v86, v92
	v_sub_f32_e32 v92, v191, v120
	v_mul_f32_e32 v92, 0x3fb8aa3b, v92
	v_exp_f32_e32 v104, v92
	v_sub_f32_e32 v92, v160, v120
	v_mul_f32_e32 v92, 0x3fb8aa3b, v92
	v_exp_f32_e32 v105, v92
	v_sub_f32_e32 v92, v161, v120
	v_mul_f32_e32 v92, 0x3fb8aa3b, v92
	v_cvt_pk_bf16_f32 v86, v87, v93
	v_cvt_pk_bf16_f32 v87, v96, v94
	v_exp_f32_e32 v94, v92
	v_sub_f32_e32 v92, v192, v120
	v_mul_f32_e32 v92, 0x3fb8aa3b, v92
	v_exp_f32_e32 v98, v92
	v_add_f32_e32 v95, v104, v105
	v_cvt_pk_bf16_f32 v84, v100, v101
	v_exp_f32_e32 v89, v89
	v_pk_add_f32 v[92:93], v[94:95], v[98:99]
	v_mul_f32_e32 v90, 0x3fb8aa3b, v90
	v_pk_add_f32 v[96:97], v[92:93], v[92:93] op_sel_hi:[0,1]
	v_sub_f32_e32 v92, v162, v120
	v_mul_f32_e32 v92, 0x3fb8aa3b, v92
	v_exp_f32_e32 v95, v92
	v_sub_f32_e32 v92, v158, v120
	v_mul_f32_e32 v92, 0x3fb8aa3b, v92
	v_exp_f32_e32 v99, v92
	v_sub_f32_e32 v92, v163, v120
	v_mul_f32_e32 v92, 0x3fb8aa3b, v92
	v_exp_f32_e32 v100, v92
	v_sub_f32_e32 v92, v159, v120
	v_mul_f32_e32 v92, 0x3fb8aa3b, v92
	v_exp_f32_e32 v96, v92
	v_add_f32_e32 v101, v95, v99
	v_sub_f32_e32 v91, v91, v120
	v_exp_f32_e32 v90, v90
	v_pk_add_f32 v[92:93], v[100:101], v[96:97]
	v_mul_f32_e32 v91, 0x3fb8aa3b, v91
	v_pk_add_f32 v[102:103], v[92:93], v[92:93] op_sel_hi:[0,1]
	v_cvt_pk_bf16_f32 v93, v94, v98
	v_cvt_pk_bf16_f32 v94, v95, v99
	v_cvt_pk_bf16_f32 v95, v100, v96
	v_sub_f32_e32 v96, v152, v120
	v_mul_f32_e32 v96, 0x3fb8aa3b, v96
	v_exp_f32_e32 v108, v96
	v_sub_f32_e32 v96, v148, v120
	v_mul_f32_e32 v96, 0x3fb8aa3b, v96
	v_exp_f32_e32 v109, v96
	v_sub_f32_e32 v96, v153, v120
	v_mul_f32_e32 v96, 0x3fb8aa3b, v96
	v_exp_f32_e32 v98, v96
	v_sub_f32_e32 v96, v149, v120
	v_mul_f32_e32 v96, 0x3fb8aa3b, v96
	v_exp_f32_e32 v102, v96
	v_add_f32_e32 v99, v108, v109
	v_cvt_pk_bf16_f32 v92, v104, v105
	v_exp_f32_e32 v91, v91
	v_pk_add_f32 v[96:97], v[98:99], v[102:103]
	s_nop 0
	v_pk_add_f32 v[100:101], v[96:97], v[96:97] op_sel_hi:[0,1]
	v_sub_f32_e32 v96, v154, v120
	v_mul_f32_e32 v96, 0x3fb8aa3b, v96
	v_exp_f32_e32 v99, v96
	v_sub_f32_e32 v96, v150, v120
	v_mul_f32_e32 v96, 0x3fb8aa3b, v96
	v_exp_f32_e32 v103, v96
	v_sub_f32_e32 v96, v155, v120
	v_mul_f32_e32 v96, 0x3fb8aa3b, v96
	v_exp_f32_e32 v104, v96
	v_sub_f32_e32 v96, v151, v120
	v_mul_f32_e32 v96, 0x3fb8aa3b, v96
	v_exp_f32_e32 v100, v96
	v_add_f32_e32 v105, v99, v103
	v_pk_add_f32 v[96:97], v[104:105], v[100:101]
	s_nop 0
	v_pk_add_f32 v[106:107], v[96:97], v[96:97] op_sel_hi:[0,1]
	v_cvt_pk_bf16_f32 v97, v98, v102
	v_cvt_pk_bf16_f32 v98, v99, v103
	v_cvt_pk_bf16_f32 v99, v104, v100
	v_sub_f32_e32 v100, v144, v120
	v_mul_f32_e32 v100, 0x3fb8aa3b, v100
	v_exp_f32_e32 v112, v100
	v_sub_f32_e32 v100, v140, v120
	v_mul_f32_e32 v100, 0x3fb8aa3b, v100
	v_exp_f32_e32 v113, v100
	v_sub_f32_e32 v100, v145, v120
	v_mul_f32_e32 v100, 0x3fb8aa3b, v100
	v_exp_f32_e32 v102, v100
	v_sub_f32_e32 v100, v141, v120
	v_mul_f32_e32 v100, 0x3fb8aa3b, v100
	v_exp_f32_e32 v106, v100
	v_add_f32_e32 v103, v112, v113
	v_cvt_pk_bf16_f32 v96, v108, v109
	v_pk_add_f32 v[100:101], v[102:103], v[106:107]
	s_nop 0
	v_pk_add_f32 v[104:105], v[100:101], v[100:101] op_sel_hi:[0,1]
	v_sub_f32_e32 v100, v146, v120
	v_mul_f32_e32 v100, 0x3fb8aa3b, v100
	v_exp_f32_e32 v103, v100
	v_sub_f32_e32 v100, v142, v120
	v_mul_f32_e32 v100, 0x3fb8aa3b, v100
	v_exp_f32_e32 v107, v100
	v_sub_f32_e32 v100, v147, v120
	v_mul_f32_e32 v100, 0x3fb8aa3b, v100
	v_exp_f32_e32 v108, v100
	v_sub_f32_e32 v100, v143, v120
	v_mul_f32_e32 v100, 0x3fb8aa3b, v100
	v_exp_f32_e32 v104, v100
	v_add_f32_e32 v109, v103, v107
	v_pk_add_f32 v[100:101], v[108:109], v[104:105]
	s_nop 0
	v_pk_add_f32 v[110:111], v[100:101], v[100:101] op_sel_hi:[0,1]
	v_cvt_pk_bf16_f32 v101, v102, v106
	v_cvt_pk_bf16_f32 v102, v103, v107
	v_cvt_pk_bf16_f32 v103, v108, v104
	v_sub_f32_e32 v104, v136, v120
	v_mul_f32_e32 v104, 0x3fb8aa3b, v104
	v_exp_f32_e32 v136, v104
	v_sub_f32_e32 v104, v132, v120
	v_mul_f32_e32 v104, 0x3fb8aa3b, v104
	v_exp_f32_e32 v132, v104
	v_sub_f32_e32 v104, v137, v120
	v_mul_f32_e32 v104, 0x3fb8aa3b, v104
	v_exp_f32_e32 v106, v104
	v_sub_f32_e32 v104, v133, v120
	v_mul_f32_e32 v104, 0x3fb8aa3b, v104
	v_exp_f32_e32 v110, v104
	v_add_f32_e32 v107, v136, v132
	v_cvt_pk_bf16_f32 v100, v112, v113
	v_pk_add_f32 v[104:105], v[106:107], v[110:111]
	s_nop 0
	v_pk_add_f32 v[108:109], v[104:105], v[104:105] op_sel_hi:[0,1]
	v_sub_f32_e32 v104, v138, v120
	v_mul_f32_e32 v104, 0x3fb8aa3b, v104
	v_exp_f32_e32 v107, v104
	v_sub_f32_e32 v104, v134, v120
	v_mul_f32_e32 v104, 0x3fb8aa3b, v104
	v_exp_f32_e32 v111, v104
	v_sub_f32_e32 v104, v139, v120
	v_mul_f32_e32 v104, 0x3fb8aa3b, v104
	v_exp_f32_e32 v112, v104
	v_sub_f32_e32 v104, v193, v120
	v_mul_f32_e32 v104, 0x3fb8aa3b, v104
	v_exp_f32_e32 v108, v104
	v_add_f32_e32 v113, v107, v111
	v_pk_add_f32 v[104:105], v[112:113], v[108:109]
	s_nop 0
	v_pk_add_f32 v[114:115], v[104:105], v[104:105] op_sel_hi:[0,1]
	v_cvt_pk_bf16_f32 v105, v106, v110
	v_cvt_pk_bf16_f32 v106, v107, v111
	v_cvt_pk_bf16_f32 v107, v112, v108
	v_sub_f32_e32 v108, v128, v120
	v_mul_f32_e32 v108, 0x3fb8aa3b, v108
	v_exp_f32_e32 v134, v108
	v_sub_f32_e32 v108, v124, v120
	v_mul_f32_e32 v108, 0x3fb8aa3b, v108
	v_exp_f32_e32 v124, v108
	v_sub_f32_e32 v108, v129, v120
	v_mul_f32_e32 v108, 0x3fb8aa3b, v108
	v_exp_f32_e32 v110, v108
	v_sub_f32_e32 v108, v135, v120
	v_mul_f32_e32 v108, 0x3fb8aa3b, v108
	v_exp_f32_e32 v114, v108
	v_add_f32_e32 v111, v134, v124
	v_cvt_pk_bf16_f32 v104, v136, v132
	v_pk_add_f32 v[108:109], v[110:111], v[114:115]
	s_nop 0
	v_pk_add_f32 v[112:113], v[108:109], v[108:109] op_sel_hi:[0,1]
	v_sub_f32_e32 v108, v130, v120
	v_mul_f32_e32 v108, 0x3fb8aa3b, v108
	v_exp_f32_e32 v111, v108
	v_sub_f32_e32 v108, v126, v120
	v_mul_f32_e32 v108, 0x3fb8aa3b, v108
	v_exp_f32_e32 v115, v108
	v_sub_f32_e32 v108, v194, v120
	v_mul_f32_e32 v108, 0x3fb8aa3b, v108
	v_exp_f32_e32 v128, v108
	v_sub_f32_e32 v108, v195, v120
	v_mul_f32_e32 v108, 0x3fb8aa3b, v108
	v_exp_f32_e32 v112, v108
	v_add_f32_e32 v129, v111, v115
	v_pk_add_f32 v[108:109], v[128:129], v[112:113]
	s_nop 0
	v_pk_add_f32 v[132:133], v[108:109], v[108:109] op_sel_hi:[0,1]
	v_cvt_pk_bf16_f32 v109, v110, v114
	v_cvt_pk_bf16_f32 v110, v111, v115
	v_cvt_pk_bf16_f32 v111, v128, v112
	v_sub_f32_e32 v112, v125, v120
	v_mul_f32_e32 v112, 0x3fb8aa3b, v112
	v_exp_f32_e32 v130, v112
	v_sub_f32_e32 v112, v116, v120
	v_mul_f32_e32 v112, 0x3fb8aa3b, v112
	v_exp_f32_e32 v116, v112
	v_sub_f32_e32 v112, v121, v120
	v_mul_f32_e32 v112, 0x3fb8aa3b, v112
	v_exp_f32_e32 v114, v112
	v_sub_f32_e32 v112, v127, v120
	v_mul_f32_e32 v112, 0x3fb8aa3b, v112
	v_exp_f32_e32 v132, v112
	v_add_f32_e32 v115, v130, v116
	v_cvt_pk_bf16_f32 v108, v134, v124
	v_pk_add_f32 v[112:113], v[114:115], v[132:133]
	s_nop 0
	v_pk_add_f32 v[124:125], v[112:113], v[112:113] op_sel_hi:[0,1]
	v_sub_f32_e32 v112, v122, v120
	v_mul_f32_e32 v112, 0x3fb8aa3b, v112
	v_exp_f32_e32 v115, v112
	v_sub_f32_e32 v112, v131, v120
	v_mul_f32_e32 v112, 0x3fb8aa3b, v112
	v_exp_f32_e32 v121, v112
	v_sub_f32_e32 v112, v199, v120
	v_mul_f32_e32 v112, 0x3fb8aa3b, v112
	v_exp_f32_e32 v126, v112
	v_sub_f32_e32 v112, v200, v120
	v_mul_f32_e32 v112, 0x3fb8aa3b, v112
	v_exp_f32_e32 v124, v112
	v_add_f32_e32 v127, v115, v121
	v_pk_add_f32 v[112:113], v[126:127], v[124:125]
	s_nop 0
	v_pk_add_f32 v[128:129], v[112:113], v[112:113] op_sel_hi:[0,1]
	v_cvt_pk_bf16_f32 v112, v130, v116
	v_sub_f32_e32 v116, v117, v120
	v_mul_f32_e32 v116, 0x3fb8aa3b, v116
	v_cvt_pk_bf16_f32 v113, v114, v132
	v_cvt_pk_bf16_f32 v114, v115, v121
	v_exp_f32_e32 v121, v116
	v_sub_f32_e32 v116, v118, v120
	v_mul_f32_e32 v116, 0x3fb8aa3b, v116
	v_exp_f32_e32 v118, v116
	v_sub_f32_e32 v116, v119, v120
	v_mul_f32_e32 v116, 0x3fb8aa3b, v116
	v_cvt_pk_bf16_f32 v115, v126, v124
	v_exp_f32_e32 v124, v116
	v_sub_f32_e32 v116, v196, v120
	v_mul_f32_e32 v116, 0x3fb8aa3b, v116
	v_exp_f32_e32 v128, v116
	v_add_f32_e32 v125, v121, v118
	v_pk_add_f32 v[116:117], v[124:125], v[128:129]
	s_nop 0
	v_pk_add_f32 v[126:127], v[116:117], v[116:117] op_sel_hi:[0,1]
	v_sub_f32_e32 v116, v197, v120
	v_mul_f32_e32 v116, 0x3fb8aa3b, v116
	v_exp_f32_e32 v119, v116
	v_sub_f32_e32 v116, v198, v120
	v_mul_f32_e32 v116, 0x3fb8aa3b, v116
	v_exp_f32_e32 v122, v116
	v_sub_f32_e32 v116, v205, v120
	v_mul_f32_e32 v116, 0x3fb8aa3b, v116
	v_exp_f32_e32 v130, v116
	v_sub_f32_e32 v116, v206, v120
	v_mul_f32_e32 v116, 0x3fb8aa3b, v116
	v_exp_f32_e32 v126, v116
	v_add_f32_e32 v131, v119, v122
	v_pk_add_f32 v[116:117], v[130:131], v[126:127]
	s_nop 0
	v_pk_add_f32 v[132:133], v[116:117], v[116:117] op_sel_hi:[0,1]
	v_cvt_pk_bf16_f32 v116, v121, v118
	v_cvt_pk_bf16_f32 v118, v119, v122
	v_sub_f32_e32 v122, v190, v120
	v_mul_f32_e32 v122, 0x3fb8aa3b, v122
	v_cvt_pk_bf16_f32 v119, v130, v126
	v_exp_f32_e32 v130, v122
	v_sub_f32_e32 v122, v201, v120
	v_sub_f32_e32 v121, v123, v120
	v_mul_f32_e32 v122, 0x3fb8aa3b, v122
	v_cvt_pk_bf16_f32 v117, v124, v128
	v_mul_f32_e32 v121, 0x3fb8aa3b, v121
	v_exp_f32_e32 v124, v122
	v_sub_f32_e32 v122, v202, v120
	v_exp_f32_e32 v121, v121
	v_mul_f32_e32 v122, 0x3fb8aa3b, v122
	v_exp_f32_e32 v132, v122
	v_add_f32_e32 v125, v121, v130
	v_pk_add_f32 v[122:123], v[124:125], v[132:133]
	s_nop 0
	v_pk_add_f32 v[126:127], v[122:123], v[122:123] op_sel_hi:[0,1]
	v_sub_f32_e32 v122, v203, v120
	v_mul_f32_e32 v122, 0x3fb8aa3b, v122
	v_exp_f32_e32 v125, v122
	v_sub_f32_e32 v122, v204, v120
	v_mul_f32_e32 v122, 0x3fb8aa3b, v122
	v_exp_f32_e32 v131, v122
	v_sub_f32_e32 v122, v181, v120
	v_mul_f32_e32 v122, 0x3fb8aa3b, v122
	v_exp_f32_e32 v128, v122
	v_sub_f32_e32 v122, v207, v120
	v_mul_f32_e32 v122, 0x3fb8aa3b, v122
	v_exp_f32_e32 v126, v122
	v_add_f32_e32 v129, v125, v131
	v_sub_f32_e32 v120, v180, v120
	v_mul_f32_e32 v120, 0x3fb8aa3b, v120
	v_pk_add_f32 v[122:123], v[128:129], v[126:127]
	v_exp_f32_e32 v120, v120
	v_add_f32_e32 v127, v122, v123
	v_cvt_pk_bf16_f32 v122, v121, v130
	v_add_f32_e32 v121, v88, v127
	v_add_f32_e32 v121, v89, v121
	v_add_f32_e32 v121, v90, v121
	v_add_f32_e32 v121, v91, v121
	v_cvt_pk_bf16_f32 v88, v88, v89
	v_cvt_pk_bf16_f32 v89, v90, v91
	ds_bpermute_b32 v90, v157, v121
	v_cvt_pk_bf16_f32 v123, v124, v132
	v_cvt_pk_bf16_f32 v124, v125, v131
	v_cvt_pk_bf16_f32 v125, v128, v126
	s_waitcnt lgkmcnt(0)
	v_add_f32_e32 v90, v121, v90
	ds_bpermute_b32 v91, v156, v90
	v_readlane_b32 s0, v254, 58
	s_movk_i32 s9, 0x320
	s_waitcnt lgkmcnt(0)
	v_add_f32_e32 v121, v90, v91
	v_mov_b32_e32 v158, s0
	v_mad_u32_u24 v154, v177, s9, v158
	v_add3_u32 v155, v154, v179, s78
	ds_read_b128 v[126:129], v155
	ds_read_b128 v[130:133], v155 offset:12800
	ds_read_b128 v[134:137], v155 offset:25600
	ds_read_b128 v[138:141], v155 offset:38400
	ds_read_b128 v[142:145], v155 offset:64
	ds_read_b128 v[146:149], v155 offset:12864
	ds_read_b128 v[150:153], v155 offset:25664
	ds_read_b128 v[160:163], v155 offset:38464
	ds_read_b128 v[180:183], v155 offset:128
	ds_read_b128 v[184:187], v155 offset:12928
	ds_read_b128 v[188:191], v155 offset:25728
	ds_read_b128 v[192:195], v155 offset:38528
	s_waitcnt lgkmcnt(11)
	v_mfma_f32_16x16x32_bf16 v[126:129], v[126:129], v[84:87], 0
	s_waitcnt lgkmcnt(10)
	v_mfma_f32_16x16x32_bf16 v[130:133], v[130:133], v[84:87], 0
	s_waitcnt lgkmcnt(9)
	v_mfma_f32_16x16x32_bf16 v[134:137], v[134:137], v[84:87], 0
	s_waitcnt lgkmcnt(8)
	v_mfma_f32_16x16x32_bf16 v[84:87], v[138:141], v[84:87], 0
	s_waitcnt lgkmcnt(7)
	v_mfma_f32_16x16x32_bf16 v[126:129], v[142:145], v[92:95], v[126:129]
	s_waitcnt lgkmcnt(6)
	v_mfma_f32_16x16x32_bf16 v[130:133], v[146:149], v[92:95], v[130:133]
	s_waitcnt lgkmcnt(5)
	v_mfma_f32_16x16x32_bf16 v[134:137], v[150:153], v[92:95], v[134:137]
	s_waitcnt lgkmcnt(4)
	v_mfma_f32_16x16x32_bf16 v[84:87], v[160:163], v[92:95], v[84:87]
	s_waitcnt lgkmcnt(3)
	v_mfma_f32_16x16x32_bf16 v[90:93], v[180:183], v[96:99], v[126:129]
	s_waitcnt lgkmcnt(2)
	v_mfma_f32_16x16x32_bf16 v[126:129], v[184:187], v[96:99], v[130:133]
	s_waitcnt lgkmcnt(1)
	v_mfma_f32_16x16x32_bf16 v[130:133], v[188:191], v[96:99], v[134:137]
	s_waitcnt lgkmcnt(0)
	v_mfma_f32_16x16x32_bf16 v[84:87], v[192:195], v[96:99], v[84:87]
	ds_read_b128 v[94:97], v155 offset:12992
	ds_read_b128 v[134:137], v155 offset:13056
	ds_read_b128 v[138:141], v155 offset:38592
	ds_read_b128 v[142:145], v155 offset:38656
	ds_read_b128 v[146:149], v155 offset:256
	ds_read_b128 v[150:153], v155 offset:320
	ds_read_b128 v[160:163], v155 offset:25792
	ds_read_b128 v[180:183], v155 offset:13120
	ds_read_b128 v[184:187], v155 offset:25856
	ds_read_b128 v[188:191], v155 offset:25920
	ds_read_b128 v[192:195], v155 offset:192
	ds_read_b128 v[196:199], v155 offset:38720
	s_waitcnt lgkmcnt(1)
	v_mfma_f32_16x16x32_bf16 v[90:93], v[192:195], v[100:103], v[90:93]
	v_mfma_f32_16x16x32_bf16 v[94:97], v[94:97], v[100:103], v[126:129]
	v_mfma_f32_16x16x32_bf16 v[126:129], v[160:163], v[100:103], v[130:133]
	v_mfma_f32_16x16x32_bf16 v[84:87], v[138:141], v[100:103], v[84:87]
	v_mfma_f32_16x16x32_bf16 v[90:93], v[146:149], v[104:107], v[90:93]
	v_mfma_f32_16x16x32_bf16 v[94:97], v[134:137], v[104:107], v[94:97]
	v_mfma_f32_16x16x32_bf16 v[98:101], v[184:187], v[104:107], v[126:129]
	v_mfma_f32_16x16x32_bf16 v[84:87], v[142:145], v[104:107], v[84:87]
	v_mfma_f32_16x16x32_bf16 v[90:93], v[150:153], v[108:111], v[90:93]
	v_mfma_f32_16x16x32_bf16 v[94:97], v[180:183], v[108:111], v[94:97]
	v_mfma_f32_16x16x32_bf16 v[98:101], v[188:191], v[108:111], v[98:101]
	s_waitcnt lgkmcnt(0)
	v_mfma_f32_16x16x32_bf16 v[84:87], v[196:199], v[108:111], v[84:87]
	ds_read_b128 v[102:105], v155 offset:13184
	ds_read_b128 v[106:109], v155 offset:13248
	ds_read_b128 v[126:129], v155 offset:38784
	ds_read_b128 v[130:133], v155 offset:38848
	ds_read_b128 v[134:137], v155 offset:448
	ds_read_b128 v[138:141], v155 offset:512
	ds_read_b128 v[142:145], v155 offset:25984
	ds_read_b128 v[146:149], v155 offset:13312
	ds_read_b128 v[150:153], v155 offset:26048
	ds_read_b128 v[160:163], v155 offset:26112
	ds_read_b128 v[180:183], v155 offset:384
	ds_read_b128 v[184:187], v155 offset:38912
	s_waitcnt lgkmcnt(1)
	v_mfma_f32_16x16x32_bf16 v[90:93], v[180:183], v[112:115], v[90:93]
	v_mfma_f32_16x16x32_bf16 v[94:97], v[102:105], v[112:115], v[94:97]
	v_mfma_f32_16x16x32_bf16 v[98:101], v[142:145], v[112:115], v[98:101]
	v_mfma_f32_16x16x32_bf16 v[84:87], v[126:129], v[112:115], v[84:87]
	v_mfma_f32_16x16x32_bf16 v[90:93], v[134:137], v[116:119], v[90:93]
	v_mfma_f32_16x16x32_bf16 v[94:97], v[106:109], v[116:119], v[94:97]
	v_mfma_f32_16x16x32_bf16 v[98:101], v[150:153], v[116:119], v[98:101]
	v_mfma_f32_16x16x32_bf16 v[84:87], v[130:133], v[116:119], v[84:87]
	v_mfma_f32_16x16x32_bf16 v[102:105], v[138:141], v[122:125], v[90:93]
	v_mfma_f32_16x16x32_bf16 v[92:95], v[146:149], v[122:125], v[94:97]
	v_mfma_f32_16x16x32_bf16 v[96:99], v[160:163], v[122:125], v[98:101]
	s_waitcnt lgkmcnt(0)
	v_mfma_f32_16x16x32_bf16 v[84:87], v[184:187], v[122:125], v[84:87]
	s_nop 1
	v_add_u32_e32 v100, v154, v178
	v_add_u32_e32 v114, 0x100, v100
	ds_read2st64_b64 v[106:109], v114 offset0:1 offset1:26
	v_mov_b32_e32 v112, v3
	v_mov_b32_e32 v113, v3
	v_mov_b32_e32 v90, v3
	v_mov_b32_e32 v91, v3
	s_waitcnt lgkmcnt(0)
	v_mov_b32_e32 v110, v106
	v_mov_b32_e32 v111, v107
	v_mov_b32_e32 v106, v3
	v_mov_b32_e32 v107, v3
	s_movk_i32 s43, 0xc00
	v_mfma_f32_16x16x32_bf16 v[100:103], v[110:113], v[88:91], v[102:105]
	v_mov_b32_e32 v110, v3
	v_mov_b32_e32 v111, v3
	s_nop 0
	v_mov_b32_e32 v104, v108
	v_mov_b32_e32 v105, v109
	v_mov_b32_e32 v159, v173
	s_nop 0
	v_mfma_f32_16x16x32_bf16 v[92:95], v[104:107], v[88:91], v[92:95]
	ds_read2st64_b64 v[104:107], v114 offset0:51 offset1:76
	s_waitcnt lgkmcnt(0)
	v_mov_b32_e32 v108, v104
	v_mov_b32_e32 v109, v105
	v_mov_b32_e32 v104, v106
	v_mov_b32_e32 v105, v107
	v_mov_b32_e32 v106, v3
	v_mov_b32_e32 v107, v3
	v_mfma_f32_16x16x32_bf16 v[96:99], v[108:111], v[88:91], v[96:99]
	s_nop 0
	v_mfma_f32_16x16x32_bf16 v[84:87], v[104:107], v[88:91], v[84:87]
	v_add_f32_e32 v88, v120, v121
	v_div_scale_f32 v89, s[0:1], v88, v88, 1.0
	v_rcp_f32_e32 v90, v89
	s_nop 0
	v_fma_f32 v91, -v89, v90, 1.0
	v_fmac_f32_e32 v90, v91, v90
	v_div_scale_f32 v91, vcc, 1.0, v88, 1.0
	v_mul_f32_e32 v104, v91, v90
	v_fma_f32 v105, -v89, v104, v91
	v_fmac_f32_e32 v104, v105, v90
	v_fma_f32 v89, -v89, v104, v91
	v_and_b32_e32 v105, 16, v0
	v_lshlrev_b32_e32 v0, 2, v1
	v_div_fmas_f32 v89, v89, v90, v104
	v_and_b32_e32 v106, -8, v0
	v_mov_b64_e32 v[0:1], s[96:97]
	v_div_fixup_f32 v104, v89, v88, 1.0
	v_mad_i64_i32 v[88:89], s[0:1], v176, s43, v[0:1]
	v_lshl_add_u64 v[108:109], s[74:75], 1, v[88:89]
	v_pk_mul_f32 v[90:91], v[102:103], v[104:105] op_sel_hi:[1,0]
	v_pk_mul_f32 v[88:89], v[100:101], v[104:105] op_sel_hi:[1,0]
	v_pk_mul_f32 v[92:93], v[92:93], v[104:105] op_sel_hi:[1,0]
	v_pk_mul_f32 v[94:95], v[94:95], v[104:105] op_sel_hi:[1,0]
	v_cvt_pk_bf16_f32 v88, v88, v89
	v_cvt_pk_bf16_f32 v89, v90, v91
	v_cvt_pk_bf16_f32 v90, v92, v93
	v_lshlrev_b32_e32 v92, 1, v105
	v_mov_b32_e32 v93, v3
	v_ashrrev_i32_e32 v107, 31, v106
	v_cvt_pk_bf16_f32 v91, v94, v95
	v_lshl_add_u64 v[92:93], v[108:109], 0, v[92:93]
	v_permlane16_swap_b32_e32 v88, v90
	v_permlane16_swap_b32_e32 v89, v91
	v_lshl_add_u64 v[92:93], v[106:107], 1, v[92:93]
	global_load_dword v177, v3, s[44:45] offset:4
	global_store_dwordx4 v[92:93], v[88:91], off offset:2048
	v_pk_mul_f32 v[94:95], v[104:105], v[86:87] op_sel_hi:[0,1]
	v_pk_mul_f32 v[86:87], v[104:105], v[84:85] op_sel_hi:[0,1]
	v_pk_mul_f32 v[88:89], v[104:105], v[98:99] op_sel_hi:[0,1]
	v_pk_mul_f32 v[90:91], v[104:105], v[96:97] op_sel_hi:[0,1]
	v_cvt_pk_bf16_f32 v84, v90, v91
	v_cvt_pk_bf16_f32 v85, v88, v89
	v_cvt_pk_bf16_f32 v86, v86, v87
	v_cvt_pk_bf16_f32 v87, v94, v95
	s_nop 0
	v_permlane16_swap_b32_e32 v84, v86
	v_permlane16_swap_b32_e32 v85, v87
	global_store_dwordx4 v[92:93], v[84:87], off offset:2112
	s_nop 0
	v_and_b32_e32 v162, 15, v159
	v_or_b32_e32 v178, s4, v162
	v_add_u32_e32 v84, s82, v178
	v_or_b32_e32 v85, s5, v162
	v_cndmask_b32_e64 v160, v84, v85, s[38:39]
	v_lshlrev_b32_e32 v84, 1, v159
	v_and_or_b32 v84, v84, 30, s21
	v_mul_lo_u32 v84, v84, s8
	v_and_b32_e32 v176, -16, v159
	v_add3_u32 v163, 0, v84, v176
	ds_read_b128 v[84:87], v163
	ds_read_b128 v[88:91], v163 offset:64
	ds_read_b128 v[92:95], v163 offset:208
	ds_read_b128 v[96:99], v163 offset:272
	ds_read_b128 v[100:103], v163 offset:6656
	ds_read_b128 v[104:107], v163 offset:6720
	ds_read_b128 v[108:111], v163 offset:6864
	ds_read_b128 v[112:115], v163 offset:6928
	ds_read_b128 v[116:119], v163 offset:13312
	ds_read_b128 v[120:123], v163 offset:13376
	ds_read_b128 v[124:127], v163 offset:13520
	ds_read_b128 v[128:131], v163 offset:13584
	v_ashrrev_i32_e32 v161, 4, v159
	s_waitcnt lgkmcnt(11)
	v_mfma_f32_16x16x32_bf16 v[84:87], v[84:87], v[80:83], 0
	s_waitcnt lgkmcnt(10)
	v_mfma_f32_16x16x32_bf16 v[188:191], v[88:91], v[76:79], v[84:87]
	s_waitcnt lgkmcnt(9)
	v_mfma_f32_16x16x32_bf16 v[84:87], v[92:95], v[80:83], 0
	s_waitcnt lgkmcnt(8)
	v_mfma_f32_16x16x32_bf16 v[192:195], v[96:99], v[76:79], v[84:87]
	s_waitcnt lgkmcnt(7)
	v_mfma_f32_16x16x32_bf16 v[84:87], v[100:103], v[80:83], 0
	s_waitcnt lgkmcnt(6)
	v_mfma_f32_16x16x32_bf16 v[152:155], v[104:107], v[76:79], v[84:87]
	s_waitcnt lgkmcnt(5)
	v_mfma_f32_16x16x32_bf16 v[84:87], v[108:111], v[80:83], 0
	s_waitcnt lgkmcnt(4)
	v_mfma_f32_16x16x32_bf16 v[148:151], v[112:115], v[76:79], v[84:87]
	s_waitcnt lgkmcnt(3)
	v_mfma_f32_16x16x32_bf16 v[84:87], v[116:119], v[80:83], 0
	s_waitcnt lgkmcnt(2)
	v_mfma_f32_16x16x32_bf16 v[144:147], v[120:123], v[76:79], v[84:87]
	s_waitcnt lgkmcnt(1)
	v_mfma_f32_16x16x32_bf16 v[84:87], v[124:127], v[80:83], 0
	s_waitcnt lgkmcnt(0)
	v_mfma_f32_16x16x32_bf16 v[140:143], v[128:131], v[76:79], v[84:87]
	s_nop 5
	ds_read_b128 v[84:87], v163 offset:19968
	ds_read_b128 v[88:91], v163 offset:20032
	ds_read_b128 v[92:95], v163 offset:20176
	ds_read_b128 v[96:99], v163 offset:20240
	ds_read_b128 v[100:103], v163 offset:26624
	ds_read_b128 v[104:107], v163 offset:26688
	ds_read_b128 v[108:111], v163 offset:26832
	ds_read_b128 v[112:115], v163 offset:26896
	ds_read_b128 v[116:119], v163 offset:33280
	ds_read_b128 v[120:123], v163 offset:33344
	ds_read_b128 v[180:183], v163 offset:33488
	ds_read_b128 v[184:187], v163 offset:33552
	s_waitcnt lgkmcnt(11)
	v_mfma_f32_16x16x32_bf16 v[84:87], v[84:87], v[80:83], 0
	s_waitcnt lgkmcnt(10)
	v_mfma_f32_16x16x32_bf16 v[136:139], v[88:91], v[76:79], v[84:87]
	s_waitcnt lgkmcnt(9)
	v_mfma_f32_16x16x32_bf16 v[84:87], v[92:95], v[80:83], 0
	s_waitcnt lgkmcnt(8)
	v_mfma_f32_16x16x32_bf16 v[132:135], v[96:99], v[76:79], v[84:87]
	s_waitcnt lgkmcnt(7)
	v_mfma_f32_16x16x32_bf16 v[84:87], v[100:103], v[80:83], 0
	s_waitcnt lgkmcnt(6)
	v_mfma_f32_16x16x32_bf16 v[128:131], v[104:107], v[76:79], v[84:87]
	s_waitcnt lgkmcnt(5)
	v_mfma_f32_16x16x32_bf16 v[84:87], v[108:111], v[80:83], 0
	s_waitcnt lgkmcnt(4)
	v_mfma_f32_16x16x32_bf16 v[124:127], v[112:115], v[76:79], v[84:87]
	s_waitcnt lgkmcnt(3)
	v_mfma_f32_16x16x32_bf16 v[84:87], v[116:119], v[80:83], 0
	s_waitcnt lgkmcnt(2)
	v_mfma_f32_16x16x32_bf16 v[120:123], v[120:123], v[76:79], v[84:87]
	s_waitcnt lgkmcnt(1)
	v_mfma_f32_16x16x32_bf16 v[84:87], v[180:183], v[80:83], 0
	s_waitcnt lgkmcnt(0)
	v_mfma_f32_16x16x32_bf16 v[116:119], v[184:187], v[76:79], v[84:87]
	s_nop 5
	ds_read_b128 v[84:87], v163 offset:39936
	ds_read_b128 v[88:91], v163 offset:40000
	ds_read_b128 v[92:95], v163 offset:40144
	ds_read_b128 v[96:99], v163 offset:40208
	ds_read_b128 v[100:103], v163 offset:46592
	ds_read_b128 v[104:107], v163 offset:46656
	ds_read_b128 v[180:183], v163 offset:46800
	ds_read_b128 v[184:187], v163 offset:46864
	ds_read_b128 v[196:199], v163 offset:53248
	ds_read_b128 v[200:203], v163 offset:53312
	ds_read_b128 v[204:207], v163 offset:53456
	ds_read_b128 v[208:211], v163 offset:53520
	s_waitcnt lgkmcnt(11)
	v_mfma_f32_16x16x32_bf16 v[84:87], v[84:87], v[80:83], 0
	s_waitcnt lgkmcnt(10)
	v_mfma_f32_16x16x32_bf16 v[112:115], v[88:91], v[76:79], v[84:87]
	s_waitcnt lgkmcnt(9)
	v_mfma_f32_16x16x32_bf16 v[84:87], v[92:95], v[80:83], 0
	s_waitcnt lgkmcnt(8)
	v_mfma_f32_16x16x32_bf16 v[108:111], v[96:99], v[76:79], v[84:87]
	s_waitcnt lgkmcnt(7)
	v_mfma_f32_16x16x32_bf16 v[84:87], v[100:103], v[80:83], 0
	s_waitcnt lgkmcnt(6)
	v_mfma_f32_16x16x32_bf16 v[104:107], v[104:107], v[76:79], v[84:87]
	s_waitcnt lgkmcnt(5)
	v_mfma_f32_16x16x32_bf16 v[84:87], v[180:183], v[80:83], 0
	s_waitcnt lgkmcnt(4)
	v_mfma_f32_16x16x32_bf16 v[100:103], v[184:187], v[76:79], v[84:87]
	s_waitcnt lgkmcnt(3)
	v_mfma_f32_16x16x32_bf16 v[84:87], v[196:199], v[80:83], 0
	s_waitcnt lgkmcnt(2)
	v_mfma_f32_16x16x32_bf16 v[96:99], v[200:203], v[76:79], v[84:87]
	s_waitcnt lgkmcnt(1)
	v_mfma_f32_16x16x32_bf16 v[84:87], v[204:207], v[80:83], 0
	s_waitcnt lgkmcnt(0)
	v_mfma_f32_16x16x32_bf16 v[92:95], v[208:211], v[76:79], v[84:87]
	s_nop 5
	v_mad_u32_u24 v84, v162, s8, 0
	v_add3_u32 v84, v84, v176, s46
	ds_read_b128 v[88:91], v84
	ds_read_b128 v[84:87], v84 offset:64
	v_lshlrev_b32_e32 v163, 3, v161
	v_add_u32_e32 v187, s3, v163
	v_add_u32_e32 v168, s21, v187
	v_sub_u32_e32 v169, v178, v168
	v_add_u32_e32 v179, 0x80, v169
	v_add_u32_e32 v169, 0x7f, v169
	v_cmp_gt_u32_e32 vcc, s33, v168
	v_cmp_gt_u32_e64 s[0:1], s34, v179
	v_cmp_gt_u32_e64 s[40:41], s34, v169
	s_and_b64 s[0:1], vcc, s[0:1]
	s_and_b64 s[40:41], vcc, s[40:41]
	v_cndmask_b32_e64 v181, v231, v188, s[0:1]
	v_cndmask_b32_e64 v179, v231, v192, s[40:41]
	v_max_f32_e32 v169, v179, v179
	v_max_f32_e32 v180, v181, v181
	v_max_f32_e32 v169, v180, v169
	v_or_b32_e32 v180, 2, v168
	v_sub_u32_e32 v180, v178, v180
	v_add_u32_e32 v182, 0x80, v180
	v_add_u32_e32 v180, 0x7f, v180
	v_cmp_gt_u32_e64 s[0:1], s34, v182
	v_cmp_gt_u32_e64 s[40:41], s34, v180
	s_and_b64 s[0:1], vcc, s[0:1]
	s_and_b64 s[40:41], vcc, s[40:41]
	v_cndmask_b32_e64 v185, v231, v189, s[0:1]
	v_cndmask_b32_e64 v182, v231, v193, s[40:41]
	v_max_f32_e32 v180, v182, v182
	v_max_f32_e32 v183, v185, v185
	v_max_f32_e32 v180, v183, v180
	s_waitcnt lgkmcnt(1)
	v_mfma_f32_16x16x32_bf16 v[80:83], v[88:91], v[80:83], 0
	s_waitcnt vmcnt(2)
	v_max3_f32 v169, v177, v169, v180
	v_or_b32_e32 v180, 4, v168
	v_sub_u32_e32 v180, v178, v180
	v_add_u32_e32 v183, 0x80, v180
	v_add_u32_e32 v180, 0x7f, v180
	v_cmp_gt_u32_e64 s[0:1], s34, v183
	v_cmp_gt_u32_e64 s[40:41], s34, v180
	s_and_b64 s[0:1], vcc, s[0:1]
	s_and_b64 s[40:41], vcc, s[40:41]
	v_cndmask_b32_e64 v183, v231, v190, s[0:1]
	v_cndmask_b32_e64 v180, v231, v194, s[40:41]
	v_or_b32_e32 v168, 6, v168
	v_max_f32_e32 v184, v180, v180
	v_max_f32_e32 v186, v183, v183
	v_sub_u32_e32 v168, v178, v168
	v_max_f32_e32 v188, v186, v184
	v_add_u32_e32 v184, 0x80, v168
	v_add_u32_e32 v168, 0x7f, v168
	v_cmp_gt_u32_e64 s[0:1], s34, v184
	v_cmp_gt_u32_e64 s[40:41], s34, v168
	s_and_b64 s[0:1], vcc, s[0:1]
	s_and_b64 vcc, vcc, s[40:41]
	v_cndmask_b32_e64 v186, v231, v191, s[0:1]
	v_cndmask_b32_e32 v184, v231, v195, vcc
	v_max_f32_e32 v168, v184, v184
	v_max_f32_e32 v189, v186, v186
	v_max_f32_e32 v168, v189, v168
	v_max3_f32 v188, v169, v188, v168
	v_add_u32_e32 v168, s22, v187
	v_sub_u32_e32 v169, v178, v168
	v_add_u32_e32 v189, 0x80, v169
	v_add_u32_e32 v169, 0x7f, v169
	v_cmp_gt_u32_e32 vcc, s33, v168
	v_cmp_gt_u32_e64 s[0:1], s34, v189
	v_cmp_gt_u32_e64 s[40:41], s34, v169
	s_and_b64 s[0:1], vcc, s[0:1]
	s_and_b64 s[40:41], vcc, s[40:41]
	v_cndmask_b32_e64 v152, v231, v152, s[0:1]
	v_cndmask_b32_e64 v148, v231, v148, s[40:41]
	v_max_f32_e32 v169, v148, v148
	v_max_f32_e32 v189, v152, v152
	v_max_f32_e32 v169, v189, v169
	v_or_b32_e32 v189, 2, v168
	v_sub_u32_e32 v189, v178, v189
	v_add_u32_e32 v190, 0x80, v189
	v_cmp_gt_u32_e64 s[0:1], s34, v190
	v_add_u32_e32 v189, 0x7f, v189
	s_and_b64 s[40:41], vcc, s[0:1]
	v_cmp_gt_u32_e64 s[0:1], s34, v189
	s_and_b64 s[0:1], vcc, s[0:1]
	v_cndmask_b32_e64 v153, v231, v153, s[40:41]
	v_cndmask_b32_e64 v149, v231, v149, s[0:1]
	v_max_f32_e32 v189, v149, v149
	v_max_f32_e32 v190, v153, v153
	v_max_f32_e32 v189, v190, v189
	v_max3_f32 v169, v188, v169, v189
	v_or_b32_e32 v188, 4, v168
	v_sub_u32_e32 v188, v178, v188
	v_add_u32_e32 v189, 0x80, v188
	v_add_u32_e32 v188, 0x7f, v188
	v_cmp_gt_u32_e64 s[0:1], s34, v189
	v_cmp_gt_u32_e64 s[40:41], s34, v188
	s_and_b64 s[0:1], vcc, s[0:1]
	s_and_b64 s[40:41], vcc, s[40:41]
	v_cndmask_b32_e64 v154, v231, v154, s[0:1]
	v_cndmask_b32_e64 v150, v231, v150, s[40:41]
	v_or_b32_e32 v168, 6, v168
	v_max_f32_e32 v188, v150, v150
	v_max_f32_e32 v189, v154, v154
	v_sub_u32_e32 v168, v178, v168
	v_max_f32_e32 v188, v189, v188
	v_add_u32_e32 v189, 0x80, v168
	v_add_u32_e32 v168, 0x7f, v168
	v_cmp_gt_u32_e64 s[0:1], s34, v189
	v_cmp_gt_u32_e64 s[40:41], s34, v168
	s_and_b64 s[0:1], vcc, s[0:1]
	s_and_b64 vcc, vcc, s[40:41]
	v_cndmask_b32_e64 v155, v231, v155, s[0:1]
	v_cndmask_b32_e32 v151, v231, v151, vcc
	v_max_f32_e32 v168, v151, v151
	v_max_f32_e32 v189, v155, v155
	v_max_f32_e32 v168, v189, v168
	v_max3_f32 v168, v169, v188, v168
	v_add_u32_e32 v169, s23, v187
	v_sub_u32_e32 v188, v178, v169
	v_add_u32_e32 v189, 0x80, v188
	v_add_u32_e32 v188, 0x7f, v188
	v_cmp_gt_u32_e32 vcc, s33, v169
	v_cmp_gt_u32_e64 s[0:1], s34, v189
	v_cmp_gt_u32_e64 s[40:41], s34, v188
	s_and_b64 s[0:1], vcc, s[0:1]
	s_and_b64 s[40:41], vcc, s[40:41]
	v_cndmask_b32_e64 v144, v231, v144, s[0:1]
	v_cndmask_b32_e64 v140, v231, v140, s[40:41]
	v_max_f32_e32 v188, v140, v140
	v_max_f32_e32 v189, v144, v144
	v_max_f32_e32 v188, v189, v188
	v_or_b32_e32 v189, 2, v169
	v_sub_u32_e32 v189, v178, v189
	v_add_u32_e32 v190, 0x80, v189
	v_add_u32_e32 v189, 0x7f, v189
	v_cmp_gt_u32_e64 s[0:1], s34, v190
	v_cmp_gt_u32_e64 s[40:41], s34, v189
	s_and_b64 s[0:1], vcc, s[0:1]
	s_and_b64 s[40:41], vcc, s[40:41]
	v_cndmask_b32_e64 v145, v231, v145, s[0:1]
	v_cndmask_b32_e64 v141, v231, v141, s[40:41]
	v_max_f32_e32 v189, v141, v141
	v_max_f32_e32 v190, v145, v145
	v_max_f32_e32 v189, v190, v189
	v_max3_f32 v168, v168, v188, v189
	v_or_b32_e32 v188, 4, v169
	v_sub_u32_e32 v188, v178, v188
	v_add_u32_e32 v189, 0x80, v188
	v_add_u32_e32 v188, 0x7f, v188
	v_cmp_gt_u32_e64 s[0:1], s34, v189
	v_cmp_gt_u32_e64 s[40:41], s34, v188
	s_and_b64 s[0:1], vcc, s[0:1]
	s_and_b64 s[40:41], vcc, s[40:41]
	v_cndmask_b32_e64 v146, v231, v146, s[0:1]
	v_cndmask_b32_e64 v142, v231, v142, s[40:41]
	v_or_b32_e32 v169, 6, v169
	v_max_f32_e32 v188, v142, v142
	v_max_f32_e32 v189, v146, v146
	v_sub_u32_e32 v169, v178, v169
	v_max_f32_e32 v188, v189, v188
	v_add_u32_e32 v189, 0x80, v169
	v_add_u32_e32 v169, 0x7f, v169
	v_cmp_gt_u32_e64 s[0:1], s34, v189
	v_cmp_gt_u32_e64 s[40:41], s34, v169
	s_and_b64 s[0:1], vcc, s[0:1]
	s_and_b64 vcc, vcc, s[40:41]
	v_cndmask_b32_e64 v147, v231, v147, s[0:1]
	v_cndmask_b32_e32 v143, v231, v143, vcc
	v_max_f32_e32 v169, v143, v143
	v_max_f32_e32 v189, v147, v147
	v_max_f32_e32 v169, v189, v169
	v_max3_f32 v168, v168, v188, v169
	v_add_u32_e32 v169, s26, v187
	v_sub_u32_e32 v188, v178, v169
	v_add_u32_e32 v189, 0x80, v188
	v_add_u32_e32 v188, 0x7f, v188
	v_cmp_gt_u32_e32 vcc, s33, v169
	v_cmp_gt_u32_e64 s[0:1], s34, v189
	v_cmp_gt_u32_e64 s[40:41], s34, v188
	s_and_b64 s[0:1], vcc, s[0:1]
	s_and_b64 s[40:41], vcc, s[40:41]
	v_cndmask_b32_e64 v136, v231, v136, s[0:1]
	v_cndmask_b32_e64 v132, v231, v132, s[40:41]
	v_max_f32_e32 v188, v132, v132
	v_max_f32_e32 v189, v136, v136
	v_max_f32_e32 v188, v189, v188
	v_or_b32_e32 v189, 2, v169
	v_sub_u32_e32 v189, v178, v189
	v_add_u32_e32 v190, 0x80, v189
	v_add_u32_e32 v189, 0x7f, v189
	v_cmp_gt_u32_e64 s[0:1], s34, v190
	v_cmp_gt_u32_e64 s[40:41], s34, v189
	s_and_b64 s[0:1], vcc, s[0:1]
	s_and_b64 s[40:41], vcc, s[40:41]
	v_cndmask_b32_e64 v137, v231, v137, s[0:1]
	v_cndmask_b32_e64 v133, v231, v133, s[40:41]
	v_max_f32_e32 v189, v133, v133
	v_max_f32_e32 v190, v137, v137
	v_max_f32_e32 v189, v190, v189
	v_max3_f32 v168, v168, v188, v189
	v_or_b32_e32 v188, 4, v169
	v_sub_u32_e32 v188, v178, v188
	v_add_u32_e32 v189, 0x80, v188
	v_add_u32_e32 v188, 0x7f, v188
	v_cmp_gt_u32_e64 s[0:1], s34, v189
	v_cmp_gt_u32_e64 s[40:41], s34, v188
	s_and_b64 s[0:1], vcc, s[0:1]
	s_and_b64 s[40:41], vcc, s[40:41]
	v_cndmask_b32_e64 v138, v231, v138, s[0:1]
	v_cndmask_b32_e64 v134, v231, v134, s[40:41]
	v_or_b32_e32 v169, 6, v169
	v_max_f32_e32 v188, v134, v134
	v_max_f32_e32 v189, v138, v138
	v_sub_u32_e32 v169, v178, v169
	v_max_f32_e32 v188, v189, v188
	v_add_u32_e32 v189, 0x80, v169
	v_add_u32_e32 v169, 0x7f, v169
	v_cmp_gt_u32_e64 s[0:1], s34, v189
	v_cmp_gt_u32_e64 s[40:41], s34, v169
	s_and_b64 s[0:1], vcc, s[0:1]
	s_and_b64 vcc, vcc, s[40:41]
	v_cndmask_b32_e64 v139, v231, v139, s[0:1]
	v_cndmask_b32_e32 v135, v231, v135, vcc
	v_max_f32_e32 v169, v135, v135
	v_max_f32_e32 v189, v139, v139
	v_max_f32_e32 v169, v189, v169
	v_max3_f32 v168, v168, v188, v169
	v_add_u32_e32 v169, s27, v187
	v_sub_u32_e32 v188, v178, v169
	v_add_u32_e32 v189, 0x80, v188
	v_add_u32_e32 v188, 0x7f, v188
	v_cmp_gt_u32_e32 vcc, s33, v169
	v_cmp_gt_u32_e64 s[0:1], s34, v189
	v_cmp_gt_u32_e64 s[40:41], s34, v188
	s_and_b64 s[0:1], vcc, s[0:1]
	s_and_b64 s[40:41], vcc, s[40:41]
	v_cndmask_b32_e64 v128, v231, v128, s[0:1]
	v_cndmask_b32_e64 v124, v231, v124, s[40:41]
	v_max_f32_e32 v188, v124, v124
	v_max_f32_e32 v189, v128, v128
	v_max_f32_e32 v188, v189, v188
	v_or_b32_e32 v189, 2, v169
	v_sub_u32_e32 v189, v178, v189
	v_add_u32_e32 v190, 0x80, v189
	v_add_u32_e32 v189, 0x7f, v189
	v_cmp_gt_u32_e64 s[0:1], s34, v190
	v_cmp_gt_u32_e64 s[40:41], s34, v189
	s_and_b64 s[0:1], vcc, s[0:1]
	s_and_b64 s[40:41], vcc, s[40:41]
	v_cndmask_b32_e64 v129, v231, v129, s[0:1]
	v_cndmask_b32_e64 v125, v231, v125, s[40:41]
	v_max_f32_e32 v189, v125, v125
	v_max_f32_e32 v190, v129, v129
	v_max_f32_e32 v189, v190, v189
	v_max3_f32 v168, v168, v188, v189
	v_or_b32_e32 v188, 4, v169
	v_sub_u32_e32 v188, v178, v188
	v_add_u32_e32 v189, 0x80, v188
	v_add_u32_e32 v188, 0x7f, v188
	v_cmp_gt_u32_e64 s[0:1], s34, v189
	v_cmp_gt_u32_e64 s[40:41], s34, v188
	s_and_b64 s[0:1], vcc, s[0:1]
	s_and_b64 s[40:41], vcc, s[40:41]
	v_cndmask_b32_e64 v130, v231, v130, s[0:1]
	v_cndmask_b32_e64 v126, v231, v126, s[40:41]
	v_or_b32_e32 v169, 6, v169
	v_max_f32_e32 v188, v126, v126
	v_max_f32_e32 v189, v130, v130
	v_sub_u32_e32 v169, v178, v169
	v_max_f32_e32 v189, v189, v188
	v_add_u32_e32 v188, 0x80, v169
	v_add_u32_e32 v169, 0x7f, v169
	v_cmp_gt_u32_e64 s[0:1], s34, v188
	v_cmp_gt_u32_e64 s[40:41], s34, v169
	s_and_b64 s[0:1], vcc, s[0:1]
	s_and_b64 vcc, vcc, s[40:41]
	v_cndmask_b32_e64 v131, v231, v131, s[0:1]
	v_cndmask_b32_e32 v188, v231, v127, vcc
	v_max_f32_e32 v127, v188, v188
	v_max_f32_e32 v169, v131, v131
	v_max_f32_e32 v127, v169, v127
	v_add_u32_e32 v169, s30, v187
	v_max3_f32 v168, v168, v189, v127
	v_sub_u32_e32 v127, v178, v169
	v_add_u32_e32 v189, 0x80, v127
	v_add_u32_e32 v127, 0x7f, v127
	v_cmp_gt_u32_e32 vcc, s33, v169
	v_cmp_gt_u32_e64 s[0:1], s34, v189
	v_cmp_gt_u32_e64 s[40:41], s34, v127
	s_and_b64 s[0:1], vcc, s[0:1]
	s_and_b64 s[40:41], vcc, s[40:41]
	v_cndmask_b32_e64 v120, v231, v120, s[0:1]
	v_cndmask_b32_e64 v116, v231, v116, s[40:41]
	v_max_f32_e32 v127, v116, v116
	v_max_f32_e32 v189, v120, v120
	v_max_f32_e32 v189, v189, v127
	v_or_b32_e32 v127, 2, v169
	v_sub_u32_e32 v127, v178, v127
	v_add_u32_e32 v190, 0x80, v127
	v_add_u32_e32 v127, 0x7f, v127
	v_cmp_gt_u32_e64 s[0:1], s34, v190
	v_cmp_gt_u32_e64 s[40:41], s34, v127
	s_and_b64 s[0:1], vcc, s[0:1]
	s_and_b64 s[40:41], vcc, s[40:41]
	v_cndmask_b32_e64 v121, v231, v121, s[0:1]
	v_cndmask_b32_e64 v127, v231, v117, s[40:41]
	v_max_f32_e32 v117, v127, v127
	v_max_f32_e32 v190, v121, v121
	v_max_f32_e32 v117, v190, v117
	v_max3_f32 v117, v168, v189, v117
	v_or_b32_e32 v168, 4, v169
	v_sub_u32_e32 v168, v178, v168
	v_add_u32_e32 v189, 0x80, v168
	v_add_u32_e32 v168, 0x7f, v168
	v_cmp_gt_u32_e64 s[0:1], s34, v189
	v_cmp_gt_u32_e64 s[40:41], s34, v168
	s_and_b64 s[0:1], vcc, s[0:1]
	s_and_b64 s[40:41], vcc, s[40:41]
	v_cndmask_b32_e64 v122, v231, v122, s[0:1]
	v_cndmask_b32_e64 v118, v231, v118, s[40:41]
	v_or_b32_e32 v169, 6, v169
	v_max_f32_e32 v168, v118, v118
	v_max_f32_e32 v189, v122, v122
	v_sub_u32_e32 v169, v178, v169
	v_max_f32_e32 v168, v189, v168
	v_add_u32_e32 v189, 0x80, v169
	v_add_u32_e32 v169, 0x7f, v169
	v_cmp_gt_u32_e64 s[0:1], s34, v189
	v_cmp_gt_u32_e64 s[40:41], s34, v169
	s_and_b64 s[0:1], vcc, s[0:1]
	s_and_b64 vcc, vcc, s[40:41]
	v_cndmask_b32_e64 v189, v231, v123, s[0:1]
	v_cndmask_b32_e32 v190, v231, v119, vcc
	v_max_f32_e32 v119, v190, v190
	v_max_f32_e32 v123, v189, v189
	v_max_f32_e32 v119, v123, v119
	v_max3_f32 v123, v117, v168, v119
	v_add_u32_e32 v168, s31, v187
	v_sub_u32_e32 v117, v178, v168
	v_add_u32_e32 v119, 0x80, v117
	v_add_u32_e32 v117, 0x7f, v117
	v_cmp_gt_u32_e32 vcc, s33, v168
	v_cmp_gt_u32_e64 s[0:1], s34, v119
	v_cmp_gt_u32_e64 s[40:41], s34, v117
	s_and_b64 s[0:1], vcc, s[0:1]
	s_and_b64 s[40:41], vcc, s[40:41]
	v_cndmask_b32_e64 v117, v231, v112, s[0:1]
	v_cndmask_b32_e64 v108, v231, v108, s[40:41]
	v_max_f32_e32 v112, v108, v108
	v_max_f32_e32 v119, v117, v117
	v_max_f32_e32 v112, v119, v112
	v_or_b32_e32 v119, 2, v168
	v_sub_u32_e32 v119, v178, v119
	v_add_u32_e32 v169, 0x80, v119
	v_add_u32_e32 v119, 0x7f, v119
	v_cmp_gt_u32_e64 s[0:1], s34, v169
	v_cmp_gt_u32_e64 s[40:41], s34, v119
	s_and_b64 s[0:1], vcc, s[0:1]
	s_and_b64 s[40:41], vcc, s[40:41]
	v_cndmask_b32_e64 v113, v231, v113, s[0:1]
	v_cndmask_b32_e64 v119, v231, v109, s[40:41]
	v_max_f32_e32 v109, v119, v119
	v_max_f32_e32 v169, v113, v113
	v_max_f32_e32 v109, v169, v109
	v_max3_f32 v109, v123, v112, v109
	v_or_b32_e32 v112, 4, v168
	v_sub_u32_e32 v112, v178, v112
	v_add_u32_e32 v123, 0x80, v112
	v_add_u32_e32 v112, 0x7f, v112
	v_cmp_gt_u32_e64 s[0:1], s34, v123
	v_cmp_gt_u32_e64 s[40:41], s34, v112
	s_and_b64 s[0:1], vcc, s[0:1]
	s_and_b64 s[40:41], vcc, s[40:41]
	v_cndmask_b32_e64 v114, v231, v114, s[0:1]
	v_cndmask_b32_e64 v123, v231, v110, s[40:41]
	v_max_f32_e32 v110, v123, v123
	v_max_f32_e32 v112, v114, v114
	v_max_f32_e32 v110, v112, v110
	v_or_b32_e32 v112, 6, v168
	v_sub_u32_e32 v112, v178, v112
	v_add_u32_e32 v168, 0x80, v112
	v_add_u32_e32 v112, 0x7f, v112
	v_cmp_gt_u32_e64 s[0:1], s34, v168
	v_cmp_gt_u32_e64 s[40:41], s34, v112
	s_and_b64 s[0:1], vcc, s[0:1]
	s_and_b64 vcc, vcc, s[40:41]
	v_cndmask_b32_e64 v194, v231, v115, s[0:1]
	v_cndmask_b32_e32 v195, v231, v111, vcc
	v_max_f32_e32 v111, v195, v195
	v_max_f32_e32 v112, v194, v194
	v_max_f32_e32 v111, v112, v111
	v_add_u32_e32 v115, s76, v187
	v_max3_f32 v112, v109, v110, v111
	v_sub_u32_e32 v109, v178, v115
	v_add_u32_e32 v110, 0x80, v109
	v_add_u32_e32 v109, 0x7f, v109
	v_cmp_gt_u32_e32 vcc, s33, v115
	v_cmp_gt_u32_e64 s[0:1], s34, v110
	v_cmp_gt_u32_e64 s[40:41], s34, v109
	s_and_b64 s[0:1], vcc, s[0:1]
	s_and_b64 s[40:41], vcc, s[40:41]
	v_cndmask_b32_e64 v109, v231, v104, s[0:1]
	v_cndmask_b32_e64 v110, v231, v100, s[40:41]
	v_max_f32_e32 v100, v110, v110
	v_max_f32_e32 v104, v109, v109
	v_max_f32_e32 v100, v104, v100
	v_or_b32_e32 v104, 2, v115
	v_sub_u32_e32 v104, v178, v104
	v_add_u32_e32 v111, 0x80, v104
	v_add_u32_e32 v104, 0x7f, v104
	v_cmp_gt_u32_e64 s[0:1], s34, v111
	v_cmp_gt_u32_e64 s[40:41], s34, v104
	s_and_b64 s[0:1], vcc, s[0:1]
	s_and_b64 s[40:41], vcc, s[40:41]
	v_cndmask_b32_e64 v111, v231, v105, s[0:1]
	v_cndmask_b32_e64 v191, v231, v101, s[40:41]
	v_max_f32_e32 v101, v191, v191
	v_max_f32_e32 v104, v111, v111
	v_max_f32_e32 v101, v104, v101
	v_max3_f32 v100, v112, v100, v101
	v_or_b32_e32 v101, 4, v115
	v_sub_u32_e32 v101, v178, v101
	v_add_u32_e32 v104, 0x80, v101
	v_add_u32_e32 v101, 0x7f, v101
	v_cmp_gt_u32_e64 s[0:1], s34, v104
	v_cmp_gt_u32_e64 s[40:41], s34, v101
	s_and_b64 s[0:1], vcc, s[0:1]
	s_and_b64 s[40:41], vcc, s[40:41]
	v_cndmask_b32_e64 v192, v231, v106, s[0:1]
	v_cndmask_b32_e64 v193, v231, v102, s[40:41]
	v_max_f32_e32 v101, v193, v193
	v_max_f32_e32 v102, v192, v192
	v_max_f32_e32 v101, v102, v101
	v_or_b32_e32 v102, 6, v115
	v_sub_u32_e32 v102, v178, v102
	v_add_u32_e32 v104, 0x80, v102
	v_add_u32_e32 v102, 0x7f, v102
	v_cmp_gt_u32_e64 s[0:1], s34, v104
	v_cmp_gt_u32_e64 s[40:41], s34, v102
	s_and_b64 s[0:1], vcc, s[0:1]
	s_and_b64 vcc, vcc, s[40:41]
	v_cndmask_b32_e64 v200, v231, v107, s[0:1]
	v_cndmask_b32_e32 v201, v231, v103, vcc
	v_max_f32_e32 v102, v201, v201
	v_max_f32_e32 v103, v200, v200
	v_max_f32_e32 v102, v103, v102
	v_max3_f32 v100, v100, v101, v102
	v_add_u32_e32 v101, s77, v187
	v_sub_u32_e32 v102, v178, v101
	v_add_u32_e32 v103, 0x80, v102
	v_add_u32_e32 v102, 0x7f, v102
	v_cmp_gt_u32_e32 vcc, s33, v101
	v_cmp_gt_u32_e64 s[0:1], s34, v103
	v_cmp_gt_u32_e64 s[40:41], s34, v102
	s_and_b64 s[0:1], vcc, s[0:1]
	s_and_b64 s[40:41], vcc, s[40:41]
	v_cndmask_b32_e64 v115, v231, v96, s[0:1]
	v_cndmask_b32_e64 v187, v231, v92, s[40:41]
	v_max_f32_e32 v92, v187, v187
	v_max_f32_e32 v96, v115, v115
	v_max_f32_e32 v92, v96, v92
	v_or_b32_e32 v96, 2, v101
	v_sub_u32_e32 v96, v178, v96
	v_add_u32_e32 v102, 0x80, v96
	v_add_u32_e32 v96, 0x7f, v96
	v_cmp_gt_u32_e64 s[0:1], s34, v102
	v_cmp_gt_u32_e64 s[40:41], s34, v96
	s_and_b64 s[0:1], vcc, s[0:1]
	s_and_b64 s[40:41], vcc, s[40:41]
	v_cndmask_b32_e64 v196, v231, v97, s[0:1]
	v_cndmask_b32_e64 v197, v231, v93, s[40:41]
	v_max_f32_e32 v93, v197, v197
	v_max_f32_e32 v96, v196, v196
	v_max_f32_e32 v93, v96, v93
	v_max3_f32 v92, v100, v92, v93
	v_or_b32_e32 v93, 4, v101
	v_sub_u32_e32 v93, v178, v93
	v_add_u32_e32 v96, 0x80, v93
	v_add_u32_e32 v93, 0x7f, v93
	v_cmp_gt_u32_e64 s[0:1], s34, v96
	v_cmp_gt_u32_e64 s[40:41], s34, v93
	s_and_b64 s[0:1], vcc, s[0:1]
	s_and_b64 s[40:41], vcc, s[40:41]
	v_cndmask_b32_e64 v198, v231, v98, s[0:1]
	v_cndmask_b32_e64 v199, v231, v94, s[40:41]
	v_max_f32_e32 v93, v199, v199
	v_max_f32_e32 v94, v198, v198
	v_max_f32_e32 v93, v94, v93
	v_or_b32_e32 v94, 6, v101
	v_sub_u32_e32 v94, v178, v94
	v_add_u32_e32 v96, 0x80, v94
	v_add_u32_e32 v94, 0x7f, v94
	v_cmp_gt_u32_e64 s[0:1], s34, v96
	v_cmp_gt_u32_e64 s[40:41], s34, v94
	s_and_b64 s[0:1], vcc, s[0:1]
	s_and_b64 vcc, vcc, s[40:41]
	v_cndmask_b32_e64 v178, v231, v99, s[0:1]
	v_cndmask_b32_e32 v202, v231, v95, vcc
	s_waitcnt lgkmcnt(0)
	v_mfma_f32_16x16x32_bf16 v[80:83], v[84:87], v[76:79], v[80:83]
	v_max_f32_e32 v94, v202, v202
	v_max_f32_e32 v95, v178, v178
	v_max_f32_e32 v94, v95, v94
	v_max3_f32 v92, v92, v93, v94
	v_mov_b32_e32 v85, v3
	s_nop 2
	v_max3_f32 v76, v92, v80, v81
	v_max3_f32 v76, v76, v82, v83
	ds_bpermute_b32 v77, v157, v76
	s_waitcnt lgkmcnt(0)
	v_max_f32_e32 v77, v77, v77
	v_max_f32_e32 v76, v76, v77
	ds_bpermute_b32 v77, v156, v76
	s_waitcnt lgkmcnt(0)
	v_max_f32_e32 v77, v77, v77
	v_max_f32_e32 v112, v76, v77
	v_sub_f32_e32 v76, v181, v112
	v_mul_f32_e32 v76, 0x3fb8aa3b, v76
	v_exp_f32_e32 v92, v76
	v_sub_f32_e32 v76, v179, v112
	v_mul_f32_e32 v76, 0x3fb8aa3b, v76
	v_exp_f32_e32 v93, v76
	v_sub_f32_e32 v76, v185, v112
	v_mul_f32_e32 v76, 0x3fb8aa3b, v76
	v_exp_f32_e32 v78, v76
	v_sub_f32_e32 v76, v182, v112
	v_mul_f32_e32 v76, 0x3fb8aa3b, v76
	v_exp_f32_e32 v84, v76
	v_add_f32_e32 v79, v92, v93
	v_sub_f32_e32 v80, v80, v112
	v_mul_f32_e32 v80, 0x3fb8aa3b, v80
	v_pk_add_f32 v[76:77], v[78:79], v[84:85]
	v_sub_f32_e32 v81, v81, v112
	v_pk_add_f32 v[86:87], v[76:77], v[76:77] op_sel_hi:[0,1]
	v_sub_f32_e32 v76, v183, v112
	v_mul_f32_e32 v76, 0x3fb8aa3b, v76
	v_exp_f32_e32 v79, v76
	v_sub_f32_e32 v76, v180, v112
	v_mul_f32_e32 v76, 0x3fb8aa3b, v76
	v_exp_f32_e32 v85, v76
	v_sub_f32_e32 v76, v186, v112
	v_mul_f32_e32 v76, 0x3fb8aa3b, v76
	v_exp_f32_e32 v88, v76
	v_sub_f32_e32 v76, v184, v112
	v_mul_f32_e32 v76, 0x3fb8aa3b, v76
	v_exp_f32_e32 v86, v76
	v_add_f32_e32 v89, v79, v85
	v_exp_f32_e32 v80, v80
	v_mul_f32_e32 v81, 0x3fb8aa3b, v81
	v_pk_add_f32 v[76:77], v[88:89], v[86:87]
	v_sub_f32_e32 v82, v82, v112
	v_pk_add_f32 v[90:91], v[76:77], v[76:77] op_sel_hi:[0,1]
	v_cvt_pk_bf16_f32 v77, v78, v84
	v_sub_f32_e32 v84, v152, v112
	v_mul_f32_e32 v84, 0x3fb8aa3b, v84
	v_exp_f32_e32 v96, v84
	v_sub_f32_e32 v84, v148, v112
	v_mul_f32_e32 v84, 0x3fb8aa3b, v84
	v_exp_f32_e32 v97, v84
	v_sub_f32_e32 v84, v153, v112
	v_mul_f32_e32 v84, 0x3fb8aa3b, v84
	v_cvt_pk_bf16_f32 v78, v79, v85
	v_cvt_pk_bf16_f32 v79, v88, v86
	v_exp_f32_e32 v86, v84
	v_sub_f32_e32 v84, v149, v112
	v_mul_f32_e32 v84, 0x3fb8aa3b, v84
	v_exp_f32_e32 v90, v84
	v_add_f32_e32 v87, v96, v97
	v_cvt_pk_bf16_f32 v76, v92, v93
	v_exp_f32_e32 v81, v81
	v_pk_add_f32 v[84:85], v[86:87], v[90:91]
	v_mul_f32_e32 v82, 0x3fb8aa3b, v82
	v_pk_add_f32 v[88:89], v[84:85], v[84:85] op_sel_hi:[0,1]
	v_sub_f32_e32 v84, v154, v112
	v_mul_f32_e32 v84, 0x3fb8aa3b, v84
	v_exp_f32_e32 v87, v84
	v_sub_f32_e32 v84, v150, v112
	v_mul_f32_e32 v84, 0x3fb8aa3b, v84
	v_exp_f32_e32 v91, v84
	v_sub_f32_e32 v84, v155, v112
	v_mul_f32_e32 v84, 0x3fb8aa3b, v84
	v_exp_f32_e32 v92, v84
	v_sub_f32_e32 v84, v151, v112
	v_mul_f32_e32 v84, 0x3fb8aa3b, v84
	v_exp_f32_e32 v88, v84
	v_add_f32_e32 v93, v87, v91
	v_sub_f32_e32 v83, v83, v112
	v_exp_f32_e32 v82, v82
	v_pk_add_f32 v[84:85], v[92:93], v[88:89]
	v_mul_f32_e32 v83, 0x3fb8aa3b, v83
	v_pk_add_f32 v[94:95], v[84:85], v[84:85] op_sel_hi:[0,1]
	v_cvt_pk_bf16_f32 v85, v86, v90
	v_cvt_pk_bf16_f32 v86, v87, v91
	v_cvt_pk_bf16_f32 v87, v92, v88
	v_sub_f32_e32 v88, v144, v112
	v_mul_f32_e32 v88, 0x3fb8aa3b, v88
	v_exp_f32_e32 v100, v88
	v_sub_f32_e32 v88, v140, v112
	v_mul_f32_e32 v88, 0x3fb8aa3b, v88
	v_exp_f32_e32 v101, v88
	v_sub_f32_e32 v88, v145, v112
	v_mul_f32_e32 v88, 0x3fb8aa3b, v88
	v_exp_f32_e32 v90, v88
	v_sub_f32_e32 v88, v141, v112
	v_mul_f32_e32 v88, 0x3fb8aa3b, v88
	v_exp_f32_e32 v94, v88
	v_add_f32_e32 v91, v100, v101
	v_cvt_pk_bf16_f32 v84, v96, v97
	v_exp_f32_e32 v83, v83
	v_pk_add_f32 v[88:89], v[90:91], v[94:95]
	s_nop 0
	v_pk_add_f32 v[92:93], v[88:89], v[88:89] op_sel_hi:[0,1]
	v_sub_f32_e32 v88, v146, v112
	v_mul_f32_e32 v88, 0x3fb8aa3b, v88
	v_exp_f32_e32 v91, v88
	v_sub_f32_e32 v88, v142, v112
	v_mul_f32_e32 v88, 0x3fb8aa3b, v88
	v_exp_f32_e32 v95, v88
	v_sub_f32_e32 v88, v147, v112
	v_mul_f32_e32 v88, 0x3fb8aa3b, v88
	v_exp_f32_e32 v96, v88
	v_sub_f32_e32 v88, v143, v112
	v_mul_f32_e32 v88, 0x3fb8aa3b, v88
	v_exp_f32_e32 v92, v88
	v_add_f32_e32 v97, v91, v95
	v_pk_add_f32 v[88:89], v[96:97], v[92:93]
	s_nop 0
	v_pk_add_f32 v[98:99], v[88:89], v[88:89] op_sel_hi:[0,1]
	v_cvt_pk_bf16_f32 v89, v90, v94
	v_cvt_pk_bf16_f32 v90, v91, v95
	v_cvt_pk_bf16_f32 v91, v96, v92
	v_sub_f32_e32 v92, v136, v112
	v_mul_f32_e32 v92, 0x3fb8aa3b, v92
	v_exp_f32_e32 v104, v92
	v_sub_f32_e32 v92, v132, v112
	v_mul_f32_e32 v92, 0x3fb8aa3b, v92
	v_exp_f32_e32 v105, v92
	v_sub_f32_e32 v92, v137, v112
	v_mul_f32_e32 v92, 0x3fb8aa3b, v92
	v_exp_f32_e32 v94, v92
	v_sub_f32_e32 v92, v133, v112
	v_mul_f32_e32 v92, 0x3fb8aa3b, v92
	v_exp_f32_e32 v98, v92
	v_add_f32_e32 v95, v104, v105
	v_cvt_pk_bf16_f32 v88, v100, v101
	v_pk_add_f32 v[92:93], v[94:95], v[98:99]
	s_nop 0
	v_pk_add_f32 v[96:97], v[92:93], v[92:93] op_sel_hi:[0,1]
	v_sub_f32_e32 v92, v138, v112
	v_mul_f32_e32 v92, 0x3fb8aa3b, v92
	v_exp_f32_e32 v95, v92
	v_sub_f32_e32 v92, v134, v112
	v_mul_f32_e32 v92, 0x3fb8aa3b, v92
	v_exp_f32_e32 v99, v92
	v_sub_f32_e32 v92, v139, v112
	v_mul_f32_e32 v92, 0x3fb8aa3b, v92
	v_exp_f32_e32 v100, v92
	v_sub_f32_e32 v92, v135, v112
	v_mul_f32_e32 v92, 0x3fb8aa3b, v92
	v_exp_f32_e32 v96, v92
	v_add_f32_e32 v101, v95, v99
	v_pk_add_f32 v[92:93], v[100:101], v[96:97]
	s_nop 0
	v_pk_add_f32 v[102:103], v[92:93], v[92:93] op_sel_hi:[0,1]
	v_cvt_pk_bf16_f32 v93, v94, v98
	v_cvt_pk_bf16_f32 v94, v95, v99
	v_cvt_pk_bf16_f32 v95, v100, v96
	v_sub_f32_e32 v96, v128, v112
	v_mul_f32_e32 v96, 0x3fb8aa3b, v96
	v_exp_f32_e32 v128, v96
	v_sub_f32_e32 v96, v124, v112
	v_mul_f32_e32 v96, 0x3fb8aa3b, v96
	v_exp_f32_e32 v124, v96
	v_sub_f32_e32 v96, v129, v112
	v_mul_f32_e32 v96, 0x3fb8aa3b, v96
	v_exp_f32_e32 v98, v96
	v_sub_f32_e32 v96, v125, v112
	v_mul_f32_e32 v96, 0x3fb8aa3b, v96
	v_exp_f32_e32 v102, v96
	v_add_f32_e32 v99, v128, v124
	v_cvt_pk_bf16_f32 v92, v104, v105
	v_pk_add_f32 v[96:97], v[98:99], v[102:103]
	s_nop 0
	v_pk_add_f32 v[100:101], v[96:97], v[96:97] op_sel_hi:[0,1]
	v_sub_f32_e32 v96, v130, v112
	v_mul_f32_e32 v96, 0x3fb8aa3b, v96
	v_exp_f32_e32 v99, v96
	v_sub_f32_e32 v96, v126, v112
	v_mul_f32_e32 v96, 0x3fb8aa3b, v96
	v_exp_f32_e32 v103, v96
	v_sub_f32_e32 v96, v131, v112
	v_mul_f32_e32 v96, 0x3fb8aa3b, v96
	v_exp_f32_e32 v104, v96
	v_sub_f32_e32 v96, v188, v112
	v_mul_f32_e32 v96, 0x3fb8aa3b, v96
	v_exp_f32_e32 v100, v96
	v_add_f32_e32 v105, v99, v103
	v_pk_add_f32 v[96:97], v[104:105], v[100:101]
	s_nop 0
	v_pk_add_f32 v[106:107], v[96:97], v[96:97] op_sel_hi:[0,1]
	v_cvt_pk_bf16_f32 v97, v98, v102
	v_cvt_pk_bf16_f32 v98, v99, v103
	v_cvt_pk_bf16_f32 v99, v104, v100
	v_sub_f32_e32 v100, v120, v112
	v_mul_f32_e32 v100, 0x3fb8aa3b, v100
	v_exp_f32_e32 v126, v100
	v_sub_f32_e32 v100, v116, v112
	v_mul_f32_e32 v100, 0x3fb8aa3b, v100
	v_exp_f32_e32 v116, v100
	v_sub_f32_e32 v100, v121, v112
	v_mul_f32_e32 v100, 0x3fb8aa3b, v100
	v_exp_f32_e32 v102, v100
	v_sub_f32_e32 v100, v127, v112
	v_mul_f32_e32 v100, 0x3fb8aa3b, v100
	v_exp_f32_e32 v106, v100
	v_add_f32_e32 v103, v126, v116
	v_cvt_pk_bf16_f32 v96, v128, v124
	v_pk_add_f32 v[100:101], v[102:103], v[106:107]
	s_nop 0
	v_pk_add_f32 v[104:105], v[100:101], v[100:101] op_sel_hi:[0,1]
	v_sub_f32_e32 v100, v122, v112
	v_mul_f32_e32 v100, 0x3fb8aa3b, v100
	v_exp_f32_e32 v103, v100
	v_sub_f32_e32 v100, v118, v112
	v_mul_f32_e32 v100, 0x3fb8aa3b, v100
	v_exp_f32_e32 v107, v100
	v_sub_f32_e32 v100, v189, v112
	v_mul_f32_e32 v100, 0x3fb8aa3b, v100
	v_exp_f32_e32 v120, v100
	v_sub_f32_e32 v100, v190, v112
	v_mul_f32_e32 v100, 0x3fb8aa3b, v100
	v_exp_f32_e32 v104, v100
	v_add_f32_e32 v121, v103, v107
	v_pk_add_f32 v[100:101], v[120:121], v[104:105]
	s_nop 0
	v_pk_add_f32 v[124:125], v[100:101], v[100:101] op_sel_hi:[0,1]
	v_cvt_pk_bf16_f32 v101, v102, v106
	v_cvt_pk_bf16_f32 v102, v103, v107
	v_cvt_pk_bf16_f32 v103, v120, v104
	v_sub_f32_e32 v104, v117, v112
	v_mul_f32_e32 v104, 0x3fb8aa3b, v104
	v_exp_f32_e32 v122, v104
	v_sub_f32_e32 v104, v108, v112
	v_mul_f32_e32 v104, 0x3fb8aa3b, v104
	v_exp_f32_e32 v108, v104
	v_sub_f32_e32 v104, v113, v112
	v_mul_f32_e32 v104, 0x3fb8aa3b, v104
	v_exp_f32_e32 v106, v104
	v_sub_f32_e32 v104, v119, v112
	v_mul_f32_e32 v104, 0x3fb8aa3b, v104
	v_exp_f32_e32 v124, v104
	v_add_f32_e32 v107, v122, v108
	v_cvt_pk_bf16_f32 v100, v126, v116
	v_pk_add_f32 v[104:105], v[106:107], v[124:125]
	s_nop 0
	v_pk_add_f32 v[116:117], v[104:105], v[104:105] op_sel_hi:[0,1]
	v_sub_f32_e32 v104, v114, v112
	v_mul_f32_e32 v104, 0x3fb8aa3b, v104
	v_exp_f32_e32 v107, v104
	v_sub_f32_e32 v104, v123, v112
	v_mul_f32_e32 v104, 0x3fb8aa3b, v104
	v_exp_f32_e32 v113, v104
	v_sub_f32_e32 v104, v194, v112
	v_mul_f32_e32 v104, 0x3fb8aa3b, v104
	v_exp_f32_e32 v118, v104
	v_sub_f32_e32 v104, v195, v112
	v_mul_f32_e32 v104, 0x3fb8aa3b, v104
	v_exp_f32_e32 v116, v104
	v_add_f32_e32 v119, v107, v113
	v_pk_add_f32 v[104:105], v[118:119], v[116:117]
	s_nop 0
	v_pk_add_f32 v[120:121], v[104:105], v[104:105] op_sel_hi:[0,1]
	v_cvt_pk_bf16_f32 v104, v122, v108
	v_sub_f32_e32 v108, v109, v112
	v_mul_f32_e32 v108, 0x3fb8aa3b, v108
	v_cvt_pk_bf16_f32 v105, v106, v124
	v_cvt_pk_bf16_f32 v106, v107, v113
	v_exp_f32_e32 v113, v108
	v_sub_f32_e32 v108, v110, v112
	v_mul_f32_e32 v108, 0x3fb8aa3b, v108
	v_exp_f32_e32 v110, v108
	v_sub_f32_e32 v108, v111, v112
	v_mul_f32_e32 v108, 0x3fb8aa3b, v108
	v_cvt_pk_bf16_f32 v107, v118, v116
	v_exp_f32_e32 v116, v108
	v_sub_f32_e32 v108, v191, v112
	v_mul_f32_e32 v108, 0x3fb8aa3b, v108
	v_exp_f32_e32 v120, v108
	v_add_f32_e32 v117, v113, v110
	v_pk_add_f32 v[108:109], v[116:117], v[120:121]
	s_nop 0
	v_pk_add_f32 v[118:119], v[108:109], v[108:109] op_sel_hi:[0,1]
	v_sub_f32_e32 v108, v192, v112
	v_mul_f32_e32 v108, 0x3fb8aa3b, v108
	v_exp_f32_e32 v111, v108
	v_sub_f32_e32 v108, v193, v112
	v_mul_f32_e32 v108, 0x3fb8aa3b, v108
	v_exp_f32_e32 v114, v108
	v_sub_f32_e32 v108, v200, v112
	v_mul_f32_e32 v108, 0x3fb8aa3b, v108
	v_exp_f32_e32 v122, v108
	v_sub_f32_e32 v108, v201, v112
	v_mul_f32_e32 v108, 0x3fb8aa3b, v108
	v_exp_f32_e32 v118, v108
	v_add_f32_e32 v123, v111, v114
	v_pk_add_f32 v[108:109], v[122:123], v[118:119]
	s_nop 0
	v_pk_add_f32 v[124:125], v[108:109], v[108:109] op_sel_hi:[0,1]
	v_cvt_pk_bf16_f32 v108, v113, v110
	v_cvt_pk_bf16_f32 v110, v111, v114
	v_sub_f32_e32 v114, v187, v112
	v_mul_f32_e32 v114, 0x3fb8aa3b, v114
	v_cvt_pk_bf16_f32 v111, v122, v118
	v_exp_f32_e32 v122, v114
	v_sub_f32_e32 v114, v196, v112
	v_sub_f32_e32 v113, v115, v112
	v_mul_f32_e32 v114, 0x3fb8aa3b, v114
	v_cvt_pk_bf16_f32 v109, v116, v120
	v_mul_f32_e32 v113, 0x3fb8aa3b, v113
	v_exp_f32_e32 v116, v114
	v_sub_f32_e32 v114, v197, v112
	v_exp_f32_e32 v113, v113
	v_mul_f32_e32 v114, 0x3fb8aa3b, v114
	v_exp_f32_e32 v124, v114
	v_add_f32_e32 v117, v113, v122
	v_pk_add_f32 v[114:115], v[116:117], v[124:125]
	s_nop 0
	v_pk_add_f32 v[118:119], v[114:115], v[114:115] op_sel_hi:[0,1]
	v_sub_f32_e32 v114, v198, v112
	v_mul_f32_e32 v114, 0x3fb8aa3b, v114
	v_exp_f32_e32 v117, v114
	v_sub_f32_e32 v114, v199, v112
	v_mul_f32_e32 v114, 0x3fb8aa3b, v114
	v_exp_f32_e32 v123, v114
	v_sub_f32_e32 v114, v178, v112
	v_mul_f32_e32 v114, 0x3fb8aa3b, v114
	v_exp_f32_e32 v120, v114
	v_sub_f32_e32 v114, v202, v112
	v_mul_f32_e32 v114, 0x3fb8aa3b, v114
	v_exp_f32_e32 v118, v114
	v_add_f32_e32 v121, v117, v123
	v_sub_f32_e32 v112, v177, v112
	v_mul_f32_e32 v112, 0x3fb8aa3b, v112
	v_pk_add_f32 v[114:115], v[120:121], v[118:119]
	v_exp_f32_e32 v112, v112
	v_add_f32_e32 v119, v114, v115
	v_cvt_pk_bf16_f32 v114, v113, v122
	v_add_f32_e32 v113, v80, v119
	v_add_f32_e32 v113, v81, v113
	v_add_f32_e32 v113, v82, v113
	v_add_f32_e32 v113, v83, v113
	v_cvt_pk_bf16_f32 v80, v80, v81
	v_cvt_pk_bf16_f32 v81, v82, v83
	ds_bpermute_b32 v82, v157, v113
	v_cvt_pk_bf16_f32 v115, v116, v124
	v_cvt_pk_bf16_f32 v116, v117, v123
	v_cvt_pk_bf16_f32 v117, v120, v118
	s_waitcnt lgkmcnt(0)
	v_add_f32_e32 v82, v113, v82
	ds_bpermute_b32 v83, v156, v82
	v_mad_u32_u24 v154, v162, s9, v158
	v_add3_u32 v155, v154, v176, s78
	ds_read_b128 v[118:121], v155
	ds_read_b128 v[122:125], v155 offset:12800
	ds_read_b128 v[126:129], v155 offset:25600
	ds_read_b128 v[130:133], v155 offset:38400
	ds_read_b128 v[134:137], v155 offset:64
	ds_read_b128 v[138:141], v155 offset:12864
	ds_read_b128 v[142:145], v155 offset:25664
	ds_read_b128 v[146:149], v155 offset:38464
	ds_read_b128 v[150:153], v155 offset:128
	ds_read_b128 v[176:179], v155 offset:12928
	ds_read_b128 v[180:183], v155 offset:25728
	ds_read_b128 v[184:187], v155 offset:38528
	s_waitcnt lgkmcnt(12)
	v_add_f32_e32 v113, v82, v83
	s_waitcnt lgkmcnt(11)
	v_mfma_f32_16x16x32_bf16 v[118:121], v[118:121], v[76:79], 0
	s_waitcnt lgkmcnt(10)
	v_mfma_f32_16x16x32_bf16 v[122:125], v[122:125], v[76:79], 0
	s_waitcnt lgkmcnt(9)
	v_mfma_f32_16x16x32_bf16 v[126:129], v[126:129], v[76:79], 0
	s_waitcnt lgkmcnt(8)
	v_mfma_f32_16x16x32_bf16 v[76:79], v[130:133], v[76:79], 0
	s_waitcnt lgkmcnt(7)
	v_mfma_f32_16x16x32_bf16 v[118:121], v[134:137], v[84:87], v[118:121]
	s_waitcnt lgkmcnt(6)
	v_mfma_f32_16x16x32_bf16 v[122:125], v[138:141], v[84:87], v[122:125]
	s_waitcnt lgkmcnt(5)
	v_mfma_f32_16x16x32_bf16 v[126:129], v[142:145], v[84:87], v[126:129]
	s_waitcnt lgkmcnt(4)
	v_mfma_f32_16x16x32_bf16 v[76:79], v[146:149], v[84:87], v[76:79]
	s_waitcnt lgkmcnt(3)
	v_mfma_f32_16x16x32_bf16 v[82:85], v[150:153], v[88:91], v[118:121]
	s_waitcnt lgkmcnt(2)
	v_mfma_f32_16x16x32_bf16 v[118:121], v[176:179], v[88:91], v[122:125]
	s_waitcnt lgkmcnt(1)
	v_mfma_f32_16x16x32_bf16 v[122:125], v[180:183], v[88:91], v[126:129]
	s_waitcnt lgkmcnt(0)
	v_mfma_f32_16x16x32_bf16 v[76:79], v[184:187], v[88:91], v[76:79]
	ds_read_b128 v[86:89], v155 offset:12992
	ds_read_b128 v[126:129], v155 offset:13056
	ds_read_b128 v[130:133], v155 offset:38592
	ds_read_b128 v[134:137], v155 offset:38656
	ds_read_b128 v[138:141], v155 offset:256
	ds_read_b128 v[142:145], v155 offset:320
	ds_read_b128 v[146:149], v155 offset:25792
	ds_read_b128 v[150:153], v155 offset:13120
	ds_read_b128 v[176:179], v155 offset:25856
	ds_read_b128 v[180:183], v155 offset:25920
	ds_read_b128 v[184:187], v155 offset:192
	ds_read_b128 v[188:191], v155 offset:38720
	s_waitcnt lgkmcnt(1)
	v_mfma_f32_16x16x32_bf16 v[82:85], v[184:187], v[92:95], v[82:85]
	v_mfma_f32_16x16x32_bf16 v[86:89], v[86:89], v[92:95], v[118:121]
	v_mfma_f32_16x16x32_bf16 v[118:121], v[146:149], v[92:95], v[122:125]
	v_mfma_f32_16x16x32_bf16 v[76:79], v[130:133], v[92:95], v[76:79]
	v_mfma_f32_16x16x32_bf16 v[82:85], v[138:141], v[96:99], v[82:85]
	v_mfma_f32_16x16x32_bf16 v[86:89], v[126:129], v[96:99], v[86:89]
	v_mfma_f32_16x16x32_bf16 v[90:93], v[176:179], v[96:99], v[118:121]
	v_mfma_f32_16x16x32_bf16 v[76:79], v[134:137], v[96:99], v[76:79]
	v_mfma_f32_16x16x32_bf16 v[82:85], v[142:145], v[100:103], v[82:85]
	v_mfma_f32_16x16x32_bf16 v[86:89], v[150:153], v[100:103], v[86:89]
	v_mfma_f32_16x16x32_bf16 v[90:93], v[180:183], v[100:103], v[90:93]
	s_waitcnt lgkmcnt(0)
	v_mfma_f32_16x16x32_bf16 v[76:79], v[188:191], v[100:103], v[76:79]
	ds_read_b128 v[94:97], v155 offset:13184
	ds_read_b128 v[98:101], v155 offset:13248
	ds_read_b128 v[118:121], v155 offset:38784
	ds_read_b128 v[122:125], v155 offset:38848
	ds_read_b128 v[126:129], v155 offset:448
	ds_read_b128 v[130:133], v155 offset:512
	ds_read_b128 v[134:137], v155 offset:25984
	ds_read_b128 v[138:141], v155 offset:13312
	ds_read_b128 v[142:145], v155 offset:26048
	ds_read_b128 v[146:149], v155 offset:26112
	ds_read_b128 v[150:153], v155 offset:384
	ds_read_b128 v[176:179], v155 offset:38912
	s_waitcnt lgkmcnt(1)
	v_mfma_f32_16x16x32_bf16 v[82:85], v[150:153], v[104:107], v[82:85]
	v_mfma_f32_16x16x32_bf16 v[86:89], v[94:97], v[104:107], v[86:89]
	v_mfma_f32_16x16x32_bf16 v[90:93], v[134:137], v[104:107], v[90:93]
	v_mfma_f32_16x16x32_bf16 v[76:79], v[118:121], v[104:107], v[76:79]
	v_mfma_f32_16x16x32_bf16 v[82:85], v[126:129], v[108:111], v[82:85]
	v_mfma_f32_16x16x32_bf16 v[86:89], v[98:101], v[108:111], v[86:89]
	v_mfma_f32_16x16x32_bf16 v[90:93], v[142:145], v[108:111], v[90:93]
	v_mfma_f32_16x16x32_bf16 v[76:79], v[122:125], v[108:111], v[76:79]
	v_mfma_f32_16x16x32_bf16 v[94:97], v[130:133], v[114:117], v[82:85]
	v_mfma_f32_16x16x32_bf16 v[84:87], v[138:141], v[114:117], v[86:89]
	v_mfma_f32_16x16x32_bf16 v[88:91], v[146:149], v[114:117], v[90:93]
	s_waitcnt lgkmcnt(0)
	v_mfma_f32_16x16x32_bf16 v[76:79], v[176:179], v[114:117], v[76:79]
	s_nop 1
	v_add_u32_e32 v92, v154, v163
	v_add_u32_e32 v106, 0x100, v92
	ds_read2st64_b64 v[98:101], v106 offset0:1 offset1:26
	v_mov_b32_e32 v104, v3
	v_mov_b32_e32 v105, v3
	v_mov_b32_e32 v82, v3
	v_mov_b32_e32 v83, v3
	s_waitcnt lgkmcnt(0)
	v_mov_b32_e32 v102, v98
	v_mov_b32_e32 v103, v99
	v_mov_b32_e32 v98, v3
	v_mov_b32_e32 v99, v3
	v_mov_b32_e32 v148, v173
	v_mfma_f32_16x16x32_bf16 v[92:95], v[102:105], v[80:83], v[94:97]
	v_mov_b32_e32 v102, v3
	v_mov_b32_e32 v103, v3
	s_nop 0
	v_mov_b32_e32 v96, v100
	v_mov_b32_e32 v97, v101
	s_nop 1
	v_mfma_f32_16x16x32_bf16 v[84:87], v[96:99], v[80:83], v[84:87]
	ds_read2st64_b64 v[96:99], v106 offset0:51 offset1:76
	s_waitcnt lgkmcnt(0)
	v_mov_b32_e32 v100, v96
	v_mov_b32_e32 v101, v97
	v_mov_b32_e32 v96, v98
	v_mov_b32_e32 v97, v99
	v_mov_b32_e32 v98, v3
	v_mov_b32_e32 v99, v3
	v_mfma_f32_16x16x32_bf16 v[88:91], v[100:103], v[80:83], v[88:91]
	s_nop 0
	v_mfma_f32_16x16x32_bf16 v[76:79], v[96:99], v[80:83], v[76:79]
	v_add_f32_e32 v80, v112, v113
	v_div_scale_f32 v81, s[0:1], v80, v80, 1.0
	v_rcp_f32_e32 v82, v81
	s_or_b32 s0, s74, 64
	s_ashr_i32 s1, s0, 31
	v_fma_f32 v83, -v81, v82, 1.0
	v_fmac_f32_e32 v82, v83, v82
	v_div_scale_f32 v83, vcc, 1.0, v80, 1.0
	v_mul_f32_e32 v96, v83, v82
	v_fma_f32 v97, -v81, v96, v83
	v_fmac_f32_e32 v96, v97, v82
	v_fma_f32 v81, -v81, v96, v83
	v_div_fmas_f32 v81, v81, v82, v96
	v_div_fixup_f32 v96, v81, v80, 1.0
	v_lshlrev_b32_e32 v80, 2, v161
	v_and_b32_e32 v97, 16, v159
	v_and_b32_e32 v98, -8, v80
	v_mad_i64_i32 v[80:81], s[36:37], v160, s43, v[0:1]
	v_lshl_add_u64 v[100:101], s[0:1], 1, v[80:81]
	v_pk_mul_f32 v[82:83], v[94:95], v[96:97] op_sel_hi:[1,0]
	v_pk_mul_f32 v[80:81], v[92:93], v[96:97] op_sel_hi:[1,0]
	v_pk_mul_f32 v[84:85], v[84:85], v[96:97] op_sel_hi:[1,0]
	v_pk_mul_f32 v[86:87], v[86:87], v[96:97] op_sel_hi:[1,0]
	v_cvt_pk_bf16_f32 v80, v80, v81
	v_cvt_pk_bf16_f32 v81, v82, v83
	v_cvt_pk_bf16_f32 v82, v84, v85
	v_lshlrev_b32_e32 v84, 1, v97
	v_mov_b32_e32 v85, v3
	v_ashrrev_i32_e32 v99, 31, v98
	v_cvt_pk_bf16_f32 v83, v86, v87
	v_lshl_add_u64 v[84:85], v[100:101], 0, v[84:85]
	v_permlane16_swap_b32_e32 v80, v82
	v_permlane16_swap_b32_e32 v81, v83
	v_lshl_add_u64 v[84:85], v[98:99], 1, v[84:85]
	global_load_dword v154, v3, s[44:45] offset:8
	global_store_dwordx4 v[84:85], v[80:83], off offset:2048
	v_pk_mul_f32 v[86:87], v[96:97], v[78:79] op_sel_hi:[0,1]
	v_pk_mul_f32 v[78:79], v[96:97], v[76:77] op_sel_hi:[0,1]
	v_pk_mul_f32 v[80:81], v[90:91], v[96:97] op_sel_hi:[1,0]
	v_pk_mul_f32 v[82:83], v[88:89], v[96:97] op_sel_hi:[1,0]
	v_cvt_pk_bf16_f32 v77, v80, v81
	v_cvt_pk_bf16_f32 v76, v82, v83
	v_cvt_pk_bf16_f32 v78, v78, v79
	v_cvt_pk_bf16_f32 v79, v86, v87
	s_nop 0
	v_permlane16_swap_b32_e32 v76, v78
	v_permlane16_swap_b32_e32 v77, v79
	global_store_dwordx4 v[84:85], v[76:79], off offset:2112
	s_nop 0
	v_and_b32_e32 v151, 15, v148
	v_or_b32_e32 v155, s4, v151
	v_add_u32_e32 v76, s82, v155
	v_or_b32_e32 v77, s5, v151
	v_cndmask_b32_e64 v149, v76, v77, s[38:39]
	v_lshlrev_b32_e32 v76, 1, v148
	v_and_or_b32 v76, v76, 30, s21
	v_mul_lo_u32 v76, v76, s8
	v_and_b32_e32 v153, -16, v148
	v_add3_u32 v152, 0, v76, v153
	ds_read_b128 v[76:79], v152
	ds_read_b128 v[80:83], v152 offset:64
	ds_read_b128 v[84:87], v152 offset:208
	ds_read_b128 v[88:91], v152 offset:272
	ds_read_b128 v[92:95], v152 offset:6656
	ds_read_b128 v[96:99], v152 offset:6720
	ds_read_b128 v[100:103], v152 offset:6864
	ds_read_b128 v[104:107], v152 offset:6928
	ds_read_b128 v[108:111], v152 offset:13312
	ds_read_b128 v[112:115], v152 offset:13376
	ds_read_b128 v[116:119], v152 offset:13520
	ds_read_b128 v[120:123], v152 offset:13584
	v_ashrrev_i32_e32 v150, 4, v148
	s_waitcnt lgkmcnt(11)
	v_mfma_f32_16x16x32_bf16 v[76:79], v[76:79], v[72:75], 0
	s_waitcnt lgkmcnt(10)
	v_mfma_f32_16x16x32_bf16 v[180:183], v[80:83], v[68:71], v[76:79]
	s_waitcnt lgkmcnt(9)
	v_mfma_f32_16x16x32_bf16 v[76:79], v[84:87], v[72:75], 0
	s_waitcnt lgkmcnt(8)
	v_mfma_f32_16x16x32_bf16 v[184:187], v[88:91], v[68:71], v[76:79]
	s_waitcnt lgkmcnt(7)
	v_mfma_f32_16x16x32_bf16 v[76:79], v[92:95], v[72:75], 0
	s_waitcnt lgkmcnt(6)
	v_mfma_f32_16x16x32_bf16 v[144:147], v[96:99], v[68:71], v[76:79]
	s_waitcnt lgkmcnt(5)
	v_mfma_f32_16x16x32_bf16 v[76:79], v[100:103], v[72:75], 0
	s_waitcnt lgkmcnt(4)
	v_mfma_f32_16x16x32_bf16 v[140:143], v[104:107], v[68:71], v[76:79]
	s_waitcnt lgkmcnt(3)
	v_mfma_f32_16x16x32_bf16 v[76:79], v[108:111], v[72:75], 0
	s_waitcnt lgkmcnt(2)
	v_mfma_f32_16x16x32_bf16 v[136:139], v[112:115], v[68:71], v[76:79]
	s_waitcnt lgkmcnt(1)
	v_mfma_f32_16x16x32_bf16 v[76:79], v[116:119], v[72:75], 0
	s_waitcnt lgkmcnt(0)
	v_mfma_f32_16x16x32_bf16 v[132:135], v[120:123], v[68:71], v[76:79]
	s_nop 5
	ds_read_b128 v[76:79], v152 offset:19968
	ds_read_b128 v[80:83], v152 offset:20032
	ds_read_b128 v[84:87], v152 offset:20176
	ds_read_b128 v[88:91], v152 offset:20240
	ds_read_b128 v[92:95], v152 offset:26624
	ds_read_b128 v[96:99], v152 offset:26688
	ds_read_b128 v[100:103], v152 offset:26832
	ds_read_b128 v[104:107], v152 offset:26896
	ds_read_b128 v[108:111], v152 offset:33280
	ds_read_b128 v[112:115], v152 offset:33344
	ds_read_b128 v[160:163], v152 offset:33488
	ds_read_b128 v[176:179], v152 offset:33552
	s_waitcnt lgkmcnt(11)
	v_mfma_f32_16x16x32_bf16 v[76:79], v[76:79], v[72:75], 0
	s_waitcnt lgkmcnt(10)
	v_mfma_f32_16x16x32_bf16 v[128:131], v[80:83], v[68:71], v[76:79]
	s_waitcnt lgkmcnt(9)
	v_mfma_f32_16x16x32_bf16 v[76:79], v[84:87], v[72:75], 0
	s_waitcnt lgkmcnt(8)
	v_mfma_f32_16x16x32_bf16 v[124:127], v[88:91], v[68:71], v[76:79]
	s_waitcnt lgkmcnt(7)
	v_mfma_f32_16x16x32_bf16 v[76:79], v[92:95], v[72:75], 0
	s_waitcnt lgkmcnt(6)
	v_mfma_f32_16x16x32_bf16 v[120:123], v[96:99], v[68:71], v[76:79]
	s_waitcnt lgkmcnt(5)
	v_mfma_f32_16x16x32_bf16 v[76:79], v[100:103], v[72:75], 0
	s_waitcnt lgkmcnt(4)
	v_mfma_f32_16x16x32_bf16 v[116:119], v[104:107], v[68:71], v[76:79]
	s_waitcnt lgkmcnt(3)
	v_mfma_f32_16x16x32_bf16 v[76:79], v[108:111], v[72:75], 0
	s_waitcnt lgkmcnt(2)
	v_mfma_f32_16x16x32_bf16 v[112:115], v[112:115], v[68:71], v[76:79]
	s_waitcnt lgkmcnt(1)
	v_mfma_f32_16x16x32_bf16 v[76:79], v[160:163], v[72:75], 0
	s_waitcnt lgkmcnt(0)
	v_mfma_f32_16x16x32_bf16 v[108:111], v[176:179], v[68:71], v[76:79]
	s_nop 5
	ds_read_b128 v[76:79], v152 offset:39936
	ds_read_b128 v[80:83], v152 offset:40000
	ds_read_b128 v[84:87], v152 offset:40144
	ds_read_b128 v[88:91], v152 offset:40208
	ds_read_b128 v[92:95], v152 offset:46592
	ds_read_b128 v[96:99], v152 offset:46656
	ds_read_b128 v[160:163], v152 offset:46800
	ds_read_b128 v[176:179], v152 offset:46864
	ds_read_b128 v[188:191], v152 offset:53248
	ds_read_b128 v[192:195], v152 offset:53312
	ds_read_b128 v[196:199], v152 offset:53456
	ds_read_b128 v[200:203], v152 offset:53520
	s_waitcnt lgkmcnt(11)
	v_mfma_f32_16x16x32_bf16 v[76:79], v[76:79], v[72:75], 0
	s_waitcnt lgkmcnt(10)
	v_mfma_f32_16x16x32_bf16 v[104:107], v[80:83], v[68:71], v[76:79]
	s_waitcnt lgkmcnt(9)
	v_mfma_f32_16x16x32_bf16 v[76:79], v[84:87], v[72:75], 0
	s_waitcnt lgkmcnt(8)
	v_mfma_f32_16x16x32_bf16 v[100:103], v[88:91], v[68:71], v[76:79]
	s_waitcnt lgkmcnt(7)
	v_mfma_f32_16x16x32_bf16 v[76:79], v[92:95], v[72:75], 0
	s_waitcnt lgkmcnt(6)
	v_mfma_f32_16x16x32_bf16 v[96:99], v[96:99], v[68:71], v[76:79]
	s_waitcnt lgkmcnt(5)
	v_mfma_f32_16x16x32_bf16 v[76:79], v[160:163], v[72:75], 0
	s_waitcnt lgkmcnt(4)
	v_mfma_f32_16x16x32_bf16 v[92:95], v[176:179], v[68:71], v[76:79]
	s_waitcnt lgkmcnt(3)
	v_mfma_f32_16x16x32_bf16 v[76:79], v[188:191], v[72:75], 0
	s_waitcnt lgkmcnt(2)
	v_mfma_f32_16x16x32_bf16 v[88:91], v[192:195], v[68:71], v[76:79]
	s_waitcnt lgkmcnt(1)
	v_mfma_f32_16x16x32_bf16 v[76:79], v[196:199], v[72:75], 0
	s_waitcnt lgkmcnt(0)
	v_mfma_f32_16x16x32_bf16 v[84:87], v[200:203], v[68:71], v[76:79]
	s_nop 5
	v_mad_u32_u24 v76, v151, s8, 0
	v_add3_u32 v76, v76, v153, s46
	ds_read_b128 v[80:83], v76
	ds_read_b128 v[76:79], v76 offset:64
	v_lshlrev_b32_e32 v152, 3, v150
	v_add_u32_e32 v179, s3, v152
	v_add_u32_e32 v168, s21, v179
	v_sub_u32_e32 v159, v155, v168
	v_add_u32_e32 v160, 0x80, v159
	v_add_u32_e32 v159, 0x7f, v159
	v_cmp_gt_u32_e32 vcc, s33, v168
	v_cmp_gt_u32_e64 s[0:1], s34, v160
	v_cmp_gt_u32_e64 s[40:41], s34, v159
	s_and_b64 s[0:1], vcc, s[0:1]
	s_and_b64 s[40:41], vcc, s[40:41]
	v_cndmask_b32_e64 v161, v231, v180, s[0:1]
	v_cndmask_b32_e64 v159, v231, v184, s[40:41]
	v_max_f32_e32 v160, v159, v159
	v_max_f32_e32 v162, v161, v161
	v_max_f32_e32 v160, v162, v160
	v_or_b32_e32 v162, 2, v168
	v_sub_u32_e32 v162, v155, v162
	v_add_u32_e32 v163, 0x80, v162
	v_add_u32_e32 v162, 0x7f, v162
	v_cmp_gt_u32_e64 s[0:1], s34, v163
	v_cmp_gt_u32_e64 s[40:41], s34, v162
	s_and_b64 s[0:1], vcc, s[0:1]
	s_and_b64 s[40:41], vcc, s[40:41]
	v_cndmask_b32_e64 v177, v231, v181, s[0:1]
	v_cndmask_b32_e64 v162, v231, v185, s[40:41]
	v_max_f32_e32 v163, v162, v162
	v_max_f32_e32 v169, v177, v177
	v_max_f32_e32 v163, v169, v163
	s_waitcnt lgkmcnt(1)
	v_mfma_f32_16x16x32_bf16 v[72:75], v[80:83], v[72:75], 0
	s_waitcnt vmcnt(2)
	v_max3_f32 v169, v154, v160, v163
	v_or_b32_e32 v160, 4, v168
	v_sub_u32_e32 v160, v155, v160
	v_add_u32_e32 v163, 0x80, v160
	v_add_u32_e32 v160, 0x7f, v160
	v_cmp_gt_u32_e64 s[0:1], s34, v163
	v_cmp_gt_u32_e64 s[40:41], s34, v160
	s_and_b64 s[0:1], vcc, s[0:1]
	s_and_b64 s[40:41], vcc, s[40:41]
	v_cndmask_b32_e64 v163, v231, v182, s[0:1]
	v_cndmask_b32_e64 v160, v231, v186, s[40:41]
	v_or_b32_e32 v168, 6, v168
	v_max_f32_e32 v176, v160, v160
	v_max_f32_e32 v178, v163, v163
	v_sub_u32_e32 v168, v155, v168
	v_max_f32_e32 v180, v178, v176
	v_add_u32_e32 v176, 0x80, v168
	v_add_u32_e32 v168, 0x7f, v168
	v_cmp_gt_u32_e64 s[0:1], s34, v176
	v_cmp_gt_u32_e64 s[40:41], s34, v168
	s_and_b64 s[0:1], vcc, s[0:1]
	s_and_b64 vcc, vcc, s[40:41]
	v_cndmask_b32_e64 v178, v231, v183, s[0:1]
	v_cndmask_b32_e32 v176, v231, v187, vcc
	v_max_f32_e32 v168, v176, v176
	v_max_f32_e32 v181, v178, v178
	v_max_f32_e32 v168, v181, v168
	v_max3_f32 v180, v169, v180, v168
	v_add_u32_e32 v168, s22, v179
	v_sub_u32_e32 v169, v155, v168
	v_add_u32_e32 v181, 0x80, v169
	v_add_u32_e32 v169, 0x7f, v169
	v_cmp_gt_u32_e32 vcc, s33, v168
	v_cmp_gt_u32_e64 s[0:1], s34, v181
	v_cmp_gt_u32_e64 s[40:41], s34, v169
	s_and_b64 s[0:1], vcc, s[0:1]
	s_and_b64 s[40:41], vcc, s[40:41]
	v_cndmask_b32_e64 v144, v231, v144, s[0:1]
	v_cndmask_b32_e64 v140, v231, v140, s[40:41]
	v_max_f32_e32 v169, v140, v140
	v_max_f32_e32 v181, v144, v144
	v_max_f32_e32 v169, v181, v169
	v_or_b32_e32 v181, 2, v168
	v_sub_u32_e32 v181, v155, v181
	v_add_u32_e32 v182, 0x80, v181
	v_cmp_gt_u32_e64 s[0:1], s34, v182
	v_add_u32_e32 v181, 0x7f, v181
	s_and_b64 s[40:41], vcc, s[0:1]
	v_cmp_gt_u32_e64 s[0:1], s34, v181
	s_and_b64 s[0:1], vcc, s[0:1]
	v_cndmask_b32_e64 v145, v231, v145, s[40:41]
	v_cndmask_b32_e64 v141, v231, v141, s[0:1]
	v_max_f32_e32 v181, v141, v141
	v_max_f32_e32 v182, v145, v145
	v_max_f32_e32 v181, v182, v181
	v_max3_f32 v169, v180, v169, v181
	v_or_b32_e32 v180, 4, v168
	v_sub_u32_e32 v180, v155, v180
	v_add_u32_e32 v181, 0x80, v180
	v_add_u32_e32 v180, 0x7f, v180
	v_cmp_gt_u32_e64 s[0:1], s34, v181
	v_cmp_gt_u32_e64 s[40:41], s34, v180
	s_and_b64 s[0:1], vcc, s[0:1]
	s_and_b64 s[40:41], vcc, s[40:41]
	v_cndmask_b32_e64 v146, v231, v146, s[0:1]
	v_cndmask_b32_e64 v142, v231, v142, s[40:41]
	v_or_b32_e32 v168, 6, v168
	v_max_f32_e32 v180, v142, v142
	v_max_f32_e32 v181, v146, v146
	v_sub_u32_e32 v168, v155, v168
	v_max_f32_e32 v180, v181, v180
	v_add_u32_e32 v181, 0x80, v168
	v_add_u32_e32 v168, 0x7f, v168
	v_cmp_gt_u32_e64 s[0:1], s34, v181
	v_cmp_gt_u32_e64 s[40:41], s34, v168
	s_and_b64 s[0:1], vcc, s[0:1]
	s_and_b64 vcc, vcc, s[40:41]
	v_cndmask_b32_e64 v147, v231, v147, s[0:1]
	v_cndmask_b32_e32 v143, v231, v143, vcc
	v_max_f32_e32 v168, v143, v143
	v_max_f32_e32 v181, v147, v147
	v_max_f32_e32 v168, v181, v168
	v_max3_f32 v168, v169, v180, v168
	v_add_u32_e32 v169, s23, v179
	v_sub_u32_e32 v180, v155, v169
	v_add_u32_e32 v181, 0x80, v180
	v_add_u32_e32 v180, 0x7f, v180
	v_cmp_gt_u32_e32 vcc, s33, v169
	v_cmp_gt_u32_e64 s[0:1], s34, v181
	v_cmp_gt_u32_e64 s[40:41], s34, v180
	s_and_b64 s[0:1], vcc, s[0:1]
	s_and_b64 s[40:41], vcc, s[40:41]
	v_cndmask_b32_e64 v136, v231, v136, s[0:1]
	v_cndmask_b32_e64 v132, v231, v132, s[40:41]
	v_max_f32_e32 v180, v132, v132
	v_max_f32_e32 v181, v136, v136
	v_max_f32_e32 v180, v181, v180
	v_or_b32_e32 v181, 2, v169
	v_sub_u32_e32 v181, v155, v181
	v_add_u32_e32 v182, 0x80, v181
	v_add_u32_e32 v181, 0x7f, v181
	v_cmp_gt_u32_e64 s[0:1], s34, v182
	v_cmp_gt_u32_e64 s[40:41], s34, v181
	s_and_b64 s[0:1], vcc, s[0:1]
	s_and_b64 s[40:41], vcc, s[40:41]
	v_cndmask_b32_e64 v137, v231, v137, s[0:1]
	v_cndmask_b32_e64 v133, v231, v133, s[40:41]
	v_max_f32_e32 v181, v133, v133
	v_max_f32_e32 v182, v137, v137
	v_max_f32_e32 v181, v182, v181
	v_max3_f32 v168, v168, v180, v181
	v_or_b32_e32 v180, 4, v169
	v_sub_u32_e32 v180, v155, v180
	v_add_u32_e32 v181, 0x80, v180
	v_add_u32_e32 v180, 0x7f, v180
	v_cmp_gt_u32_e64 s[0:1], s34, v181
	v_cmp_gt_u32_e64 s[40:41], s34, v180
	s_and_b64 s[0:1], vcc, s[0:1]
	s_and_b64 s[40:41], vcc, s[40:41]
	v_cndmask_b32_e64 v138, v231, v138, s[0:1]
	v_cndmask_b32_e64 v134, v231, v134, s[40:41]
	v_or_b32_e32 v169, 6, v169
	v_max_f32_e32 v180, v134, v134
	v_max_f32_e32 v181, v138, v138
	v_sub_u32_e32 v169, v155, v169
	v_max_f32_e32 v180, v181, v180
	v_add_u32_e32 v181, 0x80, v169
	v_add_u32_e32 v169, 0x7f, v169
	v_cmp_gt_u32_e64 s[0:1], s34, v181
	v_cmp_gt_u32_e64 s[40:41], s34, v169
	s_and_b64 s[0:1], vcc, s[0:1]
	s_and_b64 vcc, vcc, s[40:41]
	v_cndmask_b32_e64 v139, v231, v139, s[0:1]
	v_cndmask_b32_e32 v135, v231, v135, vcc
	v_max_f32_e32 v169, v135, v135
	v_max_f32_e32 v181, v139, v139
	v_max_f32_e32 v169, v181, v169
	v_max3_f32 v168, v168, v180, v169
	v_add_u32_e32 v169, s26, v179
	v_sub_u32_e32 v180, v155, v169
	v_add_u32_e32 v181, 0x80, v180
	v_add_u32_e32 v180, 0x7f, v180
	v_cmp_gt_u32_e32 vcc, s33, v169
	v_cmp_gt_u32_e64 s[0:1], s34, v181
	v_cmp_gt_u32_e64 s[40:41], s34, v180
	s_and_b64 s[0:1], vcc, s[0:1]
	s_and_b64 s[40:41], vcc, s[40:41]
	v_cndmask_b32_e64 v128, v231, v128, s[0:1]
	v_cndmask_b32_e64 v124, v231, v124, s[40:41]
	v_max_f32_e32 v180, v124, v124
	v_max_f32_e32 v181, v128, v128
	v_max_f32_e32 v180, v181, v180
	v_or_b32_e32 v181, 2, v169
	v_sub_u32_e32 v181, v155, v181
	v_add_u32_e32 v182, 0x80, v181
	v_add_u32_e32 v181, 0x7f, v181
	v_cmp_gt_u32_e64 s[0:1], s34, v182
	v_cmp_gt_u32_e64 s[40:41], s34, v181
	s_and_b64 s[0:1], vcc, s[0:1]
	s_and_b64 s[40:41], vcc, s[40:41]
	v_cndmask_b32_e64 v129, v231, v129, s[0:1]
	v_cndmask_b32_e64 v125, v231, v125, s[40:41]
	v_max_f32_e32 v181, v125, v125
	v_max_f32_e32 v182, v129, v129
	v_max_f32_e32 v181, v182, v181
	v_max3_f32 v168, v168, v180, v181
	v_or_b32_e32 v180, 4, v169
	v_sub_u32_e32 v180, v155, v180
	v_add_u32_e32 v181, 0x80, v180
	v_add_u32_e32 v180, 0x7f, v180
	v_cmp_gt_u32_e64 s[0:1], s34, v181
	v_cmp_gt_u32_e64 s[40:41], s34, v180
	s_and_b64 s[0:1], vcc, s[0:1]
	s_and_b64 s[40:41], vcc, s[40:41]
	v_cndmask_b32_e64 v130, v231, v130, s[0:1]
	v_cndmask_b32_e64 v126, v231, v126, s[40:41]
	v_or_b32_e32 v169, 6, v169
	v_max_f32_e32 v180, v126, v126
	v_max_f32_e32 v181, v130, v130
	v_sub_u32_e32 v169, v155, v169
	v_max_f32_e32 v180, v181, v180
	v_add_u32_e32 v181, 0x80, v169
	v_add_u32_e32 v169, 0x7f, v169
	v_cmp_gt_u32_e64 s[0:1], s34, v181
	v_cmp_gt_u32_e64 s[40:41], s34, v169
	s_and_b64 s[0:1], vcc, s[0:1]
	s_and_b64 vcc, vcc, s[40:41]
	v_cndmask_b32_e64 v131, v231, v131, s[0:1]
	v_cndmask_b32_e32 v127, v231, v127, vcc
	v_max_f32_e32 v169, v127, v127
	v_max_f32_e32 v181, v131, v131
	v_max_f32_e32 v169, v181, v169
	v_max3_f32 v168, v168, v180, v169
	v_add_u32_e32 v169, s27, v179
	v_sub_u32_e32 v180, v155, v169
	v_add_u32_e32 v181, 0x80, v180
	v_add_u32_e32 v180, 0x7f, v180
	v_cmp_gt_u32_e32 vcc, s33, v169
	v_cmp_gt_u32_e64 s[0:1], s34, v181
	v_cmp_gt_u32_e64 s[40:41], s34, v180
	s_and_b64 s[0:1], vcc, s[0:1]
	s_and_b64 s[40:41], vcc, s[40:41]
	v_cndmask_b32_e64 v120, v231, v120, s[0:1]
	v_cndmask_b32_e64 v116, v231, v116, s[40:41]
	v_max_f32_e32 v180, v116, v116
	v_max_f32_e32 v181, v120, v120
	v_max_f32_e32 v180, v181, v180
	v_or_b32_e32 v181, 2, v169
	v_sub_u32_e32 v181, v155, v181
	v_add_u32_e32 v182, 0x80, v181
	v_add_u32_e32 v181, 0x7f, v181
	v_cmp_gt_u32_e64 s[0:1], s34, v182
	v_cmp_gt_u32_e64 s[40:41], s34, v181
	s_and_b64 s[0:1], vcc, s[0:1]
	s_and_b64 s[40:41], vcc, s[40:41]
	v_cndmask_b32_e64 v121, v231, v121, s[0:1]
	v_cndmask_b32_e64 v117, v231, v117, s[40:41]
	v_max_f32_e32 v181, v117, v117
	v_max_f32_e32 v182, v121, v121
	v_max_f32_e32 v181, v182, v181
	v_max3_f32 v168, v168, v180, v181
	v_or_b32_e32 v180, 4, v169
	v_sub_u32_e32 v180, v155, v180
	v_add_u32_e32 v181, 0x80, v180
	v_add_u32_e32 v180, 0x7f, v180
	v_cmp_gt_u32_e64 s[0:1], s34, v181
	v_cmp_gt_u32_e64 s[40:41], s34, v180
	s_and_b64 s[0:1], vcc, s[0:1]
	s_and_b64 s[40:41], vcc, s[40:41]
	v_cndmask_b32_e64 v122, v231, v122, s[0:1]
	v_cndmask_b32_e64 v118, v231, v118, s[40:41]
	v_or_b32_e32 v169, 6, v169
	v_max_f32_e32 v180, v118, v118
	v_max_f32_e32 v181, v122, v122
	v_sub_u32_e32 v169, v155, v169
	v_max_f32_e32 v181, v181, v180
	v_add_u32_e32 v180, 0x80, v169
	v_add_u32_e32 v169, 0x7f, v169
	v_cmp_gt_u32_e64 s[0:1], s34, v180
	v_cmp_gt_u32_e64 s[40:41], s34, v169
	s_and_b64 s[0:1], vcc, s[0:1]
	s_and_b64 vcc, vcc, s[40:41]
	v_cndmask_b32_e64 v123, v231, v123, s[0:1]
	v_cndmask_b32_e32 v180, v231, v119, vcc
	v_max_f32_e32 v119, v180, v180
	v_max_f32_e32 v169, v123, v123
	v_max_f32_e32 v119, v169, v119
	v_add_u32_e32 v169, s30, v179
	v_max3_f32 v168, v168, v181, v119
	v_sub_u32_e32 v119, v155, v169
	v_add_u32_e32 v181, 0x80, v119
	v_add_u32_e32 v119, 0x7f, v119
	v_cmp_gt_u32_e32 vcc, s33, v169
	v_cmp_gt_u32_e64 s[0:1], s34, v181
	v_cmp_gt_u32_e64 s[40:41], s34, v119
	s_and_b64 s[0:1], vcc, s[0:1]
	s_and_b64 s[40:41], vcc, s[40:41]
	v_cndmask_b32_e64 v112, v231, v112, s[0:1]
	v_cndmask_b32_e64 v108, v231, v108, s[40:41]
	v_max_f32_e32 v119, v108, v108
	v_max_f32_e32 v181, v112, v112
	v_max_f32_e32 v181, v181, v119
	v_or_b32_e32 v119, 2, v169
	v_sub_u32_e32 v119, v155, v119
	v_add_u32_e32 v182, 0x80, v119
	v_add_u32_e32 v119, 0x7f, v119
	v_cmp_gt_u32_e64 s[0:1], s34, v182
	v_cmp_gt_u32_e64 s[40:41], s34, v119
	s_and_b64 s[0:1], vcc, s[0:1]
	s_and_b64 s[40:41], vcc, s[40:41]
	v_cndmask_b32_e64 v113, v231, v113, s[0:1]
	v_cndmask_b32_e64 v119, v231, v109, s[40:41]
	v_max_f32_e32 v109, v119, v119
	v_max_f32_e32 v182, v113, v113
	v_max_f32_e32 v109, v182, v109
	v_max3_f32 v109, v168, v181, v109
	v_or_b32_e32 v168, 4, v169
	v_sub_u32_e32 v168, v155, v168
	v_add_u32_e32 v181, 0x80, v168
	v_add_u32_e32 v168, 0x7f, v168
	v_cmp_gt_u32_e64 s[0:1], s34, v181
	v_cmp_gt_u32_e64 s[40:41], s34, v168
	s_and_b64 s[0:1], vcc, s[0:1]
	s_and_b64 s[40:41], vcc, s[40:41]
	v_cndmask_b32_e64 v114, v231, v114, s[0:1]
	v_cndmask_b32_e64 v110, v231, v110, s[40:41]
	v_or_b32_e32 v169, 6, v169
	v_max_f32_e32 v168, v110, v110
	v_max_f32_e32 v181, v114, v114
	v_sub_u32_e32 v169, v155, v169
	v_max_f32_e32 v168, v181, v168
	v_add_u32_e32 v181, 0x80, v169
	v_add_u32_e32 v169, 0x7f, v169
	v_cmp_gt_u32_e64 s[0:1], s34, v181
	v_cmp_gt_u32_e64 s[40:41], s34, v169
	s_and_b64 s[0:1], vcc, s[0:1]
	s_and_b64 vcc, vcc, s[40:41]
	v_cndmask_b32_e64 v181, v231, v115, s[0:1]
	v_cndmask_b32_e32 v182, v231, v111, vcc
	v_max_f32_e32 v111, v182, v182
	v_max_f32_e32 v115, v181, v181
	v_max_f32_e32 v111, v115, v111
	v_max3_f32 v115, v109, v168, v111
	v_add_u32_e32 v168, s31, v179
	v_sub_u32_e32 v109, v155, v168
	v_add_u32_e32 v111, 0x80, v109
	v_add_u32_e32 v109, 0x7f, v109
	v_cmp_gt_u32_e32 vcc, s33, v168
	v_cmp_gt_u32_e64 s[0:1], s34, v111
	v_cmp_gt_u32_e64 s[40:41], s34, v109
	s_and_b64 s[0:1], vcc, s[0:1]
	s_and_b64 s[40:41], vcc, s[40:41]
	v_cndmask_b32_e64 v109, v231, v104, s[0:1]
	v_cndmask_b32_e64 v100, v231, v100, s[40:41]
	v_max_f32_e32 v104, v100, v100
	v_max_f32_e32 v111, v109, v109
	v_max_f32_e32 v104, v111, v104
	v_or_b32_e32 v111, 2, v168
	v_sub_u32_e32 v111, v155, v111
	v_add_u32_e32 v169, 0x80, v111
	v_add_u32_e32 v111, 0x7f, v111
	v_cmp_gt_u32_e64 s[0:1], s34, v169
	v_cmp_gt_u32_e64 s[40:41], s34, v111
	s_and_b64 s[0:1], vcc, s[0:1]
	s_and_b64 s[40:41], vcc, s[40:41]
	v_cndmask_b32_e64 v105, v231, v105, s[0:1]
	v_cndmask_b32_e64 v111, v231, v101, s[40:41]
	v_max_f32_e32 v101, v111, v111
	v_max_f32_e32 v169, v105, v105
	v_max_f32_e32 v101, v169, v101
	v_max3_f32 v101, v115, v104, v101
	v_or_b32_e32 v104, 4, v168
	v_sub_u32_e32 v104, v155, v104
	v_add_u32_e32 v115, 0x80, v104
	v_add_u32_e32 v104, 0x7f, v104
	v_cmp_gt_u32_e64 s[0:1], s34, v115
	v_cmp_gt_u32_e64 s[40:41], s34, v104
	s_and_b64 s[0:1], vcc, s[0:1]
	s_and_b64 s[40:41], vcc, s[40:41]
	v_cndmask_b32_e64 v106, v231, v106, s[0:1]
	v_cndmask_b32_e64 v115, v231, v102, s[40:41]
	v_max_f32_e32 v102, v115, v115
	v_max_f32_e32 v104, v106, v106
	v_max_f32_e32 v102, v104, v102
	v_or_b32_e32 v104, 6, v168
	v_sub_u32_e32 v104, v155, v104
	v_add_u32_e32 v168, 0x80, v104
	v_add_u32_e32 v104, 0x7f, v104
	v_cmp_gt_u32_e64 s[0:1], s34, v168
	v_cmp_gt_u32_e64 s[40:41], s34, v104
	s_and_b64 s[0:1], vcc, s[0:1]
	s_and_b64 vcc, vcc, s[40:41]
	v_cndmask_b32_e64 v186, v231, v107, s[0:1]
	v_cndmask_b32_e32 v187, v231, v103, vcc
	v_max_f32_e32 v103, v187, v187
	v_max_f32_e32 v104, v186, v186
	v_max_f32_e32 v103, v104, v103
	v_add_u32_e32 v107, s76, v179
	v_max3_f32 v104, v101, v102, v103
	v_sub_u32_e32 v101, v155, v107
	v_add_u32_e32 v102, 0x80, v101
	v_add_u32_e32 v101, 0x7f, v101
	v_cmp_gt_u32_e32 vcc, s33, v107
	v_cmp_gt_u32_e64 s[0:1], s34, v102
	v_cmp_gt_u32_e64 s[40:41], s34, v101
	s_and_b64 s[0:1], vcc, s[0:1]
	s_and_b64 s[40:41], vcc, s[40:41]
	v_cndmask_b32_e64 v101, v231, v96, s[0:1]
	v_cndmask_b32_e64 v102, v231, v92, s[40:41]
	v_max_f32_e32 v92, v102, v102
	v_max_f32_e32 v96, v101, v101
	v_max_f32_e32 v92, v96, v92
	v_or_b32_e32 v96, 2, v107
	v_sub_u32_e32 v96, v155, v96
	v_add_u32_e32 v103, 0x80, v96
	v_add_u32_e32 v96, 0x7f, v96
	v_cmp_gt_u32_e64 s[0:1], s34, v103
	v_cmp_gt_u32_e64 s[40:41], s34, v96
	s_and_b64 s[0:1], vcc, s[0:1]
	s_and_b64 s[40:41], vcc, s[40:41]
	v_cndmask_b32_e64 v103, v231, v97, s[0:1]
	v_cndmask_b32_e64 v183, v231, v93, s[40:41]
	v_max_f32_e32 v93, v183, v183
	v_max_f32_e32 v96, v103, v103
	v_max_f32_e32 v93, v96, v93
	v_max3_f32 v92, v104, v92, v93
	v_or_b32_e32 v93, 4, v107
	v_sub_u32_e32 v93, v155, v93
	v_add_u32_e32 v96, 0x80, v93
	v_add_u32_e32 v93, 0x7f, v93
	v_cmp_gt_u32_e64 s[0:1], s34, v96
	v_cmp_gt_u32_e64 s[40:41], s34, v93
	s_and_b64 s[0:1], vcc, s[0:1]
	s_and_b64 s[40:41], vcc, s[40:41]
	v_cndmask_b32_e64 v184, v231, v98, s[0:1]
	v_cndmask_b32_e64 v185, v231, v94, s[40:41]
	v_max_f32_e32 v93, v185, v185
	v_max_f32_e32 v94, v184, v184
	v_max_f32_e32 v93, v94, v93
	v_or_b32_e32 v94, 6, v107
	v_sub_u32_e32 v94, v155, v94
	v_add_u32_e32 v96, 0x80, v94
	v_add_u32_e32 v94, 0x7f, v94
	v_cmp_gt_u32_e64 s[0:1], s34, v96
	v_cmp_gt_u32_e64 s[40:41], s34, v94
	s_and_b64 s[0:1], vcc, s[0:1]
	s_and_b64 vcc, vcc, s[40:41]
	v_cndmask_b32_e64 v192, v231, v99, s[0:1]
	v_cndmask_b32_e32 v193, v231, v95, vcc
	v_max_f32_e32 v94, v193, v193
	v_max_f32_e32 v95, v192, v192
	v_max_f32_e32 v94, v95, v94
	v_max3_f32 v92, v92, v93, v94
	v_add_u32_e32 v93, s77, v179
	v_sub_u32_e32 v94, v155, v93
	v_add_u32_e32 v95, 0x80, v94
	v_add_u32_e32 v94, 0x7f, v94
	v_cmp_gt_u32_e32 vcc, s33, v93
	v_cmp_gt_u32_e64 s[0:1], s34, v95
	v_cmp_gt_u32_e64 s[40:41], s34, v94
	s_and_b64 s[0:1], vcc, s[0:1]
	s_and_b64 s[40:41], vcc, s[40:41]
	v_cndmask_b32_e64 v107, v231, v88, s[0:1]
	v_cndmask_b32_e64 v179, v231, v84, s[40:41]
	v_max_f32_e32 v84, v179, v179
	v_max_f32_e32 v88, v107, v107
	v_max_f32_e32 v84, v88, v84
	v_or_b32_e32 v88, 2, v93
	v_sub_u32_e32 v88, v155, v88
	v_add_u32_e32 v94, 0x80, v88
	v_add_u32_e32 v88, 0x7f, v88
	v_cmp_gt_u32_e64 s[0:1], s34, v94
	v_cmp_gt_u32_e64 s[40:41], s34, v88
	s_and_b64 s[0:1], vcc, s[0:1]
	s_and_b64 s[40:41], vcc, s[40:41]
	v_cndmask_b32_e64 v188, v231, v89, s[0:1]
	v_cndmask_b32_e64 v189, v231, v85, s[40:41]
	v_max_f32_e32 v85, v189, v189
	v_max_f32_e32 v88, v188, v188
	v_max_f32_e32 v85, v88, v85
	v_max3_f32 v84, v92, v84, v85
	v_or_b32_e32 v85, 4, v93
	v_sub_u32_e32 v85, v155, v85
	v_add_u32_e32 v88, 0x80, v85
	v_add_u32_e32 v85, 0x7f, v85
	v_cmp_gt_u32_e64 s[0:1], s34, v88
	v_cmp_gt_u32_e64 s[40:41], s34, v85
	s_and_b64 s[0:1], vcc, s[0:1]
	s_and_b64 s[40:41], vcc, s[40:41]
	v_cndmask_b32_e64 v190, v231, v90, s[0:1]
	v_cndmask_b32_e64 v191, v231, v86, s[40:41]
	v_max_f32_e32 v85, v191, v191
	v_max_f32_e32 v86, v190, v190
	v_max_f32_e32 v85, v86, v85
	v_or_b32_e32 v86, 6, v93
	v_sub_u32_e32 v86, v155, v86
	v_add_u32_e32 v88, 0x80, v86
	v_add_u32_e32 v86, 0x7f, v86
	v_cmp_gt_u32_e64 s[0:1], s34, v88
	v_cmp_gt_u32_e64 s[40:41], s34, v86
	s_and_b64 s[0:1], vcc, s[0:1]
	s_and_b64 vcc, vcc, s[40:41]
	v_cndmask_b32_e64 v155, v231, v91, s[0:1]
	v_cndmask_b32_e32 v194, v231, v87, vcc
	s_waitcnt lgkmcnt(0)
	v_mfma_f32_16x16x32_bf16 v[72:75], v[76:79], v[68:71], v[72:75]
	v_max_f32_e32 v86, v194, v194
	v_max_f32_e32 v87, v155, v155
	v_max_f32_e32 v86, v87, v86
	v_max3_f32 v84, v84, v85, v86
	v_mov_b32_e32 v77, v3
	s_nop 2
	v_max3_f32 v68, v84, v72, v73
	v_max3_f32 v68, v68, v74, v75
	ds_bpermute_b32 v69, v157, v68
	s_waitcnt lgkmcnt(0)
	v_max_f32_e32 v69, v69, v69
	v_max_f32_e32 v68, v68, v69
	ds_bpermute_b32 v69, v156, v68
	s_waitcnt lgkmcnt(0)
	v_max_f32_e32 v69, v69, v69
	v_max_f32_e32 v104, v68, v69
	v_sub_f32_e32 v68, v161, v104
	v_mul_f32_e32 v68, 0x3fb8aa3b, v68
	v_exp_f32_e32 v84, v68
	v_sub_f32_e32 v68, v159, v104
	v_mul_f32_e32 v68, 0x3fb8aa3b, v68
	v_exp_f32_e32 v85, v68
	v_sub_f32_e32 v68, v177, v104
	v_mul_f32_e32 v68, 0x3fb8aa3b, v68
	v_exp_f32_e32 v70, v68
	v_sub_f32_e32 v68, v162, v104
	v_mul_f32_e32 v68, 0x3fb8aa3b, v68
	v_exp_f32_e32 v76, v68
	v_add_f32_e32 v71, v84, v85
	v_sub_f32_e32 v72, v72, v104
	v_mul_f32_e32 v72, 0x3fb8aa3b, v72
	v_pk_add_f32 v[68:69], v[70:71], v[76:77]
	v_sub_f32_e32 v73, v73, v104
	v_pk_add_f32 v[78:79], v[68:69], v[68:69] op_sel_hi:[0,1]
	v_sub_f32_e32 v68, v163, v104
	v_mul_f32_e32 v68, 0x3fb8aa3b, v68
	v_exp_f32_e32 v71, v68
	v_sub_f32_e32 v68, v160, v104
	v_mul_f32_e32 v68, 0x3fb8aa3b, v68
	v_exp_f32_e32 v77, v68
	v_sub_f32_e32 v68, v178, v104
	v_mul_f32_e32 v68, 0x3fb8aa3b, v68
	v_exp_f32_e32 v80, v68
	v_sub_f32_e32 v68, v176, v104
	v_mul_f32_e32 v68, 0x3fb8aa3b, v68
	v_exp_f32_e32 v78, v68
	v_add_f32_e32 v81, v71, v77
	v_exp_f32_e32 v72, v72
	v_mul_f32_e32 v73, 0x3fb8aa3b, v73
	v_pk_add_f32 v[68:69], v[80:81], v[78:79]
	v_sub_f32_e32 v74, v74, v104
	v_pk_add_f32 v[82:83], v[68:69], v[68:69] op_sel_hi:[0,1]
	v_cvt_pk_bf16_f32 v69, v70, v76
	v_sub_f32_e32 v76, v144, v104
	v_mul_f32_e32 v76, 0x3fb8aa3b, v76
	v_exp_f32_e32 v88, v76
	v_sub_f32_e32 v76, v140, v104
	v_mul_f32_e32 v76, 0x3fb8aa3b, v76
	v_exp_f32_e32 v89, v76
	v_sub_f32_e32 v76, v145, v104
	v_mul_f32_e32 v76, 0x3fb8aa3b, v76
	v_cvt_pk_bf16_f32 v70, v71, v77
	v_cvt_pk_bf16_f32 v71, v80, v78
	v_exp_f32_e32 v78, v76
	v_sub_f32_e32 v76, v141, v104
	v_mul_f32_e32 v76, 0x3fb8aa3b, v76
	v_exp_f32_e32 v82, v76
	v_add_f32_e32 v79, v88, v89
	v_cvt_pk_bf16_f32 v68, v84, v85
	v_exp_f32_e32 v73, v73
	v_pk_add_f32 v[76:77], v[78:79], v[82:83]
	v_mul_f32_e32 v74, 0x3fb8aa3b, v74
	v_pk_add_f32 v[80:81], v[76:77], v[76:77] op_sel_hi:[0,1]
	v_sub_f32_e32 v76, v146, v104
	v_mul_f32_e32 v76, 0x3fb8aa3b, v76
	v_exp_f32_e32 v79, v76
	v_sub_f32_e32 v76, v142, v104
	v_mul_f32_e32 v76, 0x3fb8aa3b, v76
	v_exp_f32_e32 v83, v76
	v_sub_f32_e32 v76, v147, v104
	v_mul_f32_e32 v76, 0x3fb8aa3b, v76
	v_exp_f32_e32 v84, v76
	v_sub_f32_e32 v76, v143, v104
	v_mul_f32_e32 v76, 0x3fb8aa3b, v76
	v_exp_f32_e32 v80, v76
	v_add_f32_e32 v85, v79, v83
	v_sub_f32_e32 v75, v75, v104
	v_exp_f32_e32 v74, v74
	v_pk_add_f32 v[76:77], v[84:85], v[80:81]
	v_mul_f32_e32 v75, 0x3fb8aa3b, v75
	v_pk_add_f32 v[86:87], v[76:77], v[76:77] op_sel_hi:[0,1]
	v_cvt_pk_bf16_f32 v77, v78, v82
	v_cvt_pk_bf16_f32 v78, v79, v83
	v_cvt_pk_bf16_f32 v79, v84, v80
	v_sub_f32_e32 v80, v136, v104
	v_mul_f32_e32 v80, 0x3fb8aa3b, v80
	v_exp_f32_e32 v92, v80
	v_sub_f32_e32 v80, v132, v104
	v_mul_f32_e32 v80, 0x3fb8aa3b, v80
	v_exp_f32_e32 v93, v80
	v_sub_f32_e32 v80, v137, v104
	v_mul_f32_e32 v80, 0x3fb8aa3b, v80
	v_exp_f32_e32 v82, v80
	v_sub_f32_e32 v80, v133, v104
	v_mul_f32_e32 v80, 0x3fb8aa3b, v80
	v_exp_f32_e32 v86, v80
	v_add_f32_e32 v83, v92, v93
	v_cvt_pk_bf16_f32 v76, v88, v89
	v_exp_f32_e32 v75, v75
	v_pk_add_f32 v[80:81], v[82:83], v[86:87]
	s_nop 0
	v_pk_add_f32 v[84:85], v[80:81], v[80:81] op_sel_hi:[0,1]
	v_sub_f32_e32 v80, v138, v104
	v_mul_f32_e32 v80, 0x3fb8aa3b, v80
	v_exp_f32_e32 v83, v80
	v_sub_f32_e32 v80, v134, v104
	v_mul_f32_e32 v80, 0x3fb8aa3b, v80
	v_exp_f32_e32 v87, v80
	v_sub_f32_e32 v80, v139, v104
	v_mul_f32_e32 v80, 0x3fb8aa3b, v80
	v_exp_f32_e32 v88, v80
	v_sub_f32_e32 v80, v135, v104
	v_mul_f32_e32 v80, 0x3fb8aa3b, v80
	v_exp_f32_e32 v84, v80
	v_add_f32_e32 v89, v83, v87
	v_pk_add_f32 v[80:81], v[88:89], v[84:85]
	s_nop 0
	v_pk_add_f32 v[90:91], v[80:81], v[80:81] op_sel_hi:[0,1]
	v_cvt_pk_bf16_f32 v81, v82, v86
	v_cvt_pk_bf16_f32 v82, v83, v87
	v_cvt_pk_bf16_f32 v83, v88, v84
	v_sub_f32_e32 v84, v128, v104
	v_mul_f32_e32 v84, 0x3fb8aa3b, v84
	v_exp_f32_e32 v96, v84
	v_sub_f32_e32 v84, v124, v104
	v_mul_f32_e32 v84, 0x3fb8aa3b, v84
	v_exp_f32_e32 v97, v84
	v_sub_f32_e32 v84, v129, v104
	v_mul_f32_e32 v84, 0x3fb8aa3b, v84
	v_exp_f32_e32 v86, v84
	v_sub_f32_e32 v84, v125, v104
	v_mul_f32_e32 v84, 0x3fb8aa3b, v84
	v_exp_f32_e32 v90, v84
	v_add_f32_e32 v87, v96, v97
	v_cvt_pk_bf16_f32 v80, v92, v93
	v_pk_add_f32 v[84:85], v[86:87], v[90:91]
	s_nop 0
	v_pk_add_f32 v[88:89], v[84:85], v[84:85] op_sel_hi:[0,1]
	v_sub_f32_e32 v84, v130, v104
	v_mul_f32_e32 v84, 0x3fb8aa3b, v84
	v_exp_f32_e32 v87, v84
	v_sub_f32_e32 v84, v126, v104
	v_mul_f32_e32 v84, 0x3fb8aa3b, v84
	v_exp_f32_e32 v91, v84
	v_sub_f32_e32 v84, v131, v104
	v_mul_f32_e32 v84, 0x3fb8aa3b, v84
	v_exp_f32_e32 v92, v84
	v_sub_f32_e32 v84, v127, v104
	v_mul_f32_e32 v84, 0x3fb8aa3b, v84
	v_exp_f32_e32 v88, v84
	v_add_f32_e32 v93, v87, v91
	v_pk_add_f32 v[84:85], v[92:93], v[88:89]
	s_nop 0
	v_pk_add_f32 v[94:95], v[84:85], v[84:85] op_sel_hi:[0,1]
	v_cvt_pk_bf16_f32 v85, v86, v90
	v_cvt_pk_bf16_f32 v86, v87, v91
	v_cvt_pk_bf16_f32 v87, v92, v88
	v_sub_f32_e32 v88, v120, v104
	v_mul_f32_e32 v88, 0x3fb8aa3b, v88
	v_exp_f32_e32 v120, v88
	v_sub_f32_e32 v88, v116, v104
	v_mul_f32_e32 v88, 0x3fb8aa3b, v88
	v_exp_f32_e32 v116, v88
	v_sub_f32_e32 v88, v121, v104
	v_mul_f32_e32 v88, 0x3fb8aa3b, v88
	v_exp_f32_e32 v90, v88
	v_sub_f32_e32 v88, v117, v104
	v_mul_f32_e32 v88, 0x3fb8aa3b, v88
	v_exp_f32_e32 v94, v88
	v_add_f32_e32 v91, v120, v116
	v_cvt_pk_bf16_f32 v84, v96, v97
	v_pk_add_f32 v[88:89], v[90:91], v[94:95]
	s_nop 0
	v_pk_add_f32 v[92:93], v[88:89], v[88:89] op_sel_hi:[0,1]
	v_sub_f32_e32 v88, v122, v104
	v_mul_f32_e32 v88, 0x3fb8aa3b, v88
	v_exp_f32_e32 v91, v88
	v_sub_f32_e32 v88, v118, v104
	v_mul_f32_e32 v88, 0x3fb8aa3b, v88
	v_exp_f32_e32 v95, v88
	v_sub_f32_e32 v88, v123, v104
	v_mul_f32_e32 v88, 0x3fb8aa3b, v88
	v_exp_f32_e32 v96, v88
	v_sub_f32_e32 v88, v180, v104
	v_mul_f32_e32 v88, 0x3fb8aa3b, v88
	v_exp_f32_e32 v92, v88
	v_add_f32_e32 v97, v91, v95
	v_pk_add_f32 v[88:89], v[96:97], v[92:93]
	s_nop 0
	v_pk_add_f32 v[98:99], v[88:89], v[88:89] op_sel_hi:[0,1]
	v_cvt_pk_bf16_f32 v89, v90, v94
	v_cvt_pk_bf16_f32 v90, v91, v95
	v_cvt_pk_bf16_f32 v91, v96, v92
	v_sub_f32_e32 v92, v112, v104
	v_mul_f32_e32 v92, 0x3fb8aa3b, v92
	v_exp_f32_e32 v118, v92
	v_sub_f32_e32 v92, v108, v104
	v_mul_f32_e32 v92, 0x3fb8aa3b, v92
	v_exp_f32_e32 v108, v92
	v_sub_f32_e32 v92, v113, v104
	v_mul_f32_e32 v92, 0x3fb8aa3b, v92
	v_exp_f32_e32 v94, v92
	v_sub_f32_e32 v92, v119, v104
	v_mul_f32_e32 v92, 0x3fb8aa3b, v92
	v_exp_f32_e32 v98, v92
	v_add_f32_e32 v95, v118, v108
	v_cvt_pk_bf16_f32 v88, v120, v116
	v_pk_add_f32 v[92:93], v[94:95], v[98:99]
	s_nop 0
	v_pk_add_f32 v[96:97], v[92:93], v[92:93] op_sel_hi:[0,1]
	v_sub_f32_e32 v92, v114, v104
	v_mul_f32_e32 v92, 0x3fb8aa3b, v92
	v_exp_f32_e32 v95, v92
	v_sub_f32_e32 v92, v110, v104
	v_mul_f32_e32 v92, 0x3fb8aa3b, v92
	v_exp_f32_e32 v99, v92
	v_sub_f32_e32 v92, v181, v104
	v_mul_f32_e32 v92, 0x3fb8aa3b, v92
	v_exp_f32_e32 v112, v92
	v_sub_f32_e32 v92, v182, v104
	v_mul_f32_e32 v92, 0x3fb8aa3b, v92
	v_exp_f32_e32 v96, v92
	v_add_f32_e32 v113, v95, v99
	v_pk_add_f32 v[92:93], v[112:113], v[96:97]
	s_nop 0
	v_pk_add_f32 v[116:117], v[92:93], v[92:93] op_sel_hi:[0,1]
	v_cvt_pk_bf16_f32 v93, v94, v98
	v_cvt_pk_bf16_f32 v94, v95, v99
	v_cvt_pk_bf16_f32 v95, v112, v96
	v_sub_f32_e32 v96, v109, v104
	v_mul_f32_e32 v96, 0x3fb8aa3b, v96
	v_exp_f32_e32 v114, v96
	v_sub_f32_e32 v96, v100, v104
	v_mul_f32_e32 v96, 0x3fb8aa3b, v96
	v_exp_f32_e32 v100, v96
	v_sub_f32_e32 v96, v105, v104
	v_mul_f32_e32 v96, 0x3fb8aa3b, v96
	v_exp_f32_e32 v98, v96
	v_sub_f32_e32 v96, v111, v104
	v_mul_f32_e32 v96, 0x3fb8aa3b, v96
	v_exp_f32_e32 v116, v96
	v_add_f32_e32 v99, v114, v100
	v_cvt_pk_bf16_f32 v92, v118, v108
	v_pk_add_f32 v[96:97], v[98:99], v[116:117]
	s_nop 0
	v_pk_add_f32 v[108:109], v[96:97], v[96:97] op_sel_hi:[0,1]
	v_sub_f32_e32 v96, v106, v104
	v_mul_f32_e32 v96, 0x3fb8aa3b, v96
	v_exp_f32_e32 v99, v96
	v_sub_f32_e32 v96, v115, v104
	v_mul_f32_e32 v96, 0x3fb8aa3b, v96
	v_exp_f32_e32 v105, v96
	v_sub_f32_e32 v96, v186, v104
	v_mul_f32_e32 v96, 0x3fb8aa3b, v96
	v_exp_f32_e32 v110, v96
	v_sub_f32_e32 v96, v187, v104
	v_mul_f32_e32 v96, 0x3fb8aa3b, v96
	v_exp_f32_e32 v108, v96
	v_add_f32_e32 v111, v99, v105
	v_pk_add_f32 v[96:97], v[110:111], v[108:109]
	s_nop 0
	v_pk_add_f32 v[112:113], v[96:97], v[96:97] op_sel_hi:[0,1]
	v_cvt_pk_bf16_f32 v96, v114, v100
	v_sub_f32_e32 v100, v101, v104
	v_mul_f32_e32 v100, 0x3fb8aa3b, v100
	v_cvt_pk_bf16_f32 v97, v98, v116
	v_cvt_pk_bf16_f32 v98, v99, v105
	v_exp_f32_e32 v105, v100
	v_sub_f32_e32 v100, v102, v104
	v_mul_f32_e32 v100, 0x3fb8aa3b, v100
	v_exp_f32_e32 v102, v100
	v_sub_f32_e32 v100, v103, v104
	v_mul_f32_e32 v100, 0x3fb8aa3b, v100
	v_cvt_pk_bf16_f32 v99, v110, v108
	v_exp_f32_e32 v108, v100
	v_sub_f32_e32 v100, v183, v104
	v_mul_f32_e32 v100, 0x3fb8aa3b, v100
	v_exp_f32_e32 v112, v100
	v_add_f32_e32 v109, v105, v102
	v_pk_add_f32 v[100:101], v[108:109], v[112:113]
	s_nop 0
	v_pk_add_f32 v[110:111], v[100:101], v[100:101] op_sel_hi:[0,1]
	v_sub_f32_e32 v100, v184, v104
	v_mul_f32_e32 v100, 0x3fb8aa3b, v100
	v_exp_f32_e32 v103, v100
	v_sub_f32_e32 v100, v185, v104
	v_mul_f32_e32 v100, 0x3fb8aa3b, v100
	v_exp_f32_e32 v106, v100
	v_sub_f32_e32 v100, v192, v104
	v_mul_f32_e32 v100, 0x3fb8aa3b, v100
	v_exp_f32_e32 v114, v100
	v_sub_f32_e32 v100, v193, v104
	v_mul_f32_e32 v100, 0x3fb8aa3b, v100
	v_exp_f32_e32 v110, v100
	v_add_f32_e32 v115, v103, v106
	v_pk_add_f32 v[100:101], v[114:115], v[110:111]
	s_nop 0
	v_pk_add_f32 v[116:117], v[100:101], v[100:101] op_sel_hi:[0,1]
	v_cvt_pk_bf16_f32 v100, v105, v102
	v_cvt_pk_bf16_f32 v102, v103, v106
	v_sub_f32_e32 v106, v179, v104
	v_mul_f32_e32 v106, 0x3fb8aa3b, v106
	v_cvt_pk_bf16_f32 v103, v114, v110
	v_exp_f32_e32 v114, v106
	v_sub_f32_e32 v106, v188, v104
	v_sub_f32_e32 v105, v107, v104
	v_mul_f32_e32 v106, 0x3fb8aa3b, v106
	v_cvt_pk_bf16_f32 v101, v108, v112
	v_mul_f32_e32 v105, 0x3fb8aa3b, v105
	v_exp_f32_e32 v108, v106
	v_sub_f32_e32 v106, v189, v104
	v_exp_f32_e32 v105, v105
	v_mul_f32_e32 v106, 0x3fb8aa3b, v106
	v_exp_f32_e32 v116, v106
	v_add_f32_e32 v109, v105, v114
	v_pk_add_f32 v[106:107], v[108:109], v[116:117]
	s_nop 0
	v_pk_add_f32 v[110:111], v[106:107], v[106:107] op_sel_hi:[0,1]
	v_sub_f32_e32 v106, v190, v104
	v_mul_f32_e32 v106, 0x3fb8aa3b, v106
	v_exp_f32_e32 v109, v106
	v_sub_f32_e32 v106, v191, v104
	v_mul_f32_e32 v106, 0x3fb8aa3b, v106
	v_exp_f32_e32 v115, v106
	v_sub_f32_e32 v106, v155, v104
	v_mul_f32_e32 v106, 0x3fb8aa3b, v106
	v_exp_f32_e32 v112, v106
	v_sub_f32_e32 v106, v194, v104
	v_mul_f32_e32 v106, 0x3fb8aa3b, v106
	v_exp_f32_e32 v110, v106
	v_add_f32_e32 v113, v109, v115
	v_sub_f32_e32 v104, v154, v104
	v_mul_f32_e32 v104, 0x3fb8aa3b, v104
	v_pk_add_f32 v[106:107], v[112:113], v[110:111]
	v_exp_f32_e32 v104, v104
	v_add_f32_e32 v111, v106, v107
	v_cvt_pk_bf16_f32 v106, v105, v114
	v_add_f32_e32 v105, v72, v111
	v_add_f32_e32 v105, v73, v105
	v_add_f32_e32 v105, v74, v105
	v_add_f32_e32 v105, v75, v105
	v_cvt_pk_bf16_f32 v72, v72, v73
	v_cvt_pk_bf16_f32 v73, v74, v75
	ds_bpermute_b32 v74, v157, v105
	v_cvt_pk_bf16_f32 v107, v108, v116
	v_cvt_pk_bf16_f32 v108, v109, v115
	v_cvt_pk_bf16_f32 v109, v112, v110
	s_waitcnt lgkmcnt(0)
	v_add_f32_e32 v74, v105, v74
	ds_bpermute_b32 v75, v156, v74
	v_mad_u32_u24 v146, v151, s9, v158
	v_add3_u32 v147, v146, v153, s78
	ds_read_b128 v[110:113], v147
	ds_read_b128 v[114:117], v147 offset:12800
	ds_read_b128 v[118:121], v147 offset:25600
	ds_read_b128 v[122:125], v147 offset:38400
	ds_read_b128 v[126:129], v147 offset:64
	ds_read_b128 v[130:133], v147 offset:12864
	ds_read_b128 v[134:137], v147 offset:25664
	ds_read_b128 v[138:141], v147 offset:38464
	ds_read_b128 v[142:145], v147 offset:128
	ds_read_b128 v[160:163], v147 offset:12928
	ds_read_b128 v[176:179], v147 offset:25728
	ds_read_b128 v[180:183], v147 offset:38528
	s_waitcnt lgkmcnt(12)
	v_add_f32_e32 v105, v74, v75
	s_waitcnt lgkmcnt(11)
	v_mfma_f32_16x16x32_bf16 v[110:113], v[110:113], v[68:71], 0
	s_waitcnt lgkmcnt(10)
	v_mfma_f32_16x16x32_bf16 v[114:117], v[114:117], v[68:71], 0
	s_waitcnt lgkmcnt(9)
	v_mfma_f32_16x16x32_bf16 v[118:121], v[118:121], v[68:71], 0
	s_waitcnt lgkmcnt(8)
	v_mfma_f32_16x16x32_bf16 v[68:71], v[122:125], v[68:71], 0
	s_waitcnt lgkmcnt(7)
	v_mfma_f32_16x16x32_bf16 v[110:113], v[126:129], v[76:79], v[110:113]
	s_waitcnt lgkmcnt(6)
	v_mfma_f32_16x16x32_bf16 v[114:117], v[130:133], v[76:79], v[114:117]
	s_waitcnt lgkmcnt(5)
	v_mfma_f32_16x16x32_bf16 v[118:121], v[134:137], v[76:79], v[118:121]
	s_waitcnt lgkmcnt(4)
	v_mfma_f32_16x16x32_bf16 v[68:71], v[138:141], v[76:79], v[68:71]
	s_waitcnt lgkmcnt(3)
	v_mfma_f32_16x16x32_bf16 v[74:77], v[142:145], v[80:83], v[110:113]
	s_waitcnt lgkmcnt(2)
	v_mfma_f32_16x16x32_bf16 v[110:113], v[160:163], v[80:83], v[114:117]
	s_waitcnt lgkmcnt(1)
	v_mfma_f32_16x16x32_bf16 v[114:117], v[176:179], v[80:83], v[118:121]
	s_waitcnt lgkmcnt(0)
	v_mfma_f32_16x16x32_bf16 v[68:71], v[180:183], v[80:83], v[68:71]
	ds_read_b128 v[78:81], v147 offset:12992
	ds_read_b128 v[118:121], v147 offset:13056
	ds_read_b128 v[122:125], v147 offset:38592
	ds_read_b128 v[126:129], v147 offset:38656
	ds_read_b128 v[130:133], v147 offset:256
	ds_read_b128 v[134:137], v147 offset:320
	ds_read_b128 v[138:141], v147 offset:25792
	ds_read_b128 v[142:145], v147 offset:13120
	ds_read_b128 v[160:163], v147 offset:25856
	ds_read_b128 v[176:179], v147 offset:25920
	ds_read_b128 v[180:183], v147 offset:192
	ds_read_b128 v[184:187], v147 offset:38720
	s_waitcnt lgkmcnt(1)
	v_mfma_f32_16x16x32_bf16 v[74:77], v[180:183], v[84:87], v[74:77]
	v_mfma_f32_16x16x32_bf16 v[78:81], v[78:81], v[84:87], v[110:113]
	v_mfma_f32_16x16x32_bf16 v[110:113], v[138:141], v[84:87], v[114:117]
	v_mfma_f32_16x16x32_bf16 v[68:71], v[122:125], v[84:87], v[68:71]
	v_mfma_f32_16x16x32_bf16 v[74:77], v[130:133], v[88:91], v[74:77]
	v_mfma_f32_16x16x32_bf16 v[78:81], v[118:121], v[88:91], v[78:81]
	v_mfma_f32_16x16x32_bf16 v[82:85], v[160:163], v[88:91], v[110:113]
	v_mfma_f32_16x16x32_bf16 v[68:71], v[126:129], v[88:91], v[68:71]
	v_mfma_f32_16x16x32_bf16 v[74:77], v[134:137], v[92:95], v[74:77]
	v_mfma_f32_16x16x32_bf16 v[78:81], v[142:145], v[92:95], v[78:81]
	v_mfma_f32_16x16x32_bf16 v[82:85], v[176:179], v[92:95], v[82:85]
	s_waitcnt lgkmcnt(0)
	v_mfma_f32_16x16x32_bf16 v[68:71], v[184:187], v[92:95], v[68:71]
	ds_read_b128 v[86:89], v147 offset:13184
	ds_read_b128 v[90:93], v147 offset:13248
	ds_read_b128 v[110:113], v147 offset:38784
	ds_read_b128 v[114:117], v147 offset:38848
	ds_read_b128 v[118:121], v147 offset:448
	ds_read_b128 v[122:125], v147 offset:512
	ds_read_b128 v[126:129], v147 offset:25984
	ds_read_b128 v[130:133], v147 offset:13312
	ds_read_b128 v[134:137], v147 offset:26048
	ds_read_b128 v[138:141], v147 offset:26112
	ds_read_b128 v[142:145], v147 offset:384
	ds_read_b128 v[160:163], v147 offset:38912
	s_waitcnt lgkmcnt(1)
	v_mfma_f32_16x16x32_bf16 v[74:77], v[142:145], v[96:99], v[74:77]
	v_mfma_f32_16x16x32_bf16 v[78:81], v[86:89], v[96:99], v[78:81]
	v_mfma_f32_16x16x32_bf16 v[82:85], v[126:129], v[96:99], v[82:85]
	v_mfma_f32_16x16x32_bf16 v[68:71], v[110:113], v[96:99], v[68:71]
	v_mfma_f32_16x16x32_bf16 v[74:77], v[118:121], v[100:103], v[74:77]
	v_mfma_f32_16x16x32_bf16 v[78:81], v[90:93], v[100:103], v[78:81]
	v_mfma_f32_16x16x32_bf16 v[82:85], v[134:137], v[100:103], v[82:85]
	v_mfma_f32_16x16x32_bf16 v[68:71], v[114:117], v[100:103], v[68:71]
	v_mfma_f32_16x16x32_bf16 v[86:89], v[122:125], v[106:109], v[74:77]
	v_mfma_f32_16x16x32_bf16 v[76:79], v[130:133], v[106:109], v[78:81]
	v_mfma_f32_16x16x32_bf16 v[80:83], v[138:141], v[106:109], v[82:85]
	s_waitcnt lgkmcnt(0)
	v_mfma_f32_16x16x32_bf16 v[68:71], v[160:163], v[106:109], v[68:71]
	s_nop 1
	v_add_u32_e32 v84, v146, v152
	v_add_u32_e32 v98, 0x100, v84
	ds_read2st64_b64 v[90:93], v98 offset0:1 offset1:26
	v_mov_b32_e32 v96, v3
	v_mov_b32_e32 v97, v3
	v_mov_b32_e32 v74, v3
	v_mov_b32_e32 v75, v3
	s_waitcnt lgkmcnt(0)
	v_mov_b32_e32 v94, v90
	v_mov_b32_e32 v95, v91
	v_mov_b32_e32 v90, v3
	v_mov_b32_e32 v91, v3
	v_mov_b32_e32 v141, v173
	v_mfma_f32_16x16x32_bf16 v[84:87], v[94:97], v[72:75], v[86:89]
	v_mov_b32_e32 v94, v3
	v_mov_b32_e32 v95, v3
	s_nop 0
	v_mov_b32_e32 v88, v92
	v_mov_b32_e32 v89, v93
	s_nop 1
	v_mfma_f32_16x16x32_bf16 v[76:79], v[88:91], v[72:75], v[76:79]
	ds_read2st64_b64 v[88:91], v98 offset0:51 offset1:76
	s_waitcnt lgkmcnt(0)
	v_mov_b32_e32 v92, v88
	v_mov_b32_e32 v93, v89
	v_mov_b32_e32 v88, v90
	v_mov_b32_e32 v89, v91
	v_mov_b32_e32 v90, v3
	v_mov_b32_e32 v91, v3
	v_mfma_f32_16x16x32_bf16 v[80:83], v[92:95], v[72:75], v[80:83]
	s_nop 0
	v_mfma_f32_16x16x32_bf16 v[68:71], v[88:91], v[72:75], v[68:71]
	v_add_f32_e32 v72, v104, v105
	v_div_scale_f32 v73, s[0:1], v72, v72, 1.0
	v_rcp_f32_e32 v74, v73
	s_or_b32 s0, s74, 0x80
	s_ashr_i32 s1, s0, 31
	v_fma_f32 v75, -v73, v74, 1.0
	v_fmac_f32_e32 v74, v75, v74
	v_div_scale_f32 v75, vcc, 1.0, v72, 1.0
	v_mul_f32_e32 v88, v75, v74
	v_fma_f32 v89, -v73, v88, v75
	v_fmac_f32_e32 v88, v89, v74
	v_fma_f32 v73, -v73, v88, v75
	v_div_fmas_f32 v73, v73, v74, v88
	v_div_fixup_f32 v88, v73, v72, 1.0
	v_lshlrev_b32_e32 v72, 2, v150
	v_and_b32_e32 v89, 16, v148
	v_and_b32_e32 v90, -8, v72
	v_mad_i64_i32 v[72:73], s[36:37], v149, s43, v[0:1]
	v_lshl_add_u64 v[92:93], s[0:1], 1, v[72:73]
	v_pk_mul_f32 v[74:75], v[86:87], v[88:89] op_sel_hi:[1,0]
	v_pk_mul_f32 v[72:73], v[84:85], v[88:89] op_sel_hi:[1,0]
	v_pk_mul_f32 v[76:77], v[76:77], v[88:89] op_sel_hi:[1,0]
	v_pk_mul_f32 v[78:79], v[78:79], v[88:89] op_sel_hi:[1,0]
	v_cvt_pk_bf16_f32 v72, v72, v73
	v_cvt_pk_bf16_f32 v73, v74, v75
	v_cvt_pk_bf16_f32 v74, v76, v77
	v_lshlrev_b32_e32 v76, 1, v89
	v_mov_b32_e32 v77, v3
	v_ashrrev_i32_e32 v91, 31, v90
	v_cvt_pk_bf16_f32 v75, v78, v79
	v_lshl_add_u64 v[76:77], v[92:93], 0, v[76:77]
	v_permlane16_swap_b32_e32 v72, v74
	v_permlane16_swap_b32_e32 v73, v75
	v_lshl_add_u64 v[76:77], v[90:91], 1, v[76:77]
	global_load_dword v146, v3, s[44:45] offset:12
	global_store_dwordx4 v[76:77], v[72:75], off offset:2048
	v_pk_mul_f32 v[78:79], v[88:89], v[70:71] op_sel_hi:[0,1]
	v_pk_mul_f32 v[70:71], v[88:89], v[68:69] op_sel_hi:[0,1]
	v_pk_mul_f32 v[72:73], v[82:83], v[88:89] op_sel_hi:[1,0]
	v_pk_mul_f32 v[74:75], v[80:81], v[88:89] op_sel_hi:[1,0]
	v_cvt_pk_bf16_f32 v69, v72, v73
	v_cvt_pk_bf16_f32 v68, v74, v75
	v_cvt_pk_bf16_f32 v70, v70, v71
	v_cvt_pk_bf16_f32 v71, v78, v79
	s_nop 0
	v_permlane16_swap_b32_e32 v68, v70
	v_permlane16_swap_b32_e32 v69, v71
	global_store_dwordx4 v[76:77], v[68:71], off offset:2112
	s_nop 0
	v_and_b32_e32 v143, 15, v141
	v_or_b32_e32 v147, s4, v143
	v_add_u32_e32 v68, s82, v147
	v_or_b32_e32 v69, s5, v143
	v_cndmask_b32_e64 v140, v68, v69, s[38:39]
	v_lshlrev_b32_e32 v68, 1, v141
	v_and_or_b32 v68, v68, 30, s21
	v_mul_lo_u32 v68, v68, s8
	v_and_b32_e32 v145, -16, v141
	v_add3_u32 v144, 0, v68, v145
	ds_read_b128 v[68:71], v144
	ds_read_b128 v[72:75], v144 offset:64
	ds_read_b128 v[76:79], v144 offset:208
	ds_read_b128 v[80:83], v144 offset:272
	ds_read_b128 v[84:87], v144 offset:6656
	ds_read_b128 v[88:91], v144 offset:6720
	ds_read_b128 v[92:95], v144 offset:6864
	ds_read_b128 v[96:99], v144 offset:6928
	ds_read_b128 v[100:103], v144 offset:13312
	ds_read_b128 v[104:107], v144 offset:13376
	ds_read_b128 v[108:111], v144 offset:13520
	ds_read_b128 v[112:115], v144 offset:13584
	v_ashrrev_i32_e32 v142, 4, v141
	s_waitcnt lgkmcnt(11)
	v_mfma_f32_16x16x32_bf16 v[68:71], v[68:71], v[64:67], 0
	s_waitcnt lgkmcnt(10)
	v_mfma_f32_16x16x32_bf16 v[150:153], v[72:75], v[60:63], v[68:71]
	s_waitcnt lgkmcnt(9)
	v_mfma_f32_16x16x32_bf16 v[68:71], v[76:79], v[64:67], 0
	s_waitcnt lgkmcnt(8)
	v_mfma_f32_16x16x32_bf16 v[160:163], v[80:83], v[60:63], v[68:71]
	s_waitcnt lgkmcnt(7)
	v_mfma_f32_16x16x32_bf16 v[68:71], v[84:87], v[64:67], 0
	s_waitcnt lgkmcnt(6)
	v_mfma_f32_16x16x32_bf16 v[136:139], v[88:91], v[60:63], v[68:71]
	s_waitcnt lgkmcnt(5)
	v_mfma_f32_16x16x32_bf16 v[68:71], v[92:95], v[64:67], 0
	s_waitcnt lgkmcnt(4)
	v_mfma_f32_16x16x32_bf16 v[132:135], v[96:99], v[60:63], v[68:71]
	s_waitcnt lgkmcnt(3)
	v_mfma_f32_16x16x32_bf16 v[68:71], v[100:103], v[64:67], 0
	s_waitcnt lgkmcnt(2)
	v_mfma_f32_16x16x32_bf16 v[128:131], v[104:107], v[60:63], v[68:71]
	s_waitcnt lgkmcnt(1)
	v_mfma_f32_16x16x32_bf16 v[68:71], v[108:111], v[64:67], 0
	s_waitcnt lgkmcnt(0)
	v_mfma_f32_16x16x32_bf16 v[124:127], v[112:115], v[60:63], v[68:71]
	s_nop 5
	ds_read_b128 v[68:71], v144 offset:19968
	ds_read_b128 v[72:75], v144 offset:20032
	ds_read_b128 v[76:79], v144 offset:20176
	ds_read_b128 v[80:83], v144 offset:20240
	ds_read_b128 v[84:87], v144 offset:26624
	ds_read_b128 v[88:91], v144 offset:26688
	ds_read_b128 v[92:95], v144 offset:26832
	ds_read_b128 v[96:99], v144 offset:26896
	ds_read_b128 v[100:103], v144 offset:33280
	ds_read_b128 v[104:107], v144 offset:33344
	ds_read_b128 v[176:179], v144 offset:33488
	ds_read_b128 v[180:183], v144 offset:33552
	s_waitcnt lgkmcnt(11)
	v_mfma_f32_16x16x32_bf16 v[68:71], v[68:71], v[64:67], 0
	s_waitcnt lgkmcnt(10)
	v_mfma_f32_16x16x32_bf16 v[120:123], v[72:75], v[60:63], v[68:71]
	s_waitcnt lgkmcnt(9)
	v_mfma_f32_16x16x32_bf16 v[68:71], v[76:79], v[64:67], 0
	s_waitcnt lgkmcnt(8)
	v_mfma_f32_16x16x32_bf16 v[116:119], v[80:83], v[60:63], v[68:71]
	s_waitcnt lgkmcnt(7)
	v_mfma_f32_16x16x32_bf16 v[68:71], v[84:87], v[64:67], 0
	s_waitcnt lgkmcnt(6)
	v_mfma_f32_16x16x32_bf16 v[112:115], v[88:91], v[60:63], v[68:71]
	s_waitcnt lgkmcnt(5)
	v_mfma_f32_16x16x32_bf16 v[68:71], v[92:95], v[64:67], 0
	s_waitcnt lgkmcnt(4)
	v_mfma_f32_16x16x32_bf16 v[108:111], v[96:99], v[60:63], v[68:71]
	s_waitcnt lgkmcnt(3)
	v_mfma_f32_16x16x32_bf16 v[68:71], v[100:103], v[64:67], 0
	s_waitcnt lgkmcnt(2)
	v_mfma_f32_16x16x32_bf16 v[104:107], v[104:107], v[60:63], v[68:71]
	s_waitcnt lgkmcnt(1)
	v_mfma_f32_16x16x32_bf16 v[68:71], v[176:179], v[64:67], 0
	s_waitcnt lgkmcnt(0)
	v_mfma_f32_16x16x32_bf16 v[100:103], v[180:183], v[60:63], v[68:71]
	s_nop 5
	ds_read_b128 v[68:71], v144 offset:39936
	ds_read_b128 v[72:75], v144 offset:40000
	ds_read_b128 v[76:79], v144 offset:40144
	ds_read_b128 v[80:83], v144 offset:40208
	ds_read_b128 v[84:87], v144 offset:46592
	ds_read_b128 v[88:91], v144 offset:46656
	ds_read_b128 v[176:179], v144 offset:46800
	ds_read_b128 v[180:183], v144 offset:46864
	ds_read_b128 v[184:187], v144 offset:53248
	ds_read_b128 v[188:191], v144 offset:53312
	ds_read_b128 v[192:195], v144 offset:53456
	ds_read_b128 v[196:199], v144 offset:53520
	s_waitcnt lgkmcnt(11)
	v_mfma_f32_16x16x32_bf16 v[68:71], v[68:71], v[64:67], 0
	s_waitcnt lgkmcnt(10)
	v_mfma_f32_16x16x32_bf16 v[96:99], v[72:75], v[60:63], v[68:71]
	s_waitcnt lgkmcnt(9)
	v_mfma_f32_16x16x32_bf16 v[68:71], v[76:79], v[64:67], 0
	s_waitcnt lgkmcnt(8)
	v_mfma_f32_16x16x32_bf16 v[92:95], v[80:83], v[60:63], v[68:71]
	s_waitcnt lgkmcnt(7)
	v_mfma_f32_16x16x32_bf16 v[68:71], v[84:87], v[64:67], 0
	s_waitcnt lgkmcnt(6)
	v_mfma_f32_16x16x32_bf16 v[88:91], v[88:91], v[60:63], v[68:71]
	s_waitcnt lgkmcnt(5)
	v_mfma_f32_16x16x32_bf16 v[68:71], v[176:179], v[64:67], 0
	s_waitcnt lgkmcnt(4)
	v_mfma_f32_16x16x32_bf16 v[84:87], v[180:183], v[60:63], v[68:71]
	s_waitcnt lgkmcnt(3)
	v_mfma_f32_16x16x32_bf16 v[68:71], v[184:187], v[64:67], 0
	s_waitcnt lgkmcnt(2)
	v_mfma_f32_16x16x32_bf16 v[80:83], v[188:191], v[60:63], v[68:71]
	s_waitcnt lgkmcnt(1)
	v_mfma_f32_16x16x32_bf16 v[68:71], v[192:195], v[64:67], 0
	s_waitcnt lgkmcnt(0)
	v_mfma_f32_16x16x32_bf16 v[76:79], v[196:199], v[60:63], v[68:71]
	s_nop 5
	v_mad_u32_u24 v68, v143, s8, 0
	v_add3_u32 v68, v68, v145, s46
	ds_read_b128 v[72:75], v68
	ds_read_b128 v[68:71], v68 offset:64
	v_lshlrev_b32_e32 v144, 3, v142
	v_add_u32_e32 v159, s3, v144
	v_add_u32_e32 v155, s21, v159
	v_sub_u32_e32 v148, v147, v155
	v_add_u32_e32 v149, 0x80, v148
	v_add_u32_e32 v148, 0x7f, v148
	v_cmp_gt_u32_e32 vcc, s33, v155
	v_cmp_gt_u32_e64 s[0:1], s34, v149
	v_cmp_gt_u32_e64 s[40:41], s34, v148
	s_and_b64 s[0:1], vcc, s[0:1]
	s_and_b64 s[40:41], vcc, s[40:41]
	v_cndmask_b32_e64 v150, v231, v150, s[0:1]
	v_cndmask_b32_e64 v148, v231, v160, s[40:41]
	v_max_f32_e32 v149, v148, v148
	v_max_f32_e32 v154, v150, v150
	v_max_f32_e32 v149, v154, v149
	v_or_b32_e32 v154, 2, v155
	v_sub_u32_e32 v154, v147, v154
	v_add_u32_e32 v160, 0x80, v154
	v_add_u32_e32 v154, 0x7f, v154
	v_cmp_gt_u32_e64 s[0:1], s34, v160
	v_cmp_gt_u32_e64 s[40:41], s34, v154
	s_and_b64 s[0:1], vcc, s[0:1]
	s_and_b64 s[40:41], vcc, s[40:41]
	v_cndmask_b32_e64 v154, v231, v151, s[0:1]
	v_cndmask_b32_e64 v151, v231, v161, s[40:41]
	v_max_f32_e32 v160, v151, v151
	v_max_f32_e32 v161, v154, v154
	v_max_f32_e32 v160, v161, v160
	s_waitcnt lgkmcnt(1)
	v_mfma_f32_16x16x32_bf16 v[64:67], v[72:75], v[64:67], 0
	s_mov_b32 s8, 0x13800
	s_waitcnt vmcnt(2)
	v_max3_f32 v160, v146, v149, v160
	v_or_b32_e32 v149, 4, v155
	v_sub_u32_e32 v149, v147, v149
	v_add_u32_e32 v161, 0x80, v149
	v_add_u32_e32 v149, 0x7f, v149
	v_cmp_gt_u32_e64 s[0:1], s34, v161
	v_cmp_gt_u32_e64 s[40:41], s34, v149
	s_and_b64 s[0:1], vcc, s[0:1]
	s_and_b64 s[40:41], vcc, s[40:41]
	v_cndmask_b32_e64 v152, v231, v152, s[0:1]
	v_cndmask_b32_e64 v149, v231, v162, s[40:41]
	v_or_b32_e32 v155, 6, v155
	v_max_f32_e32 v161, v149, v149
	v_max_f32_e32 v162, v152, v152
	v_sub_u32_e32 v155, v147, v155
	v_max_f32_e32 v161, v162, v161
	v_add_u32_e32 v162, 0x80, v155
	v_add_u32_e32 v155, 0x7f, v155
	v_cmp_gt_u32_e64 s[0:1], s34, v162
	v_cmp_gt_u32_e64 s[40:41], s34, v155
	s_and_b64 s[0:1], vcc, s[0:1]
	s_and_b64 vcc, vcc, s[40:41]
	v_cndmask_b32_e64 v155, v231, v153, s[0:1]
	v_cndmask_b32_e32 v153, v231, v163, vcc
	v_max_f32_e32 v162, v153, v153
	v_max_f32_e32 v163, v155, v155
	v_max_f32_e32 v162, v163, v162
	v_max3_f32 v160, v160, v161, v162
	v_add_u32_e32 v161, s22, v159
	v_sub_u32_e32 v162, v147, v161
	v_add_u32_e32 v163, 0x80, v162
	v_add_u32_e32 v162, 0x7f, v162
	v_cmp_gt_u32_e32 vcc, s33, v161
	v_cmp_gt_u32_e64 s[0:1], s34, v163
	v_cmp_gt_u32_e64 s[40:41], s34, v162
	s_and_b64 s[0:1], vcc, s[0:1]
	s_and_b64 s[40:41], vcc, s[40:41]
	v_cndmask_b32_e64 v136, v231, v136, s[0:1]
	v_cndmask_b32_e64 v132, v231, v132, s[40:41]
	v_max_f32_e32 v162, v132, v132
	v_max_f32_e32 v163, v136, v136
	v_max_f32_e32 v162, v163, v162
	v_or_b32_e32 v163, 2, v161
	v_sub_u32_e32 v163, v147, v163
	v_add_u32_e32 v168, 0x80, v163
	v_cmp_gt_u32_e64 s[0:1], s34, v168
	v_add_u32_e32 v163, 0x7f, v163
	s_and_b64 s[40:41], vcc, s[0:1]
	v_cmp_gt_u32_e64 s[0:1], s34, v163
	s_and_b64 s[0:1], vcc, s[0:1]
	v_cndmask_b32_e64 v137, v231, v137, s[40:41]
	v_cndmask_b32_e64 v133, v231, v133, s[0:1]
	v_max_f32_e32 v163, v133, v133
	v_max_f32_e32 v168, v137, v137
	v_max_f32_e32 v163, v168, v163
	v_max3_f32 v160, v160, v162, v163
	v_or_b32_e32 v162, 4, v161
	v_sub_u32_e32 v162, v147, v162
	v_add_u32_e32 v163, 0x80, v162
	v_add_u32_e32 v162, 0x7f, v162
	v_cmp_gt_u32_e64 s[0:1], s34, v163
	v_cmp_gt_u32_e64 s[40:41], s34, v162
	s_and_b64 s[0:1], vcc, s[0:1]
	s_and_b64 s[40:41], vcc, s[40:41]
	v_cndmask_b32_e64 v138, v231, v138, s[0:1]
	v_cndmask_b32_e64 v134, v231, v134, s[40:41]
	v_or_b32_e32 v161, 6, v161
	v_max_f32_e32 v162, v134, v134
	v_max_f32_e32 v163, v138, v138
	v_sub_u32_e32 v161, v147, v161
	v_max_f32_e32 v162, v163, v162
	v_add_u32_e32 v163, 0x80, v161
	v_add_u32_e32 v161, 0x7f, v161
	v_cmp_gt_u32_e64 s[0:1], s34, v163
	v_cmp_gt_u32_e64 s[40:41], s34, v161
	s_and_b64 s[0:1], vcc, s[0:1]
	s_and_b64 vcc, vcc, s[40:41]
	v_cndmask_b32_e64 v139, v231, v139, s[0:1]
	v_cndmask_b32_e32 v135, v231, v135, vcc
	v_max_f32_e32 v161, v135, v135
	v_max_f32_e32 v163, v139, v139
	v_max_f32_e32 v161, v163, v161
	v_max3_f32 v160, v160, v162, v161
	v_add_u32_e32 v161, s23, v159
	v_sub_u32_e32 v162, v147, v161
	v_add_u32_e32 v163, 0x80, v162
	v_add_u32_e32 v162, 0x7f, v162
	v_cmp_gt_u32_e32 vcc, s33, v161
	v_cmp_gt_u32_e64 s[0:1], s34, v163
	v_cmp_gt_u32_e64 s[40:41], s34, v162
	s_and_b64 s[0:1], vcc, s[0:1]
	s_and_b64 s[40:41], vcc, s[40:41]
	v_cndmask_b32_e64 v128, v231, v128, s[0:1]
	v_cndmask_b32_e64 v124, v231, v124, s[40:41]
	v_max_f32_e32 v162, v124, v124
	v_max_f32_e32 v163, v128, v128
	v_max_f32_e32 v162, v163, v162
	v_or_b32_e32 v163, 2, v161
	v_sub_u32_e32 v163, v147, v163
	v_add_u32_e32 v168, 0x80, v163
	v_add_u32_e32 v163, 0x7f, v163
	v_cmp_gt_u32_e64 s[0:1], s34, v168
	v_cmp_gt_u32_e64 s[40:41], s34, v163
	s_and_b64 s[0:1], vcc, s[0:1]
	s_and_b64 s[40:41], vcc, s[40:41]
	v_cndmask_b32_e64 v129, v231, v129, s[0:1]
	v_cndmask_b32_e64 v125, v231, v125, s[40:41]
	v_max_f32_e32 v163, v125, v125
	v_max_f32_e32 v168, v129, v129
	v_max_f32_e32 v163, v168, v163
	v_max3_f32 v160, v160, v162, v163
	v_or_b32_e32 v162, 4, v161
	v_sub_u32_e32 v162, v147, v162
	v_add_u32_e32 v163, 0x80, v162
	v_add_u32_e32 v162, 0x7f, v162
	v_cmp_gt_u32_e64 s[0:1], s34, v163
	v_cmp_gt_u32_e64 s[40:41], s34, v162
	s_and_b64 s[0:1], vcc, s[0:1]
	s_and_b64 s[40:41], vcc, s[40:41]
	v_cndmask_b32_e64 v130, v231, v130, s[0:1]
	v_cndmask_b32_e64 v126, v231, v126, s[40:41]
	v_or_b32_e32 v161, 6, v161
	v_max_f32_e32 v162, v126, v126
	v_max_f32_e32 v163, v130, v130
	v_sub_u32_e32 v161, v147, v161
	v_max_f32_e32 v162, v163, v162
	v_add_u32_e32 v163, 0x80, v161
	v_add_u32_e32 v161, 0x7f, v161
	v_cmp_gt_u32_e64 s[0:1], s34, v163
	v_cmp_gt_u32_e64 s[40:41], s34, v161
	s_and_b64 s[0:1], vcc, s[0:1]
	s_and_b64 vcc, vcc, s[40:41]
	v_cndmask_b32_e64 v131, v231, v131, s[0:1]
	v_cndmask_b32_e32 v127, v231, v127, vcc
	v_max_f32_e32 v161, v127, v127
	v_max_f32_e32 v163, v131, v131
	v_max_f32_e32 v161, v163, v161
	v_max3_f32 v160, v160, v162, v161
	v_add_u32_e32 v161, s26, v159
	v_sub_u32_e32 v162, v147, v161
	v_add_u32_e32 v163, 0x80, v162
	v_add_u32_e32 v162, 0x7f, v162
	v_cmp_gt_u32_e32 vcc, s33, v161
	v_cmp_gt_u32_e64 s[0:1], s34, v163
	v_cmp_gt_u32_e64 s[40:41], s34, v162
	s_and_b64 s[0:1], vcc, s[0:1]
	s_and_b64 s[40:41], vcc, s[40:41]
	v_cndmask_b32_e64 v120, v231, v120, s[0:1]
	v_cndmask_b32_e64 v116, v231, v116, s[40:41]
	v_max_f32_e32 v162, v116, v116
	v_max_f32_e32 v163, v120, v120
	v_max_f32_e32 v162, v163, v162
	v_or_b32_e32 v163, 2, v161
	v_sub_u32_e32 v163, v147, v163
	v_add_u32_e32 v168, 0x80, v163
	v_add_u32_e32 v163, 0x7f, v163
	v_cmp_gt_u32_e64 s[0:1], s34, v168
	v_cmp_gt_u32_e64 s[40:41], s34, v163
	s_and_b64 s[0:1], vcc, s[0:1]
	s_and_b64 s[40:41], vcc, s[40:41]
	v_cndmask_b32_e64 v121, v231, v121, s[0:1]
	v_cndmask_b32_e64 v117, v231, v117, s[40:41]
	v_max_f32_e32 v163, v117, v117
	v_max_f32_e32 v168, v121, v121
	v_max_f32_e32 v163, v168, v163
	v_max3_f32 v160, v160, v162, v163
	v_or_b32_e32 v162, 4, v161
	v_sub_u32_e32 v162, v147, v162
	v_add_u32_e32 v163, 0x80, v162
	v_add_u32_e32 v162, 0x7f, v162
	v_cmp_gt_u32_e64 s[0:1], s34, v163
	v_cmp_gt_u32_e64 s[40:41], s34, v162
	s_and_b64 s[0:1], vcc, s[0:1]
	s_and_b64 s[40:41], vcc, s[40:41]
	v_cndmask_b32_e64 v122, v231, v122, s[0:1]
	v_cndmask_b32_e64 v118, v231, v118, s[40:41]
	v_or_b32_e32 v161, 6, v161
	v_max_f32_e32 v162, v118, v118
	v_max_f32_e32 v163, v122, v122
	v_sub_u32_e32 v161, v147, v161
	v_max_f32_e32 v162, v163, v162
	v_add_u32_e32 v163, 0x80, v161
	v_add_u32_e32 v161, 0x7f, v161
	v_cmp_gt_u32_e64 s[0:1], s34, v163
	v_cmp_gt_u32_e64 s[40:41], s34, v161
	s_and_b64 s[0:1], vcc, s[0:1]
	s_and_b64 vcc, vcc, s[40:41]
	v_cndmask_b32_e64 v123, v231, v123, s[0:1]
	v_cndmask_b32_e32 v119, v231, v119, vcc
	v_max_f32_e32 v161, v119, v119
	v_max_f32_e32 v163, v123, v123
	v_max_f32_e32 v161, v163, v161
	v_max3_f32 v160, v160, v162, v161
	v_add_u32_e32 v161, s27, v159
	v_sub_u32_e32 v162, v147, v161
	v_add_u32_e32 v163, 0x80, v162
	v_add_u32_e32 v162, 0x7f, v162
	v_cmp_gt_u32_e32 vcc, s33, v161
	v_cmp_gt_u32_e64 s[0:1], s34, v163
	v_cmp_gt_u32_e64 s[40:41], s34, v162
	s_and_b64 s[0:1], vcc, s[0:1]
	s_and_b64 s[40:41], vcc, s[40:41]
	v_cndmask_b32_e64 v112, v231, v112, s[0:1]
	v_cndmask_b32_e64 v108, v231, v108, s[40:41]
	v_max_f32_e32 v162, v108, v108
	v_max_f32_e32 v163, v112, v112
	v_max_f32_e32 v162, v163, v162
	v_or_b32_e32 v163, 2, v161
	v_sub_u32_e32 v163, v147, v163
	v_add_u32_e32 v168, 0x80, v163
	v_add_u32_e32 v163, 0x7f, v163
	v_cmp_gt_u32_e64 s[0:1], s34, v168
	v_cmp_gt_u32_e64 s[40:41], s34, v163
	s_and_b64 s[0:1], vcc, s[0:1]
	s_and_b64 s[40:41], vcc, s[40:41]
	v_cndmask_b32_e64 v113, v231, v113, s[0:1]
	v_cndmask_b32_e64 v109, v231, v109, s[40:41]
	v_max_f32_e32 v163, v109, v109
	v_max_f32_e32 v168, v113, v113
	v_max_f32_e32 v163, v168, v163
	v_max3_f32 v162, v160, v162, v163
	v_or_b32_e32 v160, 4, v161
	v_sub_u32_e32 v160, v147, v160
	v_add_u32_e32 v163, 0x80, v160
	v_add_u32_e32 v160, 0x7f, v160
	v_cmp_gt_u32_e64 s[0:1], s34, v163
	v_cmp_gt_u32_e64 s[40:41], s34, v160
	s_and_b64 s[0:1], vcc, s[0:1]
	s_and_b64 s[40:41], vcc, s[40:41]
	v_cndmask_b32_e64 v114, v231, v114, s[0:1]
	v_cndmask_b32_e64 v110, v231, v110, s[40:41]
	v_max_f32_e32 v160, v110, v110
	v_max_f32_e32 v163, v114, v114
	v_max_f32_e32 v163, v163, v160
	v_or_b32_e32 v160, 6, v161
	v_sub_u32_e32 v160, v147, v160
	v_add_u32_e32 v161, 0x80, v160
	v_add_u32_e32 v160, 0x7f, v160
	v_cmp_gt_u32_e64 s[0:1], s34, v161
	v_cmp_gt_u32_e64 s[40:41], s34, v160
	s_and_b64 s[0:1], vcc, s[0:1]
	s_and_b64 vcc, vcc, s[40:41]
	v_cndmask_b32_e64 v115, v231, v115, s[0:1]
	v_cndmask_b32_e32 v160, v231, v111, vcc
	v_max_f32_e32 v111, v160, v160
	v_max_f32_e32 v161, v115, v115
	v_max_f32_e32 v111, v161, v111
	v_max3_f32 v161, v162, v163, v111
	v_add_u32_e32 v162, s30, v159
	v_sub_u32_e32 v111, v147, v162
	v_add_u32_e32 v163, 0x80, v111
	v_add_u32_e32 v111, 0x7f, v111
	v_cmp_gt_u32_e32 vcc, s33, v162
	v_cmp_gt_u32_e64 s[0:1], s34, v163
	v_cmp_gt_u32_e64 s[40:41], s34, v111
	s_and_b64 s[0:1], vcc, s[0:1]
	s_and_b64 s[40:41], vcc, s[40:41]
	v_cndmask_b32_e64 v104, v231, v104, s[0:1]
	v_cndmask_b32_e64 v100, v231, v100, s[40:41]
	v_max_f32_e32 v111, v100, v100
	v_max_f32_e32 v163, v104, v104
	v_max_f32_e32 v163, v163, v111
	v_or_b32_e32 v111, 2, v162
	v_sub_u32_e32 v111, v147, v111
	v_add_u32_e32 v168, 0x80, v111
	v_add_u32_e32 v111, 0x7f, v111
	v_cmp_gt_u32_e64 s[0:1], s34, v168
	v_cmp_gt_u32_e64 s[40:41], s34, v111
	s_and_b64 s[0:1], vcc, s[0:1]
	s_and_b64 s[40:41], vcc, s[40:41]
	v_cndmask_b32_e64 v105, v231, v105, s[0:1]
	v_cndmask_b32_e64 v111, v231, v101, s[40:41]
	v_max_f32_e32 v101, v111, v111
	v_max_f32_e32 v168, v105, v105
	v_max_f32_e32 v101, v168, v101
	v_max3_f32 v101, v161, v163, v101
	v_or_b32_e32 v161, 4, v162
	v_sub_u32_e32 v161, v147, v161
	v_add_u32_e32 v163, 0x80, v161
	v_add_u32_e32 v161, 0x7f, v161
	v_cmp_gt_u32_e64 s[0:1], s34, v163
	v_cmp_gt_u32_e64 s[40:41], s34, v161
	s_and_b64 s[0:1], vcc, s[0:1]
	s_and_b64 s[40:41], vcc, s[40:41]
	v_cndmask_b32_e64 v106, v231, v106, s[0:1]
	v_cndmask_b32_e64 v102, v231, v102, s[40:41]
	v_max_f32_e32 v161, v102, v102
	v_max_f32_e32 v163, v106, v106
	v_max_f32_e32 v163, v163, v161
	v_or_b32_e32 v161, 6, v162
	v_sub_u32_e32 v161, v147, v161
	v_add_u32_e32 v162, 0x80, v161
	v_add_u32_e32 v161, 0x7f, v161
	v_cmp_gt_u32_e64 s[0:1], s34, v162
	v_cmp_gt_u32_e64 s[40:41], s34, v161
	s_and_b64 s[0:1], vcc, s[0:1]
	s_and_b64 vcc, vcc, s[40:41]
	v_cndmask_b32_e64 v161, v231, v107, s[0:1]
	v_cndmask_b32_e32 v162, v231, v103, vcc
	v_max_f32_e32 v103, v162, v162
	v_max_f32_e32 v107, v161, v161
	v_max_f32_e32 v103, v107, v103
	v_max3_f32 v107, v101, v163, v103
	v_add_u32_e32 v163, s31, v159
	v_sub_u32_e32 v101, v147, v163
	v_add_u32_e32 v103, 0x80, v101
	v_add_u32_e32 v101, 0x7f, v101
	v_cmp_gt_u32_e32 vcc, s33, v163
	v_cmp_gt_u32_e64 s[0:1], s34, v103
	v_cmp_gt_u32_e64 s[40:41], s34, v101
	s_and_b64 s[0:1], vcc, s[0:1]
	s_and_b64 s[40:41], vcc, s[40:41]
	v_cndmask_b32_e64 v101, v231, v96, s[0:1]
	v_cndmask_b32_e64 v92, v231, v92, s[40:41]
	v_max_f32_e32 v96, v92, v92
	v_max_f32_e32 v103, v101, v101
	v_max_f32_e32 v96, v103, v96
	v_or_b32_e32 v103, 2, v163
	v_sub_u32_e32 v103, v147, v103
	v_add_u32_e32 v168, 0x80, v103
	v_add_u32_e32 v103, 0x7f, v103
	v_cmp_gt_u32_e64 s[0:1], s34, v168
	v_cmp_gt_u32_e64 s[40:41], s34, v103
	s_and_b64 s[0:1], vcc, s[0:1]
	s_and_b64 s[40:41], vcc, s[40:41]
	v_cndmask_b32_e64 v97, v231, v97, s[0:1]
	v_cndmask_b32_e64 v103, v231, v93, s[40:41]
	v_max_f32_e32 v93, v103, v103
	v_max_f32_e32 v168, v97, v97
	v_max_f32_e32 v93, v168, v93
	v_max3_f32 v93, v107, v96, v93
	v_or_b32_e32 v96, 4, v163
	v_sub_u32_e32 v96, v147, v96
	v_add_u32_e32 v107, 0x80, v96
	v_add_u32_e32 v96, 0x7f, v96
	v_cmp_gt_u32_e64 s[0:1], s34, v107
	v_cmp_gt_u32_e64 s[40:41], s34, v96
	s_and_b64 s[0:1], vcc, s[0:1]
	s_and_b64 s[40:41], vcc, s[40:41]
	v_cndmask_b32_e64 v98, v231, v98, s[0:1]
	v_cndmask_b32_e64 v107, v231, v94, s[40:41]
	v_max_f32_e32 v94, v107, v107
	v_max_f32_e32 v96, v98, v98
	v_max_f32_e32 v94, v96, v94
	v_or_b32_e32 v96, 6, v163
	v_sub_u32_e32 v96, v147, v96
	v_add_u32_e32 v163, 0x80, v96
	v_add_u32_e32 v96, 0x7f, v96
	v_cmp_gt_u32_e64 s[0:1], s34, v163
	v_cmp_gt_u32_e64 s[40:41], s34, v96
	s_and_b64 s[0:1], vcc, s[0:1]
	s_and_b64 vcc, vcc, s[40:41]
	v_cndmask_b32_e64 v178, v231, v99, s[0:1]
	v_cndmask_b32_e32 v179, v231, v95, vcc
	v_max_f32_e32 v95, v179, v179
	v_max_f32_e32 v96, v178, v178
	v_max_f32_e32 v95, v96, v95
	v_add_u32_e32 v99, s76, v159
	v_max3_f32 v96, v93, v94, v95
	v_sub_u32_e32 v93, v147, v99
	v_add_u32_e32 v94, 0x80, v93
	v_add_u32_e32 v93, 0x7f, v93
	v_cmp_gt_u32_e32 vcc, s33, v99
	v_cmp_gt_u32_e64 s[0:1], s34, v94
	v_cmp_gt_u32_e64 s[40:41], s34, v93
	s_and_b64 s[0:1], vcc, s[0:1]
	s_and_b64 s[40:41], vcc, s[40:41]
	v_cndmask_b32_e64 v93, v231, v88, s[0:1]
	v_cndmask_b32_e64 v94, v231, v84, s[40:41]
	v_max_f32_e32 v84, v94, v94
	v_max_f32_e32 v88, v93, v93
	v_max_f32_e32 v84, v88, v84
	v_or_b32_e32 v88, 2, v99
	v_sub_u32_e32 v88, v147, v88
	v_add_u32_e32 v95, 0x80, v88
	v_add_u32_e32 v88, 0x7f, v88
	v_cmp_gt_u32_e64 s[0:1], s34, v95
	v_cmp_gt_u32_e64 s[40:41], s34, v88
	s_and_b64 s[0:1], vcc, s[0:1]
	s_and_b64 s[40:41], vcc, s[40:41]
	v_cndmask_b32_e64 v95, v231, v89, s[0:1]
	v_cndmask_b32_e64 v163, v231, v85, s[40:41]
	v_max_f32_e32 v85, v163, v163
	v_max_f32_e32 v88, v95, v95
	v_max_f32_e32 v85, v88, v85
	v_max3_f32 v84, v96, v84, v85
	v_or_b32_e32 v85, 4, v99
	v_sub_u32_e32 v85, v147, v85
	v_add_u32_e32 v88, 0x80, v85
	v_add_u32_e32 v85, 0x7f, v85
	v_cmp_gt_u32_e64 s[0:1], s34, v88
	v_cmp_gt_u32_e64 s[40:41], s34, v85
	s_and_b64 s[0:1], vcc, s[0:1]
	s_and_b64 s[40:41], vcc, s[40:41]
	v_cndmask_b32_e64 v176, v231, v90, s[0:1]
	v_cndmask_b32_e64 v177, v231, v86, s[40:41]
	v_max_f32_e32 v85, v177, v177
	v_max_f32_e32 v86, v176, v176
	v_max_f32_e32 v85, v86, v85
	v_or_b32_e32 v86, 6, v99
	v_sub_u32_e32 v86, v147, v86
	v_add_u32_e32 v88, 0x80, v86
	v_add_u32_e32 v86, 0x7f, v86
	v_cmp_gt_u32_e64 s[0:1], s34, v88
	v_cmp_gt_u32_e64 s[40:41], s34, v86
	s_and_b64 s[0:1], vcc, s[0:1]
	s_and_b64 vcc, vcc, s[40:41]
	v_cndmask_b32_e64 v184, v231, v91, s[0:1]
	v_cndmask_b32_e32 v185, v231, v87, vcc
	v_max_f32_e32 v86, v185, v185
	v_max_f32_e32 v87, v184, v184
	v_max_f32_e32 v86, v87, v86
	v_max3_f32 v84, v84, v85, v86
	v_add_u32_e32 v85, s77, v159
	v_sub_u32_e32 v86, v147, v85
	v_add_u32_e32 v87, 0x80, v86
	v_add_u32_e32 v86, 0x7f, v86
	v_cmp_gt_u32_e32 vcc, s33, v85
	v_cmp_gt_u32_e64 s[0:1], s34, v87
	v_cmp_gt_u32_e64 s[40:41], s34, v86
	s_and_b64 s[0:1], vcc, s[0:1]
	s_and_b64 s[40:41], vcc, s[40:41]
	v_cndmask_b32_e64 v99, v231, v80, s[0:1]
	v_cndmask_b32_e64 v159, v231, v76, s[40:41]
	v_max_f32_e32 v76, v159, v159
	v_max_f32_e32 v80, v99, v99
	v_max_f32_e32 v76, v80, v76
	v_or_b32_e32 v80, 2, v85
	v_sub_u32_e32 v80, v147, v80
	v_add_u32_e32 v86, 0x80, v80
	v_add_u32_e32 v80, 0x7f, v80
	v_cmp_gt_u32_e64 s[0:1], s34, v86
	v_cmp_gt_u32_e64 s[40:41], s34, v80
	s_and_b64 s[0:1], vcc, s[0:1]
	s_and_b64 s[40:41], vcc, s[40:41]
	v_cndmask_b32_e64 v180, v231, v81, s[0:1]
	v_cndmask_b32_e64 v181, v231, v77, s[40:41]
	v_max_f32_e32 v77, v181, v181
	v_max_f32_e32 v80, v180, v180
	v_max_f32_e32 v77, v80, v77
	v_max3_f32 v76, v84, v76, v77
	v_or_b32_e32 v77, 4, v85
	v_sub_u32_e32 v77, v147, v77
	v_add_u32_e32 v80, 0x80, v77
	v_add_u32_e32 v77, 0x7f, v77
	v_cmp_gt_u32_e64 s[0:1], s34, v80
	v_cmp_gt_u32_e64 s[40:41], s34, v77
	s_and_b64 s[0:1], vcc, s[0:1]
	s_and_b64 s[40:41], vcc, s[40:41]
	v_cndmask_b32_e64 v182, v231, v82, s[0:1]
	v_cndmask_b32_e64 v183, v231, v78, s[40:41]
	v_max_f32_e32 v77, v183, v183
	v_max_f32_e32 v78, v182, v182
	v_max_f32_e32 v77, v78, v77
	v_or_b32_e32 v78, 6, v85
	v_sub_u32_e32 v78, v147, v78
	v_add_u32_e32 v80, 0x80, v78
	v_add_u32_e32 v78, 0x7f, v78
	v_cmp_gt_u32_e64 s[0:1], s34, v80
	v_cmp_gt_u32_e64 s[40:41], s34, v78
	s_and_b64 s[0:1], vcc, s[0:1]
	s_and_b64 vcc, vcc, s[40:41]
	v_cndmask_b32_e64 v147, v231, v83, s[0:1]
	v_cndmask_b32_e32 v186, v231, v79, vcc
	s_waitcnt lgkmcnt(0)
	v_mfma_f32_16x16x32_bf16 v[64:67], v[68:71], v[60:63], v[64:67]
	v_max_f32_e32 v78, v186, v186
	v_max_f32_e32 v79, v147, v147
	v_max_f32_e32 v78, v79, v78
	v_max3_f32 v76, v76, v77, v78
	v_mov_b32_e32 v69, v3
	s_nop 2
	v_max3_f32 v60, v76, v64, v65
	v_max3_f32 v60, v60, v66, v67
	ds_bpermute_b32 v61, v157, v60
	s_waitcnt lgkmcnt(0)
	v_max_f32_e32 v61, v61, v61
	v_max_f32_e32 v60, v60, v61
	ds_bpermute_b32 v61, v156, v60
	s_waitcnt lgkmcnt(0)
	v_max_f32_e32 v61, v61, v61
	v_max_f32_e32 v96, v60, v61
	v_sub_f32_e32 v60, v150, v96
	v_mul_f32_e32 v60, 0x3fb8aa3b, v60
	v_exp_f32_e32 v76, v60
	v_sub_f32_e32 v60, v148, v96
	v_mul_f32_e32 v60, 0x3fb8aa3b, v60
	v_exp_f32_e32 v77, v60
	v_sub_f32_e32 v60, v154, v96
	v_mul_f32_e32 v60, 0x3fb8aa3b, v60
	v_exp_f32_e32 v62, v60
	v_sub_f32_e32 v60, v151, v96
	v_mul_f32_e32 v60, 0x3fb8aa3b, v60
	v_exp_f32_e32 v68, v60
	v_add_f32_e32 v63, v76, v77
	v_sub_f32_e32 v64, v64, v96
	v_mul_f32_e32 v64, 0x3fb8aa3b, v64
	v_pk_add_f32 v[60:61], v[62:63], v[68:69]
	v_sub_f32_e32 v65, v65, v96
	v_pk_add_f32 v[70:71], v[60:61], v[60:61] op_sel_hi:[0,1]
	v_sub_f32_e32 v60, v152, v96
	v_mul_f32_e32 v60, 0x3fb8aa3b, v60
	v_exp_f32_e32 v63, v60
	v_sub_f32_e32 v60, v149, v96
	v_mul_f32_e32 v60, 0x3fb8aa3b, v60
	v_exp_f32_e32 v69, v60
	v_sub_f32_e32 v60, v155, v96
	v_mul_f32_e32 v60, 0x3fb8aa3b, v60
	v_exp_f32_e32 v72, v60
	v_sub_f32_e32 v60, v153, v96
	v_mul_f32_e32 v60, 0x3fb8aa3b, v60
	v_exp_f32_e32 v70, v60
	v_add_f32_e32 v73, v63, v69
	v_exp_f32_e32 v64, v64
	v_mul_f32_e32 v65, 0x3fb8aa3b, v65
	v_pk_add_f32 v[60:61], v[72:73], v[70:71]
	v_sub_f32_e32 v66, v66, v96
	v_pk_add_f32 v[74:75], v[60:61], v[60:61] op_sel_hi:[0,1]
	v_cvt_pk_bf16_f32 v61, v62, v68
	v_sub_f32_e32 v68, v136, v96
	v_mul_f32_e32 v68, 0x3fb8aa3b, v68
	v_exp_f32_e32 v80, v68
	v_sub_f32_e32 v68, v132, v96
	v_mul_f32_e32 v68, 0x3fb8aa3b, v68
	v_exp_f32_e32 v81, v68
	v_sub_f32_e32 v68, v137, v96
	v_mul_f32_e32 v68, 0x3fb8aa3b, v68
	v_cvt_pk_bf16_f32 v62, v63, v69
	v_cvt_pk_bf16_f32 v63, v72, v70
	v_exp_f32_e32 v70, v68
	v_sub_f32_e32 v68, v133, v96
	v_mul_f32_e32 v68, 0x3fb8aa3b, v68
	v_exp_f32_e32 v74, v68
	v_add_f32_e32 v71, v80, v81
	v_cvt_pk_bf16_f32 v60, v76, v77
	v_exp_f32_e32 v65, v65
	v_pk_add_f32 v[68:69], v[70:71], v[74:75]
	v_mul_f32_e32 v66, 0x3fb8aa3b, v66
	v_pk_add_f32 v[72:73], v[68:69], v[68:69] op_sel_hi:[0,1]
	v_sub_f32_e32 v68, v138, v96
	v_mul_f32_e32 v68, 0x3fb8aa3b, v68
	v_exp_f32_e32 v71, v68
	v_sub_f32_e32 v68, v134, v96
	v_mul_f32_e32 v68, 0x3fb8aa3b, v68
	v_exp_f32_e32 v75, v68
	v_sub_f32_e32 v68, v139, v96
	v_mul_f32_e32 v68, 0x3fb8aa3b, v68
	v_exp_f32_e32 v76, v68
	v_sub_f32_e32 v68, v135, v96
	v_mul_f32_e32 v68, 0x3fb8aa3b, v68
	v_exp_f32_e32 v72, v68
	v_add_f32_e32 v77, v71, v75
	v_sub_f32_e32 v67, v67, v96
	v_exp_f32_e32 v66, v66
	v_pk_add_f32 v[68:69], v[76:77], v[72:73]
	v_mul_f32_e32 v67, 0x3fb8aa3b, v67
	v_pk_add_f32 v[78:79], v[68:69], v[68:69] op_sel_hi:[0,1]
	v_cvt_pk_bf16_f32 v69, v70, v74
	v_cvt_pk_bf16_f32 v70, v71, v75
	v_cvt_pk_bf16_f32 v71, v76, v72
	v_sub_f32_e32 v72, v128, v96
	v_mul_f32_e32 v72, 0x3fb8aa3b, v72
	v_exp_f32_e32 v84, v72
	v_sub_f32_e32 v72, v124, v96
	v_mul_f32_e32 v72, 0x3fb8aa3b, v72
	v_exp_f32_e32 v85, v72
	v_sub_f32_e32 v72, v129, v96
	v_mul_f32_e32 v72, 0x3fb8aa3b, v72
	v_exp_f32_e32 v74, v72
	v_sub_f32_e32 v72, v125, v96
	v_mul_f32_e32 v72, 0x3fb8aa3b, v72
	v_exp_f32_e32 v78, v72
	v_add_f32_e32 v75, v84, v85
	v_cvt_pk_bf16_f32 v68, v80, v81
	v_exp_f32_e32 v67, v67
	v_pk_add_f32 v[72:73], v[74:75], v[78:79]
	s_nop 0
	v_pk_add_f32 v[76:77], v[72:73], v[72:73] op_sel_hi:[0,1]
	v_sub_f32_e32 v72, v130, v96
	v_mul_f32_e32 v72, 0x3fb8aa3b, v72
	v_exp_f32_e32 v75, v72
	v_sub_f32_e32 v72, v126, v96
	v_mul_f32_e32 v72, 0x3fb8aa3b, v72
	v_exp_f32_e32 v79, v72
	v_sub_f32_e32 v72, v131, v96
	v_mul_f32_e32 v72, 0x3fb8aa3b, v72
	v_exp_f32_e32 v80, v72
	v_sub_f32_e32 v72, v127, v96
	v_mul_f32_e32 v72, 0x3fb8aa3b, v72
	v_exp_f32_e32 v76, v72
	v_add_f32_e32 v81, v75, v79
	v_pk_add_f32 v[72:73], v[80:81], v[76:77]
	s_nop 0
	v_pk_add_f32 v[82:83], v[72:73], v[72:73] op_sel_hi:[0,1]
	v_cvt_pk_bf16_f32 v73, v74, v78
	v_cvt_pk_bf16_f32 v74, v75, v79
	v_cvt_pk_bf16_f32 v75, v80, v76
	v_sub_f32_e32 v76, v120, v96
	v_mul_f32_e32 v76, 0x3fb8aa3b, v76
	v_exp_f32_e32 v88, v76
	v_sub_f32_e32 v76, v116, v96
	v_mul_f32_e32 v76, 0x3fb8aa3b, v76
	v_exp_f32_e32 v89, v76
	v_sub_f32_e32 v76, v121, v96
	v_mul_f32_e32 v76, 0x3fb8aa3b, v76
	v_exp_f32_e32 v78, v76
	v_sub_f32_e32 v76, v117, v96
	v_mul_f32_e32 v76, 0x3fb8aa3b, v76
	v_exp_f32_e32 v82, v76
	v_add_f32_e32 v79, v88, v89
	v_cvt_pk_bf16_f32 v72, v84, v85
	v_pk_add_f32 v[76:77], v[78:79], v[82:83]
	s_nop 0
	v_pk_add_f32 v[80:81], v[76:77], v[76:77] op_sel_hi:[0,1]
	v_sub_f32_e32 v76, v122, v96
	v_mul_f32_e32 v76, 0x3fb8aa3b, v76
	v_exp_f32_e32 v79, v76
	v_sub_f32_e32 v76, v118, v96
	v_mul_f32_e32 v76, 0x3fb8aa3b, v76
	v_exp_f32_e32 v83, v76
	v_sub_f32_e32 v76, v123, v96
	v_mul_f32_e32 v76, 0x3fb8aa3b, v76
	v_exp_f32_e32 v84, v76
	v_sub_f32_e32 v76, v119, v96
	v_mul_f32_e32 v76, 0x3fb8aa3b, v76
	v_exp_f32_e32 v80, v76
	v_add_f32_e32 v85, v79, v83
	v_pk_add_f32 v[76:77], v[84:85], v[80:81]
	s_nop 0
	v_pk_add_f32 v[86:87], v[76:77], v[76:77] op_sel_hi:[0,1]
	v_cvt_pk_bf16_f32 v77, v78, v82
	v_cvt_pk_bf16_f32 v78, v79, v83
	v_cvt_pk_bf16_f32 v79, v84, v80
	v_sub_f32_e32 v80, v112, v96
	v_mul_f32_e32 v80, 0x3fb8aa3b, v80
	v_exp_f32_e32 v112, v80
	v_sub_f32_e32 v80, v108, v96
	v_mul_f32_e32 v80, 0x3fb8aa3b, v80
	v_exp_f32_e32 v108, v80
	v_sub_f32_e32 v80, v113, v96
	v_mul_f32_e32 v80, 0x3fb8aa3b, v80
	v_exp_f32_e32 v82, v80
	v_sub_f32_e32 v80, v109, v96
	v_mul_f32_e32 v80, 0x3fb8aa3b, v80
	v_exp_f32_e32 v86, v80
	v_add_f32_e32 v83, v112, v108
	v_cvt_pk_bf16_f32 v76, v88, v89
	v_pk_add_f32 v[80:81], v[82:83], v[86:87]
	s_nop 0
	v_pk_add_f32 v[84:85], v[80:81], v[80:81] op_sel_hi:[0,1]
	v_sub_f32_e32 v80, v114, v96
	v_mul_f32_e32 v80, 0x3fb8aa3b, v80
	v_exp_f32_e32 v83, v80
	v_sub_f32_e32 v80, v110, v96
	v_mul_f32_e32 v80, 0x3fb8aa3b, v80
	v_exp_f32_e32 v87, v80
	v_sub_f32_e32 v80, v115, v96
	v_mul_f32_e32 v80, 0x3fb8aa3b, v80
	v_exp_f32_e32 v88, v80
	v_sub_f32_e32 v80, v160, v96
	v_mul_f32_e32 v80, 0x3fb8aa3b, v80
	v_exp_f32_e32 v84, v80
	v_add_f32_e32 v89, v83, v87
	v_pk_add_f32 v[80:81], v[88:89], v[84:85]
	s_nop 0
	v_pk_add_f32 v[90:91], v[80:81], v[80:81] op_sel_hi:[0,1]
	v_cvt_pk_bf16_f32 v81, v82, v86
	v_cvt_pk_bf16_f32 v82, v83, v87
	v_cvt_pk_bf16_f32 v83, v88, v84
	v_sub_f32_e32 v84, v104, v96
	v_mul_f32_e32 v84, 0x3fb8aa3b, v84
	v_exp_f32_e32 v110, v84
	v_sub_f32_e32 v84, v100, v96
	v_mul_f32_e32 v84, 0x3fb8aa3b, v84
	v_exp_f32_e32 v100, v84
	v_sub_f32_e32 v84, v105, v96
	v_mul_f32_e32 v84, 0x3fb8aa3b, v84
	v_exp_f32_e32 v86, v84
	v_sub_f32_e32 v84, v111, v96
	v_mul_f32_e32 v84, 0x3fb8aa3b, v84
	v_exp_f32_e32 v90, v84
	v_add_f32_e32 v87, v110, v100
	v_cvt_pk_bf16_f32 v80, v112, v108
	v_pk_add_f32 v[84:85], v[86:87], v[90:91]
	s_nop 0
	v_pk_add_f32 v[88:89], v[84:85], v[84:85] op_sel_hi:[0,1]
	v_sub_f32_e32 v84, v106, v96
	v_mul_f32_e32 v84, 0x3fb8aa3b, v84
	v_exp_f32_e32 v87, v84
	v_sub_f32_e32 v84, v102, v96
	v_mul_f32_e32 v84, 0x3fb8aa3b, v84
	v_exp_f32_e32 v91, v84
	v_sub_f32_e32 v84, v161, v96
	v_mul_f32_e32 v84, 0x3fb8aa3b, v84
	v_exp_f32_e32 v104, v84
	v_sub_f32_e32 v84, v162, v96
	v_mul_f32_e32 v84, 0x3fb8aa3b, v84
	v_exp_f32_e32 v88, v84
	v_add_f32_e32 v105, v87, v91
	v_pk_add_f32 v[84:85], v[104:105], v[88:89]
	s_nop 0
	v_pk_add_f32 v[108:109], v[84:85], v[84:85] op_sel_hi:[0,1]
	v_cvt_pk_bf16_f32 v85, v86, v90
	v_cvt_pk_bf16_f32 v86, v87, v91
	v_cvt_pk_bf16_f32 v87, v104, v88
	v_sub_f32_e32 v88, v101, v96
	v_mul_f32_e32 v88, 0x3fb8aa3b, v88
	v_exp_f32_e32 v106, v88
	v_sub_f32_e32 v88, v92, v96
	v_mul_f32_e32 v88, 0x3fb8aa3b, v88
	v_exp_f32_e32 v92, v88
	v_sub_f32_e32 v88, v97, v96
	v_mul_f32_e32 v88, 0x3fb8aa3b, v88
	v_exp_f32_e32 v90, v88
	v_sub_f32_e32 v88, v103, v96
	v_mul_f32_e32 v88, 0x3fb8aa3b, v88
	v_exp_f32_e32 v108, v88
	v_add_f32_e32 v91, v106, v92
	v_cvt_pk_bf16_f32 v84, v110, v100
	v_pk_add_f32 v[88:89], v[90:91], v[108:109]
	s_nop 0
	v_pk_add_f32 v[100:101], v[88:89], v[88:89] op_sel_hi:[0,1]
	v_sub_f32_e32 v88, v98, v96
	v_mul_f32_e32 v88, 0x3fb8aa3b, v88
	v_exp_f32_e32 v91, v88
	v_sub_f32_e32 v88, v107, v96
	v_mul_f32_e32 v88, 0x3fb8aa3b, v88
	v_exp_f32_e32 v97, v88
	v_sub_f32_e32 v88, v178, v96
	v_mul_f32_e32 v88, 0x3fb8aa3b, v88
	v_exp_f32_e32 v102, v88
	v_sub_f32_e32 v88, v179, v96
	v_mul_f32_e32 v88, 0x3fb8aa3b, v88
	v_exp_f32_e32 v100, v88
	v_add_f32_e32 v103, v91, v97
	v_pk_add_f32 v[88:89], v[102:103], v[100:101]
	s_nop 0
	v_pk_add_f32 v[104:105], v[88:89], v[88:89] op_sel_hi:[0,1]
	v_cvt_pk_bf16_f32 v88, v106, v92
	v_sub_f32_e32 v92, v93, v96
	v_mul_f32_e32 v92, 0x3fb8aa3b, v92
	v_cvt_pk_bf16_f32 v89, v90, v108
	v_cvt_pk_bf16_f32 v90, v91, v97
	v_exp_f32_e32 v97, v92
	v_sub_f32_e32 v92, v94, v96
	v_mul_f32_e32 v92, 0x3fb8aa3b, v92
	v_exp_f32_e32 v94, v92
	v_sub_f32_e32 v92, v95, v96
	v_mul_f32_e32 v92, 0x3fb8aa3b, v92
	v_cvt_pk_bf16_f32 v91, v102, v100
	v_exp_f32_e32 v100, v92
	v_sub_f32_e32 v92, v163, v96
	v_mul_f32_e32 v92, 0x3fb8aa3b, v92
	v_exp_f32_e32 v104, v92
	v_add_f32_e32 v101, v97, v94
	v_pk_add_f32 v[92:93], v[100:101], v[104:105]
	s_nop 0
	v_pk_add_f32 v[102:103], v[92:93], v[92:93] op_sel_hi:[0,1]
	v_sub_f32_e32 v92, v176, v96
	v_mul_f32_e32 v92, 0x3fb8aa3b, v92
	v_exp_f32_e32 v95, v92
	v_sub_f32_e32 v92, v177, v96
	v_mul_f32_e32 v92, 0x3fb8aa3b, v92
	v_exp_f32_e32 v98, v92
	v_sub_f32_e32 v92, v184, v96
	v_mul_f32_e32 v92, 0x3fb8aa3b, v92
	v_exp_f32_e32 v106, v92
	v_sub_f32_e32 v92, v185, v96
	v_mul_f32_e32 v92, 0x3fb8aa3b, v92
	v_exp_f32_e32 v102, v92
	v_add_f32_e32 v107, v95, v98
	v_pk_add_f32 v[92:93], v[106:107], v[102:103]
	s_nop 0
	v_pk_add_f32 v[108:109], v[92:93], v[92:93] op_sel_hi:[0,1]
	v_cvt_pk_bf16_f32 v92, v97, v94
	v_cvt_pk_bf16_f32 v94, v95, v98
	v_sub_f32_e32 v98, v159, v96
	v_mul_f32_e32 v98, 0x3fb8aa3b, v98
	v_cvt_pk_bf16_f32 v95, v106, v102
	v_exp_f32_e32 v106, v98
	v_sub_f32_e32 v98, v180, v96
	v_sub_f32_e32 v97, v99, v96
	v_mul_f32_e32 v98, 0x3fb8aa3b, v98
	v_cvt_pk_bf16_f32 v93, v100, v104
	v_mul_f32_e32 v97, 0x3fb8aa3b, v97
	v_exp_f32_e32 v100, v98
	v_sub_f32_e32 v98, v181, v96
	v_exp_f32_e32 v97, v97
	v_mul_f32_e32 v98, 0x3fb8aa3b, v98
	v_exp_f32_e32 v108, v98
	v_add_f32_e32 v101, v97, v106
	v_pk_add_f32 v[98:99], v[100:101], v[108:109]
	s_nop 0
	v_pk_add_f32 v[102:103], v[98:99], v[98:99] op_sel_hi:[0,1]
	v_sub_f32_e32 v98, v182, v96
	v_mul_f32_e32 v98, 0x3fb8aa3b, v98
	v_exp_f32_e32 v101, v98
	v_sub_f32_e32 v98, v183, v96
	v_mul_f32_e32 v98, 0x3fb8aa3b, v98
	v_exp_f32_e32 v107, v98
	v_sub_f32_e32 v98, v147, v96
	v_mul_f32_e32 v98, 0x3fb8aa3b, v98
	v_exp_f32_e32 v104, v98
	v_sub_f32_e32 v98, v186, v96
	v_mul_f32_e32 v98, 0x3fb8aa3b, v98
	v_exp_f32_e32 v102, v98
	v_add_f32_e32 v105, v101, v107
	v_sub_f32_e32 v96, v146, v96
	v_mul_f32_e32 v96, 0x3fb8aa3b, v96
	v_pk_add_f32 v[98:99], v[104:105], v[102:103]
	v_exp_f32_e32 v96, v96
	v_add_f32_e32 v103, v98, v99
	v_cvt_pk_bf16_f32 v98, v97, v106
	v_add_f32_e32 v97, v64, v103
	v_add_f32_e32 v97, v65, v97
	v_add_f32_e32 v97, v66, v97
	v_add_f32_e32 v97, v67, v97
	v_cvt_pk_bf16_f32 v64, v64, v65
	v_cvt_pk_bf16_f32 v65, v66, v67
	ds_bpermute_b32 v66, v157, v97
	v_cvt_pk_bf16_f32 v99, v100, v108
	v_cvt_pk_bf16_f32 v100, v101, v107
	v_cvt_pk_bf16_f32 v101, v104, v102
	s_waitcnt lgkmcnt(0)
	v_add_f32_e32 v66, v97, v66
	ds_bpermute_b32 v67, v156, v66
	v_mad_u32_u24 v138, v143, s9, v158
	v_add3_u32 v139, v138, v145, s78
	ds_read_b128 v[102:105], v139
	ds_read_b128 v[106:109], v139 offset:12800
	ds_read_b128 v[110:113], v139 offset:25600
	ds_read_b128 v[114:117], v139 offset:38400
	ds_read_b128 v[118:121], v139 offset:64
	ds_read_b128 v[122:125], v139 offset:12864
	ds_read_b128 v[126:129], v139 offset:25664
	ds_read_b128 v[130:133], v139 offset:38464
	ds_read_b128 v[134:137], v139 offset:128
	ds_read_b128 v[146:149], v139 offset:12928
	ds_read_b128 v[150:153], v139 offset:25728
	ds_read_b128 v[158:161], v139 offset:38528
	s_waitcnt lgkmcnt(12)
	v_add_f32_e32 v97, v66, v67
	s_waitcnt lgkmcnt(11)
	v_mfma_f32_16x16x32_bf16 v[102:105], v[102:105], v[60:63], 0
	s_waitcnt lgkmcnt(10)
	v_mfma_f32_16x16x32_bf16 v[106:109], v[106:109], v[60:63], 0
	s_waitcnt lgkmcnt(9)
	v_mfma_f32_16x16x32_bf16 v[110:113], v[110:113], v[60:63], 0
	s_waitcnt lgkmcnt(8)
	v_mfma_f32_16x16x32_bf16 v[60:63], v[114:117], v[60:63], 0
	s_waitcnt lgkmcnt(7)
	v_mfma_f32_16x16x32_bf16 v[102:105], v[118:121], v[68:71], v[102:105]
	s_waitcnt lgkmcnt(6)
	v_mfma_f32_16x16x32_bf16 v[106:109], v[122:125], v[68:71], v[106:109]
	s_waitcnt lgkmcnt(5)
	v_mfma_f32_16x16x32_bf16 v[110:113], v[126:129], v[68:71], v[110:113]
	s_waitcnt lgkmcnt(4)
	v_mfma_f32_16x16x32_bf16 v[60:63], v[130:133], v[68:71], v[60:63]
	s_waitcnt lgkmcnt(3)
	v_mfma_f32_16x16x32_bf16 v[66:69], v[134:137], v[72:75], v[102:105]
	s_waitcnt lgkmcnt(2)
	v_mfma_f32_16x16x32_bf16 v[102:105], v[146:149], v[72:75], v[106:109]
	s_waitcnt lgkmcnt(1)
	v_mfma_f32_16x16x32_bf16 v[106:109], v[150:153], v[72:75], v[110:113]
	s_waitcnt lgkmcnt(0)
	v_mfma_f32_16x16x32_bf16 v[60:63], v[158:161], v[72:75], v[60:63]
	ds_read_b128 v[70:73], v139 offset:12992
	ds_read_b128 v[110:113], v139 offset:13056
	ds_read_b128 v[114:117], v139 offset:38592
	ds_read_b128 v[118:121], v139 offset:38656
	ds_read_b128 v[122:125], v139 offset:256
	ds_read_b128 v[126:129], v139 offset:320
	ds_read_b128 v[130:133], v139 offset:25792
	ds_read_b128 v[134:137], v139 offset:13120
	ds_read_b128 v[146:149], v139 offset:25856
	ds_read_b128 v[150:153], v139 offset:25920
	ds_read_b128 v[158:161], v139 offset:192
	ds_read_b128 v[176:179], v139 offset:38720
	s_waitcnt lgkmcnt(1)
	v_mfma_f32_16x16x32_bf16 v[66:69], v[158:161], v[76:79], v[66:69]
	v_mfma_f32_16x16x32_bf16 v[70:73], v[70:73], v[76:79], v[102:105]
	v_mfma_f32_16x16x32_bf16 v[102:105], v[130:133], v[76:79], v[106:109]
	v_mfma_f32_16x16x32_bf16 v[60:63], v[114:117], v[76:79], v[60:63]
	v_mfma_f32_16x16x32_bf16 v[66:69], v[122:125], v[80:83], v[66:69]
	v_mfma_f32_16x16x32_bf16 v[70:73], v[110:113], v[80:83], v[70:73]
	v_mfma_f32_16x16x32_bf16 v[74:77], v[146:149], v[80:83], v[102:105]
	v_mfma_f32_16x16x32_bf16 v[60:63], v[118:121], v[80:83], v[60:63]
	v_mfma_f32_16x16x32_bf16 v[66:69], v[126:129], v[84:87], v[66:69]
	v_mfma_f32_16x16x32_bf16 v[70:73], v[134:137], v[84:87], v[70:73]
	v_mfma_f32_16x16x32_bf16 v[74:77], v[150:153], v[84:87], v[74:77]
	s_waitcnt lgkmcnt(0)
	v_mfma_f32_16x16x32_bf16 v[60:63], v[176:179], v[84:87], v[60:63]
	ds_read_b128 v[78:81], v139 offset:13184
	ds_read_b128 v[82:85], v139 offset:13248
	ds_read_b128 v[102:105], v139 offset:38784
	ds_read_b128 v[106:109], v139 offset:38848
	ds_read_b128 v[110:113], v139 offset:448
	ds_read_b128 v[114:117], v139 offset:512
	ds_read_b128 v[118:121], v139 offset:25984
	ds_read_b128 v[122:125], v139 offset:13312
	ds_read_b128 v[126:129], v139 offset:26048
	ds_read_b128 v[130:133], v139 offset:26112
	ds_read_b128 v[134:137], v139 offset:384
	ds_read_b128 v[146:149], v139 offset:38912
	s_waitcnt lgkmcnt(1)
	v_mfma_f32_16x16x32_bf16 v[66:69], v[134:137], v[88:91], v[66:69]
	v_mfma_f32_16x16x32_bf16 v[70:73], v[78:81], v[88:91], v[70:73]
	v_mfma_f32_16x16x32_bf16 v[74:77], v[118:121], v[88:91], v[74:77]
	v_mfma_f32_16x16x32_bf16 v[60:63], v[102:105], v[88:91], v[60:63]
	v_mfma_f32_16x16x32_bf16 v[66:69], v[110:113], v[92:95], v[66:69]
	v_mfma_f32_16x16x32_bf16 v[70:73], v[82:85], v[92:95], v[70:73]
	v_mfma_f32_16x16x32_bf16 v[74:77], v[126:129], v[92:95], v[74:77]
	v_mfma_f32_16x16x32_bf16 v[60:63], v[106:109], v[92:95], v[60:63]
	v_mfma_f32_16x16x32_bf16 v[78:81], v[114:117], v[98:101], v[66:69]
	v_mfma_f32_16x16x32_bf16 v[68:71], v[122:125], v[98:101], v[70:73]
	v_mfma_f32_16x16x32_bf16 v[72:75], v[130:133], v[98:101], v[74:77]
	s_waitcnt lgkmcnt(0)
	v_mfma_f32_16x16x32_bf16 v[60:63], v[146:149], v[98:101], v[60:63]
	s_nop 1
	v_add_u32_e32 v76, v138, v144
	v_add_u32_e32 v90, 0x100, v76
	ds_read2st64_b64 v[82:85], v90 offset0:1 offset1:26
	v_mov_b32_e32 v88, v3
	v_mov_b32_e32 v89, v3
	v_mov_b32_e32 v66, v3
	v_mov_b32_e32 v67, v3
	s_waitcnt lgkmcnt(0)
	v_mov_b32_e32 v86, v82
	v_mov_b32_e32 v87, v83
	v_mov_b32_e32 v82, v3
	v_mov_b32_e32 v83, v3
	v_mad_i64_i32 v[0:1], s[4:5], v140, s43, v[0:1]
	v_mfma_f32_16x16x32_bf16 v[76:79], v[86:89], v[64:67], v[78:81]
	v_mov_b32_e32 v86, v3
	v_mov_b32_e32 v87, v3
	s_movk_i32 s48, 0xc00
	v_mov_b32_e32 v80, v84
	v_mov_b32_e32 v81, v85
	s_nop 1
	v_mfma_f32_16x16x32_bf16 v[68:71], v[80:83], v[64:67], v[68:71]
	ds_read2st64_b64 v[80:83], v90 offset0:51 offset1:76
	s_waitcnt lgkmcnt(0)
	v_mov_b32_e32 v84, v80
	v_mov_b32_e32 v85, v81
	v_mov_b32_e32 v80, v82
	v_mov_b32_e32 v81, v83
	v_mov_b32_e32 v82, v3
	v_mov_b32_e32 v83, v3
	v_mfma_f32_16x16x32_bf16 v[72:75], v[84:87], v[64:67], v[72:75]
	s_nop 0
	v_mfma_f32_16x16x32_bf16 v[60:63], v[80:83], v[64:67], v[60:63]
	v_add_f32_e32 v64, v96, v97
	v_div_scale_f32 v65, s[0:1], v64, v64, 1.0
	v_rcp_f32_e32 v66, v65
	s_or_b32 s0, s74, 0xc0
	s_ashr_i32 s1, s0, 31
	v_lshl_add_u64 v[0:1], s[0:1], 1, v[0:1]
	v_fma_f32 v67, -v65, v66, 1.0
	v_fmac_f32_e32 v66, v67, v66
	v_div_scale_f32 v67, vcc, 1.0, v64, 1.0
	v_mul_f32_e32 v80, v67, v66
	v_fma_f32 v81, -v65, v80, v67
	v_fmac_f32_e32 v80, v81, v66
	v_fma_f32 v65, -v65, v80, v67
	v_div_fmas_f32 v65, v65, v66, v80
	v_div_fixup_f32 v80, v65, v64, 1.0
	v_and_b32_e32 v81, 16, v141
	v_lshlrev_b32_e32 v64, 2, v142
	v_and_b32_e32 v82, -8, v64
	v_pk_mul_f32 v[66:67], v[78:79], v[80:81] op_sel_hi:[1,0]
	v_pk_mul_f32 v[64:65], v[76:77], v[80:81] op_sel_hi:[1,0]
	v_pk_mul_f32 v[68:69], v[68:69], v[80:81] op_sel_hi:[1,0]
	v_pk_mul_f32 v[70:71], v[70:71], v[80:81] op_sel_hi:[1,0]
	v_cvt_pk_bf16_f32 v64, v64, v65
	v_cvt_pk_bf16_f32 v65, v66, v67
	v_cvt_pk_bf16_f32 v66, v68, v69
	v_lshlrev_b32_e32 v68, 1, v81
	v_mov_b32_e32 v69, v3
	v_ashrrev_i32_e32 v83, 31, v82
	v_cvt_pk_bf16_f32 v67, v70, v71
	v_lshl_add_u64 v[0:1], v[0:1], 0, v[68:69]
	v_permlane16_swap_b32_e32 v64, v66
	v_permlane16_swap_b32_e32 v65, v67
	v_lshl_add_u64 v[0:1], v[82:83], 1, v[0:1]
	s_cmp_eq_u32 s81, 0
	global_store_dwordx4 v[0:1], v[64:67], off offset:2048
	v_pk_mul_f32 v[68:69], v[80:81], v[62:63] op_sel_hi:[0,1]
	v_pk_mul_f32 v[62:63], v[80:81], v[60:61] op_sel_hi:[0,1]
	v_pk_mul_f32 v[64:65], v[74:75], v[80:81] op_sel_hi:[1,0]
	v_pk_mul_f32 v[66:67], v[72:73], v[80:81] op_sel_hi:[1,0]
	s_cselect_b64 s[0:1], -1, 0
	v_cvt_pk_bf16_f32 v60, v66, v67
	v_cvt_pk_bf16_f32 v61, v64, v65
	v_cvt_pk_bf16_f32 v62, v62, v63
	v_cvt_pk_bf16_f32 v63, v68, v69
	s_and_b64 s[0:1], s[0:1], s[10:11]
	v_permlane16_swap_b32_e32 v60, v62
	v_permlane16_swap_b32_e32 v61, v63
	s_andn2_b64 vcc, exec, s[0:1]
	global_store_dwordx4 v[0:1], v[60:63], off offset:2112
	s_cbranch_vccnz .LBB0_410
	s_add_i32 s0, s42, s6
	v_readlane_b32 s4, v252, 24
	s_lshl_b32 s0, s0, 6
	v_lshl_or_b32 v0, s80, 14, v175
	v_mov_b32_e32 v1, v3
	v_readlane_b32 s5, v252, 25
	s_ashr_i32 s1, s0, 31
	s_lshl_b64 s[46:47], s[0:1], 1
	v_lshl_add_u64 v[0:1], s[4:5], 0, v[0:1]
	v_lshl_add_u64 v[0:1], v[0:1], 0, s[46:47]
	v_lshl_add_u64 v[0:1], v[0:1], 0, v[2:3]
	s_mov_b64 s[0:1], 0x1000000
	v_lshl_add_u64 v[60:61], v[0:1], 0, s[0:1]
	v_add_co_u32_e32 v0, vcc, 0x1000000, v0
	v_mov_b32_e32 v140, v173
	s_nop 0
	v_addc_co_u32_e32 v1, vcc, 0, v1, vcc
	global_load_dwordx4 v[64:67], v[0:1], off
	s_nop 0
	global_load_dwordx4 v[60:63], v[60:61], off offset:64
	s_nop 0
	v_lshlrev_b32_e32 v0, 1, v140
	v_and_b32_e32 v0, 30, v0
	v_mul_u32_u24_e32 v0, 0xd0, v0
	v_and_b32_e32 v144, -16, v140
	v_add3_u32 v0, 0, v0, v144
	ds_read_b128 v[68:71], v0
	ds_read_b128 v[72:75], v0 offset:64
	ds_read_b128 v[76:79], v0 offset:208
	ds_read_b128 v[80:83], v0 offset:272
	ds_read_b128 v[84:87], v0 offset:6656
	ds_read_b128 v[88:91], v0 offset:6720
	ds_read_b128 v[92:95], v0 offset:6864
	ds_read_b128 v[96:99], v0 offset:6928
	ds_read_b128 v[100:103], v0 offset:13312
	ds_read_b128 v[104:107], v0 offset:13376
	ds_read_b128 v[108:111], v0 offset:13520
	ds_read_b128 v[112:115], v0 offset:13584
	v_and_b32_e32 v142, 15, v140
	v_ashrrev_i32_e32 v141, 4, v140
	s_waitcnt vmcnt(1) lgkmcnt(11)
	v_mfma_f32_16x16x32_bf16 v[68:71], v[68:71], v[64:67], 0
	s_waitcnt vmcnt(0) lgkmcnt(10)
	v_mfma_f32_16x16x32_bf16 v[158:161], v[72:75], v[60:63], v[68:71]
	s_waitcnt lgkmcnt(9)
	v_mfma_f32_16x16x32_bf16 v[68:71], v[76:79], v[64:67], 0
	s_waitcnt lgkmcnt(8)
	v_mfma_f32_16x16x32_bf16 v[176:179], v[80:83], v[60:63], v[68:71]
	s_waitcnt lgkmcnt(7)
	v_mfma_f32_16x16x32_bf16 v[68:71], v[84:87], v[64:67], 0
	s_waitcnt lgkmcnt(6)
	v_mfma_f32_16x16x32_bf16 v[136:139], v[88:91], v[60:63], v[68:71]
	s_waitcnt lgkmcnt(5)
	v_mfma_f32_16x16x32_bf16 v[68:71], v[92:95], v[64:67], 0
	s_waitcnt lgkmcnt(4)
	v_mfma_f32_16x16x32_bf16 v[132:135], v[96:99], v[60:63], v[68:71]
	s_waitcnt lgkmcnt(3)
	v_mfma_f32_16x16x32_bf16 v[68:71], v[100:103], v[64:67], 0
	s_waitcnt lgkmcnt(2)
	v_mfma_f32_16x16x32_bf16 v[128:131], v[104:107], v[60:63], v[68:71]
	s_waitcnt lgkmcnt(1)
	v_mfma_f32_16x16x32_bf16 v[68:71], v[108:111], v[64:67], 0
	s_waitcnt lgkmcnt(0)
	v_mfma_f32_16x16x32_bf16 v[124:127], v[112:115], v[60:63], v[68:71]
	s_nop 5
	ds_read_b128 v[68:71], v0 offset:19968
	ds_read_b128 v[72:75], v0 offset:20032
	ds_read_b128 v[76:79], v0 offset:20176
	ds_read_b128 v[80:83], v0 offset:20240
	ds_read_b128 v[84:87], v0 offset:26624
	ds_read_b128 v[88:91], v0 offset:26688
	ds_read_b128 v[92:95], v0 offset:26832
	ds_read_b128 v[96:99], v0 offset:26896
	ds_read_b128 v[100:103], v0 offset:33280
	ds_read_b128 v[104:107], v0 offset:33344
	ds_read_b128 v[146:149], v0 offset:33488
	ds_read_b128 v[150:153], v0 offset:33552
	s_waitcnt lgkmcnt(11)
	v_mfma_f32_16x16x32_bf16 v[68:71], v[68:71], v[64:67], 0
	s_waitcnt lgkmcnt(10)
	v_mfma_f32_16x16x32_bf16 v[120:123], v[72:75], v[60:63], v[68:71]
	s_waitcnt lgkmcnt(9)
	v_mfma_f32_16x16x32_bf16 v[68:71], v[76:79], v[64:67], 0
	s_waitcnt lgkmcnt(8)
	v_mfma_f32_16x16x32_bf16 v[116:119], v[80:83], v[60:63], v[68:71]
	s_waitcnt lgkmcnt(7)
	v_mfma_f32_16x16x32_bf16 v[68:71], v[84:87], v[64:67], 0
	s_waitcnt lgkmcnt(6)
	v_mfma_f32_16x16x32_bf16 v[112:115], v[88:91], v[60:63], v[68:71]
	s_waitcnt lgkmcnt(5)
	v_mfma_f32_16x16x32_bf16 v[68:71], v[92:95], v[64:67], 0
	s_waitcnt lgkmcnt(4)
	v_mfma_f32_16x16x32_bf16 v[108:111], v[96:99], v[60:63], v[68:71]
	s_waitcnt lgkmcnt(3)
	v_mfma_f32_16x16x32_bf16 v[68:71], v[100:103], v[64:67], 0
	s_waitcnt lgkmcnt(2)
	v_mfma_f32_16x16x32_bf16 v[104:107], v[104:107], v[60:63], v[68:71]
	s_waitcnt lgkmcnt(1)
	v_mfma_f32_16x16x32_bf16 v[68:71], v[146:149], v[64:67], 0
	s_waitcnt lgkmcnt(0)
	v_mfma_f32_16x16x32_bf16 v[100:103], v[150:153], v[60:63], v[68:71]
	s_nop 5
	ds_read_b128 v[68:71], v0 offset:39936
	ds_read_b128 v[72:75], v0 offset:40000
	ds_read_b128 v[76:79], v0 offset:40144
	ds_read_b128 v[80:83], v0 offset:40208
	ds_read_b128 v[84:87], v0 offset:46592
	ds_read_b128 v[88:91], v0 offset:46656
	ds_read_b128 v[146:149], v0 offset:46800
	ds_read_b128 v[150:153], v0 offset:46864
	ds_read_b128 v[180:183], v0 offset:53248
	ds_read_b128 v[184:187], v0 offset:53312
	ds_read_b128 v[188:191], v0 offset:53456
	ds_read_b128 v[192:195], v0 offset:53520
	s_waitcnt lgkmcnt(11)
	v_mfma_f32_16x16x32_bf16 v[68:71], v[68:71], v[64:67], 0
	s_waitcnt lgkmcnt(10)
	v_mfma_f32_16x16x32_bf16 v[96:99], v[72:75], v[60:63], v[68:71]
	s_waitcnt lgkmcnt(9)
	v_mfma_f32_16x16x32_bf16 v[68:71], v[76:79], v[64:67], 0
	s_waitcnt lgkmcnt(8)
	v_mfma_f32_16x16x32_bf16 v[92:95], v[80:83], v[60:63], v[68:71]
	s_waitcnt lgkmcnt(7)
	v_mfma_f32_16x16x32_bf16 v[68:71], v[84:87], v[64:67], 0
	s_waitcnt lgkmcnt(6)
	v_mfma_f32_16x16x32_bf16 v[88:91], v[88:91], v[60:63], v[68:71]
	s_waitcnt lgkmcnt(5)
	v_mfma_f32_16x16x32_bf16 v[68:71], v[146:149], v[64:67], 0
	s_waitcnt lgkmcnt(4)
	v_mfma_f32_16x16x32_bf16 v[84:87], v[150:153], v[60:63], v[68:71]
	s_waitcnt lgkmcnt(3)
	v_mfma_f32_16x16x32_bf16 v[68:71], v[180:183], v[64:67], 0
	s_waitcnt lgkmcnt(2)
	v_mfma_f32_16x16x32_bf16 v[80:83], v[184:187], v[60:63], v[68:71]
	s_waitcnt lgkmcnt(1)
	v_mfma_f32_16x16x32_bf16 v[68:71], v[188:191], v[64:67], 0
	s_waitcnt lgkmcnt(0)
	v_mfma_f32_16x16x32_bf16 v[76:79], v[192:195], v[60:63], v[68:71]
	s_movk_i32 s0, 0xd0
	v_mad_u32_u24 v0, v142, s0, 0
	s_add_u32 s0, s44, s72
	v_add3_u32 v0, v0, v144, s8
	s_addc_u32 s1, s45, s73
	ds_read_b128 v[72:75], v0
	ds_read_b128 v[68:71], v0 offset:64
	global_load_dword v145, v3, s[0:1]
	v_or_b32_e32 v152, -16, v140
	v_lshlrev_b32_e32 v143, 3, v141
	v_add_u32_e32 v0, -16, v141
	s_movk_i32 s3, 0x100
	v_sub_u32_e32 v151, v152, v143
	v_cmp_gt_u32_e64 s[0:1], s3, v0
	v_add_u32_e32 v0, 0x100, v151
	v_cmp_gt_u32_e64 s[40:41], s34, v0
	v_add_u32_e32 v0, 0xffffff81, v143
	v_cmp_lt_i32_e32 vcc, 15, v141
	v_cmp_gt_i32_e64 s[42:43], s33, v0
	v_add_u32_e32 v0, 0xff, v151
	s_and_b64 s[4:5], vcc, s[42:43]
	v_cmp_gt_u32_e64 s[42:43], s34, v0
	s_and_b64 s[40:41], s[0:1], s[40:41]
	s_and_b64 s[42:43], s[4:5], s[42:43]
	v_cndmask_b32_e64 v1, v231, v158, s[40:41]
	v_cndmask_b32_e64 v0, v231, v176, s[42:43]
	v_max_f32_e32 v2, v0, v0
	v_max_f32_e32 v146, v1, v1
	v_max_f32_e32 v146, v146, v2
	v_add_u32_e32 v2, 0xfe, v151
	v_cmp_gt_u32_e64 s[40:41], s34, v2
	v_add_u32_e32 v2, 0xffffff83, v143
	v_cmp_gt_i32_e64 s[42:43], s33, v2
	v_add_u32_e32 v2, 0xfd, v151
	s_and_b64 s[4:5], vcc, s[42:43]
	v_cmp_gt_u32_e64 s[42:43], s34, v2
	s_and_b64 s[40:41], s[0:1], s[40:41]
	s_and_b64 s[42:43], s[4:5], s[42:43]
	v_cndmask_b32_e64 v148, v231, v159, s[40:41]
	v_cndmask_b32_e64 v2, v231, v177, s[42:43]
	v_max_f32_e32 v147, v2, v2
	v_max_f32_e32 v149, v148, v148
	v_max_f32_e32 v147, v149, v147
	s_waitcnt lgkmcnt(1)
	v_mfma_f32_16x16x32_bf16 v[64:67], v[72:75], v[64:67], 0
	s_waitcnt vmcnt(0)
	v_max3_f32 v153, v145, v146, v147
	v_add_u32_e32 v146, 0xfc, v151
	v_cmp_gt_u32_e64 s[40:41], s34, v146
	v_add_u32_e32 v146, 0xffffff85, v143
	v_cmp_gt_i32_e64 s[42:43], s33, v146
	v_add_u32_e32 v146, 0xfb, v151
	s_and_b64 s[4:5], vcc, s[42:43]
	v_cmp_gt_u32_e64 s[42:43], s34, v146
	s_and_b64 s[40:41], s[0:1], s[40:41]
	s_and_b64 s[42:43], s[4:5], s[42:43]
	v_cndmask_b32_e64 v147, v231, v160, s[40:41]
	v_cndmask_b32_e64 v146, v231, v178, s[42:43]
	v_max_f32_e32 v149, v146, v146
	v_max_f32_e32 v150, v147, v147
	v_max_f32_e32 v154, v150, v149
	v_add_u32_e32 v149, 0xfa, v151
	v_cmp_gt_u32_e64 s[40:41], s34, v149
	v_add_u32_e32 v149, 0xffffff87, v143
	s_and_b64 s[0:1], s[0:1], s[40:41]
	v_cmp_gt_i32_e64 s[40:41], s33, v149
	v_add_u32_e32 v149, 0xf9, v151
	s_and_b64 s[4:5], vcc, s[40:41]
	v_cmp_gt_u32_e32 vcc, s34, v149
	s_and_b64 vcc, s[4:5], vcc
	v_cndmask_b32_e64 v150, v231, v161, s[0:1]
	v_cndmask_b32_e32 v149, v231, v179, vcc
	v_max_f32_e32 v155, v149, v149
	v_max_f32_e32 v158, v150, v150
	v_max_f32_e32 v155, v158, v155
	v_max3_f32 v153, v153, v154, v155
	v_add_u32_e32 v154, -12, v141
	v_cmp_gt_u32_e64 s[40:41], s3, v154
	v_add_u32_e32 v154, 0xe0, v151
	v_cmp_gt_u32_e64 s[0:1], s34, v154
	v_add_u32_e32 v154, 0xffffffa1, v143
	v_cmp_lt_i32_e32 vcc, 11, v141
	s_and_b64 s[42:43], s[40:41], s[0:1]
	v_cmp_gt_i32_e64 s[0:1], s33, v154
	v_add_u32_e32 v154, 0xdf, v151
	s_and_b64 s[4:5], vcc, s[0:1]
	v_cmp_gt_u32_e64 s[0:1], s34, v154
	s_and_b64 s[44:45], s[4:5], s[0:1]
	v_cndmask_b32_e64 v136, v231, v136, s[42:43]
	v_cndmask_b32_e64 v132, v231, v132, s[44:45]
	v_max_f32_e32 v154, v132, v132
	v_max_f32_e32 v155, v136, v136
	v_max_f32_e32 v154, v155, v154
	v_add_u32_e32 v155, 0xde, v151
	v_cmp_gt_u32_e64 s[0:1], s34, v155
	v_add_u32_e32 v155, 0xffffffa3, v143
	v_cmp_gt_i32_e64 s[42:43], s33, v155
	v_add_u32_e32 v155, 0xdd, v151
	s_and_b64 s[4:5], vcc, s[42:43]
	v_cmp_gt_u32_e64 s[42:43], s34, v155
	s_and_b64 s[0:1], s[40:41], s[0:1]
	s_and_b64 s[42:43], s[4:5], s[42:43]
	v_cndmask_b32_e64 v137, v231, v137, s[0:1]
	v_cndmask_b32_e64 v133, v231, v133, s[42:43]
	v_max_f32_e32 v155, v133, v133
	v_max_f32_e32 v158, v137, v137
	v_max_f32_e32 v155, v158, v155
	v_max3_f32 v153, v153, v154, v155
	v_add_u32_e32 v154, 0xdc, v151
	v_cmp_gt_u32_e64 s[0:1], s34, v154
	v_add_u32_e32 v154, 0xffffffa5, v143
	v_cmp_gt_i32_e64 s[42:43], s33, v154
	v_add_u32_e32 v154, 0xdb, v151
	s_and_b64 s[4:5], vcc, s[42:43]
	v_cmp_gt_u32_e64 s[42:43], s34, v154
	s_and_b64 s[0:1], s[40:41], s[0:1]
	s_and_b64 s[42:43], s[4:5], s[42:43]
	v_cndmask_b32_e64 v138, v231, v138, s[0:1]
	v_cndmask_b32_e64 v134, v231, v134, s[42:43]
	v_max_f32_e32 v154, v134, v134
	v_max_f32_e32 v155, v138, v138
	v_max_f32_e32 v154, v155, v154
	v_add_u32_e32 v155, 0xda, v151
	v_cmp_gt_u32_e64 s[0:1], s34, v155
	v_add_u32_e32 v155, 0xffffffa7, v143
	s_and_b64 s[0:1], s[40:41], s[0:1]
	v_cmp_gt_i32_e64 s[40:41], s33, v155
	v_add_u32_e32 v155, 0xd9, v151
	s_and_b64 s[4:5], vcc, s[40:41]
	v_cmp_gt_u32_e32 vcc, s34, v155
	s_and_b64 vcc, s[4:5], vcc
	v_cndmask_b32_e64 v139, v231, v139, s[0:1]
	v_cndmask_b32_e32 v135, v231, v135, vcc
	v_max_f32_e32 v155, v135, v135
	v_max_f32_e32 v158, v139, v139
	v_max_f32_e32 v155, v158, v155
	v_max3_f32 v153, v153, v154, v155
	v_add_u32_e32 v154, -8, v141
	v_cmp_gt_u32_e64 s[0:1], s3, v154
	v_add_u32_e32 v154, 0xc0, v151
	v_cmp_gt_u32_e64 s[40:41], s34, v154
	v_subrev_u32_e32 v154, 63, v143
	v_cmp_lt_i32_e32 vcc, 7, v141
	v_cmp_gt_i32_e64 s[42:43], s33, v154
	v_add_u32_e32 v154, 0xbf, v151
	s_and_b64 s[4:5], vcc, s[42:43]
	v_cmp_gt_u32_e64 s[42:43], s34, v154
	s_and_b64 s[40:41], s[0:1], s[40:41]
	s_and_b64 s[42:43], s[4:5], s[42:43]
	v_cndmask_b32_e64 v128, v231, v128, s[40:41]
	v_cndmask_b32_e64 v124, v231, v124, s[42:43]
	v_max_f32_e32 v154, v124, v124
	v_max_f32_e32 v155, v128, v128
	v_max_f32_e32 v154, v155, v154
	v_add_u32_e32 v155, 0xbe, v151
	v_cmp_gt_u32_e64 s[40:41], s34, v155
	v_subrev_u32_e32 v155, 61, v143
	v_cmp_gt_i32_e64 s[42:43], s33, v155
	v_add_u32_e32 v155, 0xbd, v151
	s_and_b64 s[4:5], vcc, s[42:43]
	v_cmp_gt_u32_e64 s[42:43], s34, v155
	s_and_b64 s[40:41], s[0:1], s[40:41]
	s_and_b64 s[42:43], s[4:5], s[42:43]
	v_cndmask_b32_e64 v129, v231, v129, s[40:41]
	v_cndmask_b32_e64 v125, v231, v125, s[42:43]
	v_max_f32_e32 v155, v125, v125
	v_max_f32_e32 v158, v129, v129
	v_max_f32_e32 v155, v158, v155
	v_max3_f32 v153, v153, v154, v155
	v_add_u32_e32 v154, 0xbc, v151
	v_cmp_gt_u32_e64 s[40:41], s34, v154
	v_subrev_u32_e32 v154, 59, v143
	v_cmp_gt_i32_e64 s[42:43], s33, v154
	v_add_u32_e32 v154, 0xbb, v151
	s_and_b64 s[4:5], vcc, s[42:43]
	v_cmp_gt_u32_e64 s[42:43], s34, v154
	s_and_b64 s[40:41], s[0:1], s[40:41]
	s_and_b64 s[42:43], s[4:5], s[42:43]
	v_cndmask_b32_e64 v130, v231, v130, s[40:41]
	v_cndmask_b32_e64 v126, v231, v126, s[42:43]
	v_max_f32_e32 v154, v126, v126
	v_max_f32_e32 v155, v130, v130
	v_max_f32_e32 v154, v155, v154
	v_add_u32_e32 v155, 0xba, v151
	v_cmp_gt_u32_e64 s[40:41], s34, v155
	v_subrev_u32_e32 v155, 57, v143
	s_and_b64 s[0:1], s[0:1], s[40:41]
	v_cmp_gt_i32_e64 s[40:41], s33, v155
	v_add_u32_e32 v155, 0xb9, v151
	s_and_b64 s[4:5], vcc, s[40:41]
	v_cmp_gt_u32_e32 vcc, s34, v155
	s_and_b64 vcc, s[4:5], vcc
	v_cndmask_b32_e64 v131, v231, v131, s[0:1]
	v_cndmask_b32_e32 v127, v231, v127, vcc
	v_max_f32_e32 v155, v127, v127
	v_max_f32_e32 v158, v131, v131
	v_max_f32_e32 v155, v158, v155
	v_max3_f32 v153, v153, v154, v155
	v_add_u32_e32 v154, -4, v141
	v_cmp_gt_u32_e64 s[0:1], s3, v154
	v_add_u32_e32 v154, 0xa0, v151
	v_cmp_gt_u32_e64 s[40:41], s34, v154
	v_subrev_u32_e32 v154, 31, v143
	v_cmp_lt_i32_e32 vcc, 3, v141
	v_cmp_gt_i32_e64 s[42:43], s33, v154
	v_add_u32_e32 v154, 0x9f, v151
	s_and_b64 s[4:5], vcc, s[42:43]
	v_cmp_gt_u32_e64 s[42:43], s34, v154
	s_and_b64 s[40:41], s[0:1], s[40:41]
	s_and_b64 s[42:43], s[4:5], s[42:43]
	v_cndmask_b32_e64 v120, v231, v120, s[40:41]
	v_cndmask_b32_e64 v116, v231, v116, s[42:43]
	v_max_f32_e32 v154, v116, v116
	v_max_f32_e32 v155, v120, v120
	v_max_f32_e32 v154, v155, v154
	v_add_u32_e32 v155, 0x9e, v151
	v_cmp_gt_u32_e64 s[40:41], s34, v155
	v_subrev_u32_e32 v155, 29, v143
	v_cmp_gt_i32_e64 s[42:43], s33, v155
	v_add_u32_e32 v155, 0x9d, v151
	s_and_b64 s[4:5], vcc, s[42:43]
	v_cmp_gt_u32_e64 s[42:43], s34, v155
	s_and_b64 s[40:41], s[0:1], s[40:41]
	s_and_b64 s[42:43], s[4:5], s[42:43]
	v_cndmask_b32_e64 v121, v231, v121, s[40:41]
	v_cndmask_b32_e64 v117, v231, v117, s[42:43]
	v_max_f32_e32 v155, v117, v117
	v_max_f32_e32 v158, v121, v121
	v_max_f32_e32 v155, v158, v155
	v_max3_f32 v153, v153, v154, v155
	v_add_u32_e32 v154, 0x9c, v151
	v_cmp_gt_u32_e64 s[40:41], s34, v154
	v_subrev_u32_e32 v154, 27, v143
	v_cmp_gt_i32_e64 s[42:43], s33, v154
	v_add_u32_e32 v154, 0x9b, v151
	s_and_b64 s[4:5], vcc, s[42:43]
	v_cmp_gt_u32_e64 s[42:43], s34, v154
	s_and_b64 s[40:41], s[0:1], s[40:41]
	s_and_b64 s[42:43], s[4:5], s[42:43]
	v_cndmask_b32_e64 v122, v231, v122, s[40:41]
	v_cndmask_b32_e64 v118, v231, v118, s[42:43]
	v_max_f32_e32 v154, v118, v118
	v_max_f32_e32 v155, v122, v122
	v_max_f32_e32 v154, v155, v154
	v_add_u32_e32 v155, 0x9a, v151
	v_cmp_gt_u32_e64 s[40:41], s34, v155
	v_subrev_u32_e32 v155, 25, v143
	s_and_b64 s[0:1], s[0:1], s[40:41]
	v_cmp_gt_i32_e64 s[40:41], s33, v155
	v_add_u32_e32 v155, 0x99, v151
	s_and_b64 s[4:5], vcc, s[40:41]
	v_cmp_gt_u32_e32 vcc, s34, v155
	s_and_b64 vcc, s[4:5], vcc
	v_cndmask_b32_e64 v123, v231, v123, s[0:1]
	v_cndmask_b32_e32 v119, v231, v119, vcc
	v_max_f32_e32 v155, v119, v119
	v_max_f32_e32 v158, v123, v123
	v_max_f32_e32 v155, v158, v155
	v_max3_f32 v153, v153, v154, v155
	v_add_u32_e32 v154, 0x80, v151
	v_cmp_gt_u32_e64 s[0:1], s3, v141
	v_cmp_gt_u32_e64 s[40:41], s34, v154
	v_or_b32_e32 v154, 1, v143
	v_cmp_lt_i32_e32 vcc, -1, v141
	s_and_b64 s[0:1], s[0:1], s[40:41]
	v_cmp_gt_i32_e64 s[40:41], s33, v154
	v_add_u32_e32 v154, 0x7f, v151
	s_and_b64 s[4:5], vcc, s[40:41]
	v_cmp_gt_u32_e64 s[40:41], s34, v154
	s_and_b64 s[40:41], s[4:5], s[40:41]
	v_cndmask_b32_e64 v112, v231, v112, s[0:1]
	v_cndmask_b32_e64 v108, v231, v108, s[40:41]
	v_max_f32_e32 v154, v108, v108
	v_max_f32_e32 v155, v112, v112
	v_max_f32_e32 v154, v155, v154
	v_or_b32_e32 v155, 2, v143
	v_sub_u32_e32 v158, v152, v155
	v_cmp_gt_i32_e64 s[0:1], s33, v155
	v_add_u32_e32 v155, 0x80, v158
	s_and_b64 s[4:5], vcc, s[0:1]
	v_cmp_gt_u32_e64 s[0:1], s34, v155
	v_or_b32_e32 v155, 3, v143
	v_cmp_gt_i32_e64 s[40:41], s33, v155
	v_add_u32_e32 v155, 0x7f, v158
	s_and_b64 s[0:1], s[4:5], s[0:1]
	s_and_b64 s[4:5], vcc, s[40:41]
	v_cmp_gt_u32_e64 s[40:41], s34, v155
	s_and_b64 s[40:41], s[4:5], s[40:41]
	v_cndmask_b32_e64 v113, v231, v113, s[0:1]
	v_cndmask_b32_e64 v109, v231, v109, s[40:41]
	v_max_f32_e32 v155, v109, v109
	v_max_f32_e32 v158, v113, v113
	v_max_f32_e32 v155, v158, v155
	v_max3_f32 v153, v153, v154, v155
	v_or_b32_e32 v154, 4, v143
	v_sub_u32_e32 v155, v152, v154
	v_cmp_gt_i32_e64 s[0:1], s33, v154
	v_add_u32_e32 v154, 0x80, v155
	s_and_b64 s[4:5], vcc, s[0:1]
	v_cmp_gt_u32_e64 s[0:1], s34, v154
	v_or_b32_e32 v154, 5, v143
	v_cmp_gt_i32_e64 s[40:41], s33, v154
	v_add_u32_e32 v154, 0x7f, v155
	s_and_b64 s[0:1], s[4:5], s[0:1]
	s_and_b64 s[4:5], vcc, s[40:41]
	v_cmp_gt_u32_e64 s[40:41], s34, v154
	s_and_b64 s[40:41], s[4:5], s[40:41]
	v_cndmask_b32_e64 v114, v231, v114, s[0:1]
	v_cndmask_b32_e64 v110, v231, v110, s[40:41]
	v_max_f32_e32 v154, v110, v110
	v_max_f32_e32 v155, v114, v114
	v_max_f32_e32 v154, v155, v154
	v_or_b32_e32 v155, 6, v143
	v_sub_u32_e32 v152, v152, v155
	v_cmp_gt_i32_e64 s[0:1], s33, v155
	v_add_u32_e32 v155, 0x80, v152
	s_and_b64 s[4:5], vcc, s[0:1]
	v_cmp_gt_u32_e64 s[0:1], s34, v155
	v_or_b32_e32 v155, 7, v143
	v_cmp_gt_i32_e64 s[40:41], s33, v155
	v_add_u32_e32 v152, 0x7f, v152
	s_and_b64 s[0:1], s[4:5], s[0:1]
	s_and_b64 s[4:5], vcc, s[40:41]
	v_cmp_gt_u32_e32 vcc, s34, v152
	s_and_b64 vcc, s[4:5], vcc
	v_cndmask_b32_e64 v115, v231, v115, s[0:1]
	v_cndmask_b32_e32 v152, v231, v111, vcc
	v_max_f32_e32 v111, v152, v152
	v_max_f32_e32 v155, v115, v115
	v_max_f32_e32 v111, v155, v111
	v_max3_f32 v153, v153, v154, v111
	v_add_u32_e32 v111, 4, v141
	v_cmp_gt_u32_e64 s[0:1], s3, v111
	v_add_u32_e32 v111, 0x60, v151
	v_cmp_gt_u32_e64 s[40:41], s34, v111
	v_add_u32_e32 v111, 33, v143
	v_cmp_lt_i32_e32 vcc, -5, v141
	v_cmp_gt_i32_e64 s[42:43], s33, v111
	v_add_u32_e32 v111, 0x5f, v151
	s_and_b64 s[4:5], vcc, s[42:43]
	v_cmp_gt_u32_e64 s[42:43], s34, v111
	s_and_b64 s[40:41], s[0:1], s[40:41]
	s_and_b64 s[42:43], s[4:5], s[42:43]
	v_cndmask_b32_e64 v104, v231, v104, s[40:41]
	v_cndmask_b32_e64 v100, v231, v100, s[42:43]
	v_max_f32_e32 v111, v100, v100
	v_max_f32_e32 v154, v104, v104
	v_max_f32_e32 v154, v154, v111
	v_add_u32_e32 v111, 0x5e, v151
	v_cmp_gt_u32_e64 s[40:41], s34, v111
	v_add_u32_e32 v111, 35, v143
	v_cmp_gt_i32_e64 s[42:43], s33, v111
	v_add_u32_e32 v111, 0x5d, v151
	s_and_b64 s[4:5], vcc, s[42:43]
	v_cmp_gt_u32_e64 s[42:43], s34, v111
	s_and_b64 s[40:41], s[0:1], s[40:41]
	s_and_b64 s[42:43], s[4:5], s[42:43]
	v_cndmask_b32_e64 v105, v231, v105, s[40:41]
	v_cndmask_b32_e64 v111, v231, v101, s[42:43]
	v_max_f32_e32 v101, v111, v111
	v_max_f32_e32 v155, v105, v105
	v_max_f32_e32 v101, v155, v101
	v_max3_f32 v101, v153, v154, v101
	v_add_u32_e32 v153, 0x5c, v151
	v_cmp_gt_u32_e64 s[40:41], s34, v153
	v_add_u32_e32 v153, 37, v143
	v_cmp_gt_i32_e64 s[42:43], s33, v153
	v_add_u32_e32 v153, 0x5b, v151
	s_and_b64 s[4:5], vcc, s[42:43]
	v_cmp_gt_u32_e64 s[42:43], s34, v153
	s_and_b64 s[40:41], s[0:1], s[40:41]
	s_and_b64 s[42:43], s[4:5], s[42:43]
	v_cndmask_b32_e64 v106, v231, v106, s[40:41]
	v_cndmask_b32_e64 v102, v231, v102, s[42:43]
	v_max_f32_e32 v153, v102, v102
	v_max_f32_e32 v154, v106, v106
	v_max_f32_e32 v154, v154, v153
	v_add_u32_e32 v153, 0x5a, v151
	v_cmp_gt_u32_e64 s[40:41], s34, v153
	v_add_u32_e32 v153, 39, v143
	s_and_b64 s[0:1], s[0:1], s[40:41]
	v_cmp_gt_i32_e64 s[40:41], s33, v153
	v_add_u32_e32 v153, 0x59, v151
	s_and_b64 s[4:5], vcc, s[40:41]
	v_cmp_gt_u32_e32 vcc, s34, v153
	s_and_b64 vcc, s[4:5], vcc
	v_cndmask_b32_e64 v107, v231, v107, s[0:1]
	v_cndmask_b32_e32 v153, v231, v103, vcc
	v_max_f32_e32 v103, v153, v153
	v_max_f32_e32 v155, v107, v107
	v_max_f32_e32 v103, v155, v103
	v_max3_f32 v154, v101, v154, v103
	v_add_u32_e32 v101, 8, v141
	v_cmp_gt_u32_e64 s[0:1], s3, v101
	v_add_u32_e32 v101, 64, v151
	v_cmp_gt_u32_e64 s[40:41], s34, v101
	v_add_u32_e32 v101, 0x41, v143
	v_cmp_lt_i32_e32 vcc, -9, v141
	v_cmp_gt_i32_e64 s[42:43], s33, v101
	v_add_u32_e32 v101, 63, v151
	s_and_b64 s[4:5], vcc, s[42:43]
	v_cmp_gt_u32_e64 s[42:43], s34, v101
	s_and_b64 s[40:41], s[0:1], s[40:41]
	s_and_b64 s[42:43], s[4:5], s[42:43]
	v_cndmask_b32_e64 v101, v231, v96, s[40:41]
	v_cndmask_b32_e64 v92, v231, v92, s[42:43]
	v_max_f32_e32 v96, v92, v92
	v_max_f32_e32 v103, v101, v101
	v_max_f32_e32 v96, v103, v96
	v_add_u32_e32 v103, 62, v151
	v_cmp_gt_u32_e64 s[40:41], s34, v103
	v_add_u32_e32 v103, 0x43, v143
	v_cmp_gt_i32_e64 s[42:43], s33, v103
	v_add_u32_e32 v103, 61, v151
	s_and_b64 s[4:5], vcc, s[42:43]
	v_cmp_gt_u32_e64 s[42:43], s34, v103
	s_and_b64 s[40:41], s[0:1], s[40:41]
	s_and_b64 s[42:43], s[4:5], s[42:43]
	v_cndmask_b32_e64 v97, v231, v97, s[40:41]
	v_cndmask_b32_e64 v103, v231, v93, s[42:43]
	v_max_f32_e32 v93, v103, v103
	v_max_f32_e32 v155, v97, v97
	v_max_f32_e32 v93, v155, v93
	v_max3_f32 v93, v154, v96, v93
	v_add_u32_e32 v96, 60, v151
	v_cmp_gt_u32_e64 s[40:41], s34, v96
	v_add_u32_e32 v96, 0x45, v143
	v_cmp_gt_i32_e64 s[42:43], s33, v96
	v_add_u32_e32 v96, 59, v151
	s_and_b64 s[4:5], vcc, s[42:43]
	v_cmp_gt_u32_e64 s[42:43], s34, v96
	s_and_b64 s[40:41], s[0:1], s[40:41]
	s_and_b64 s[42:43], s[4:5], s[42:43]
	v_cndmask_b32_e64 v98, v231, v98, s[40:41]
	v_cndmask_b32_e64 v154, v231, v94, s[42:43]
	v_max_f32_e32 v94, v154, v154
	v_max_f32_e32 v96, v98, v98
	v_max_f32_e32 v94, v96, v94
	v_add_u32_e32 v96, 58, v151
	v_cmp_gt_u32_e64 s[40:41], s34, v96
	v_add_u32_e32 v96, 0x47, v143
	s_and_b64 s[0:1], s[0:1], s[40:41]
	v_cmp_gt_i32_e64 s[40:41], s33, v96
	v_add_u32_e32 v96, 57, v151
	s_and_b64 s[4:5], vcc, s[40:41]
	v_cmp_gt_u32_e32 vcc, s34, v96
	s_and_b64 vcc, s[4:5], vcc
	v_cndmask_b32_e64 v159, v231, v99, s[0:1]
	v_cndmask_b32_e32 v161, v231, v95, vcc
	v_max_f32_e32 v95, v161, v161
	v_max_f32_e32 v96, v159, v159
	v_max_f32_e32 v95, v96, v95
	v_max3_f32 v96, v93, v94, v95
	v_add_u32_e32 v93, 12, v141
	v_cmp_gt_u32_e64 s[0:1], s3, v93
	v_add_u32_e32 v93, 32, v151
	v_cmp_gt_u32_e64 s[40:41], s34, v93
	v_add_u32_e32 v93, 0x61, v143
	v_cmp_lt_i32_e32 vcc, -13, v141
	v_cmp_gt_i32_e64 s[42:43], s33, v93
	v_add_u32_e32 v93, 31, v151
	s_and_b64 s[4:5], vcc, s[42:43]
	v_cmp_gt_u32_e64 s[42:43], s34, v93
	s_and_b64 s[40:41], s[0:1], s[40:41]
	s_and_b64 s[42:43], s[4:5], s[42:43]
	v_cndmask_b32_e64 v93, v231, v88, s[40:41]
	v_cndmask_b32_e64 v94, v231, v84, s[42:43]
	v_max_f32_e32 v84, v94, v94
	v_max_f32_e32 v88, v93, v93
	v_max_f32_e32 v84, v88, v84
	v_add_u32_e32 v88, 30, v151
	v_cmp_gt_u32_e64 s[40:41], s34, v88
	v_add_u32_e32 v88, 0x63, v143
	v_cmp_gt_i32_e64 s[42:43], s33, v88
	v_add_u32_e32 v88, 29, v151
	s_and_b64 s[4:5], vcc, s[42:43]
	v_cmp_gt_u32_e64 s[42:43], s34, v88
	s_and_b64 s[40:41], s[0:1], s[40:41]
	s_and_b64 s[42:43], s[4:5], s[42:43]
	v_cndmask_b32_e64 v95, v231, v89, s[40:41]
	v_cndmask_b32_e64 v99, v231, v85, s[42:43]
	v_max_f32_e32 v85, v99, v99
	v_max_f32_e32 v88, v95, v95
	v_max_f32_e32 v85, v88, v85
	v_max3_f32 v84, v96, v84, v85
	v_add_u32_e32 v85, 28, v151
	v_cmp_gt_u32_e64 s[40:41], s34, v85
	v_add_u32_e32 v85, 0x65, v143
	v_cmp_gt_i32_e64 s[42:43], s33, v85
	v_add_u32_e32 v85, 27, v151
	s_and_b64 s[4:5], vcc, s[42:43]
	v_cmp_gt_u32_e64 s[42:43], s34, v85
	s_and_b64 s[40:41], s[0:1], s[40:41]
	s_and_b64 s[42:43], s[4:5], s[42:43]
	v_cndmask_b32_e64 v160, v231, v90, s[40:41]
	v_cndmask_b32_e64 v162, v231, v86, s[42:43]
	v_max_f32_e32 v85, v162, v162
	v_max_f32_e32 v86, v160, v160
	v_max_f32_e32 v85, v86, v85
	v_add_u32_e32 v86, 26, v151
	v_cmp_gt_u32_e64 s[40:41], s34, v86
	v_add_u32_e32 v86, 0x67, v143
	s_and_b64 s[0:1], s[0:1], s[40:41]
	v_cmp_gt_i32_e64 s[40:41], s33, v86
	v_add_u32_e32 v86, 25, v151
	s_and_b64 s[4:5], vcc, s[40:41]
	v_cmp_gt_u32_e32 vcc, s34, v86
	s_and_b64 vcc, s[4:5], vcc
	v_cndmask_b32_e64 v177, v231, v91, s[0:1]
	v_cndmask_b32_e32 v178, v231, v87, vcc
	v_max_f32_e32 v86, v178, v178
	v_max_f32_e32 v87, v177, v177
	v_max_f32_e32 v86, v87, v86
	v_max3_f32 v84, v84, v85, v86
	s_movk_i32 s0, 0xffef
	v_add_u32_e32 v85, 16, v141
	v_cmp_lt_i32_e32 vcc, s0, v141
	v_cmp_gt_u32_e64 s[0:1], s3, v85
	v_add_u32_e32 v85, 0x81, v143
	v_cmp_gt_i32_e64 s[42:43], s33, v85
	v_add_u32_e32 v85, -1, v151
	v_cmp_gt_u32_e64 s[40:41], s34, v151
	s_and_b64 s[4:5], vcc, s[42:43]
	v_cmp_gt_u32_e64 s[42:43], s34, v85
	s_and_b64 s[40:41], s[0:1], s[40:41]
	s_and_b64 s[42:43], s[4:5], s[42:43]
	v_cndmask_b32_e64 v155, v231, v80, s[40:41]
	v_cndmask_b32_e64 v158, v231, v76, s[42:43]
	v_max_f32_e32 v76, v158, v158
	v_max_f32_e32 v80, v155, v155
	v_max_f32_e32 v76, v80, v76
	v_add_u32_e32 v80, -2, v151
	v_cmp_gt_u32_e64 s[40:41], s34, v80
	v_add_u32_e32 v80, 0x83, v143
	v_cmp_gt_i32_e64 s[42:43], s33, v80
	v_add_u32_e32 v80, -3, v151
	s_and_b64 s[4:5], vcc, s[42:43]
	v_cmp_gt_u32_e64 s[42:43], s34, v80
	s_and_b64 s[40:41], s[0:1], s[40:41]
	s_and_b64 s[42:43], s[4:5], s[42:43]
	v_cndmask_b32_e64 v163, v231, v81, s[40:41]
	v_cndmask_b32_e64 v176, v231, v77, s[42:43]
	v_max_f32_e32 v77, v176, v176
	v_max_f32_e32 v80, v163, v163
	v_max_f32_e32 v77, v80, v77
	v_max3_f32 v76, v84, v76, v77
	v_add_u32_e32 v77, -4, v151
	v_cmp_gt_u32_e64 s[40:41], s34, v77
	v_add_u32_e32 v77, 0x85, v143
	v_cmp_gt_i32_e64 s[42:43], s33, v77
	v_add_u32_e32 v77, -5, v151
	s_and_b64 s[4:5], vcc, s[42:43]
	v_cmp_gt_u32_e64 s[42:43], s34, v77
	s_and_b64 s[40:41], s[0:1], s[40:41]
	s_and_b64 s[42:43], s[4:5], s[42:43]
	v_cndmask_b32_e64 v179, v231, v82, s[40:41]
	v_cndmask_b32_e64 v180, v231, v78, s[42:43]
	v_max_f32_e32 v77, v180, v180
	v_max_f32_e32 v78, v179, v179
	v_max_f32_e32 v77, v78, v77
	v_add_u32_e32 v78, -6, v151
	v_cmp_gt_u32_e64 s[40:41], s34, v78
	v_add_u32_e32 v78, 0x87, v143
	s_and_b64 s[0:1], s[0:1], s[40:41]
	v_cmp_gt_i32_e64 s[40:41], s33, v78
	v_add_u32_e32 v78, -7, v151
	s_and_b64 s[4:5], vcc, s[40:41]
	v_cmp_gt_u32_e32 vcc, s34, v78
	s_and_b64 vcc, s[4:5], vcc
	v_cndmask_b32_e64 v151, v231, v83, s[0:1]
	v_cndmask_b32_e32 v181, v231, v79, vcc
	s_waitcnt lgkmcnt(0)
	v_mfma_f32_16x16x32_bf16 v[64:67], v[68:71], v[60:63], v[64:67]
	v_max_f32_e32 v78, v181, v181
	v_max_f32_e32 v79, v151, v151
	v_max_f32_e32 v78, v79, v78
	v_max3_f32 v76, v76, v77, v78
	s_nop 3
	v_max3_f32 v60, v76, v64, v65
	v_max3_f32 v60, v60, v66, v67
	ds_bpermute_b32 v61, v157, v60
	s_waitcnt lgkmcnt(0)
	v_max_f32_e32 v61, v61, v61
	v_max_f32_e32 v60, v60, v61
	ds_bpermute_b32 v61, v156, v60
	s_waitcnt lgkmcnt(0)
	v_max_f32_e32 v61, v61, v61
	v_max_f32_e32 v96, v60, v61
	v_sub_f32_e32 v0, v0, v96
	v_sub_f32_e32 v1, v1, v96
	v_mul_f32_e32 v0, 0x3fb8aa3b, v0
	v_mul_f32_e32 v1, 0x3fb8aa3b, v1
	v_exp_f32_e32 v63, v0
	v_sub_f32_e32 v0, v148, v96
	v_sub_f32_e32 v2, v2, v96
	v_exp_f32_e32 v62, v1
	v_mul_f32_e32 v0, 0x3fb8aa3b, v0
	v_mul_f32_e32 v2, 0x3fb8aa3b, v2
	v_exp_f32_e32 v0, v0
	v_exp_f32_e32 v2, v2
	v_add_f32_e32 v1, v62, v63
	v_pk_add_f32 v[60:61], v[0:1], v[2:3]
	s_nop 0
	v_pk_add_f32 v[68:69], v[60:61], v[60:61] op_sel_hi:[0,1]
	v_sub_f32_e32 v60, v146, v96
	v_mul_f32_e32 v60, 0x3fb8aa3b, v60
	v_exp_f32_e32 v74, v60
	v_sub_f32_e32 v60, v150, v96
	v_sub_f32_e32 v1, v147, v96
	v_mul_f32_e32 v60, 0x3fb8aa3b, v60
	v_mul_f32_e32 v1, 0x3fb8aa3b, v1
	v_exp_f32_e32 v70, v60
	v_sub_f32_e32 v60, v149, v96
	v_exp_f32_e32 v1, v1
	v_mul_f32_e32 v60, 0x3fb8aa3b, v60
	v_exp_f32_e32 v68, v60
	v_add_f32_e32 v71, v1, v74
	v_pk_add_f32 v[60:61], v[70:71], v[68:69]
	s_nop 0
	v_pk_add_f32 v[72:73], v[60:61], v[60:61] op_sel_hi:[0,1]
	v_cvt_pk_bf16_f32 v61, v0, v2
	v_sub_f32_e32 v0, v136, v96
	v_mul_f32_e32 v0, 0x3fb8aa3b, v0
	v_exp_f32_e32 v2, v0
	v_sub_f32_e32 v0, v132, v96
	v_mul_f32_e32 v0, 0x3fb8aa3b, v0
	v_cvt_pk_bf16_f32 v60, v62, v63
	v_cvt_pk_bf16_f32 v63, v70, v68
	v_exp_f32_e32 v70, v0
	v_sub_f32_e32 v0, v137, v96
	v_sub_f32_e32 v68, v133, v96
	v_mul_f32_e32 v0, 0x3fb8aa3b, v0
	v_mul_f32_e32 v68, 0x3fb8aa3b, v68
	v_exp_f32_e32 v0, v0
	v_exp_f32_e32 v72, v68
	v_cvt_pk_bf16_f32 v62, v1, v74
	v_add_f32_e32 v1, v2, v70
	v_pk_add_f32 v[68:69], v[0:1], v[72:73]
	s_nop 0
	v_pk_add_f32 v[74:75], v[68:69], v[68:69] op_sel_hi:[0,1]
	v_sub_f32_e32 v68, v134, v96
	v_mul_f32_e32 v68, 0x3fb8aa3b, v68
	v_exp_f32_e32 v71, v68
	v_sub_f32_e32 v68, v139, v96
	v_sub_f32_e32 v1, v138, v96
	v_mul_f32_e32 v68, 0x3fb8aa3b, v68
	v_mul_f32_e32 v1, 0x3fb8aa3b, v1
	v_exp_f32_e32 v76, v68
	v_sub_f32_e32 v68, v135, v96
	v_exp_f32_e32 v1, v1
	v_mul_f32_e32 v68, 0x3fb8aa3b, v68
	v_exp_f32_e32 v74, v68
	v_add_f32_e32 v77, v1, v71
	v_pk_add_f32 v[68:69], v[76:77], v[74:75]
	s_nop 0
	v_pk_add_f32 v[78:79], v[68:69], v[68:69] op_sel_hi:[0,1]
	v_cvt_pk_bf16_f32 v69, v0, v72
	v_sub_f32_e32 v0, v128, v96
	v_mul_f32_e32 v0, 0x3fb8aa3b, v0
	v_cvt_pk_bf16_f32 v68, v2, v70
	v_exp_f32_e32 v2, v0
	v_sub_f32_e32 v0, v124, v96
	v_mul_f32_e32 v0, 0x3fb8aa3b, v0
	v_cvt_pk_bf16_f32 v70, v1, v71
	v_cvt_pk_bf16_f32 v71, v76, v74
	v_exp_f32_e32 v74, v0
	v_sub_f32_e32 v0, v129, v96
	v_sub_f32_e32 v72, v125, v96
	v_mul_f32_e32 v0, 0x3fb8aa3b, v0
	v_mul_f32_e32 v72, 0x3fb8aa3b, v72
	v_exp_f32_e32 v0, v0
	v_exp_f32_e32 v78, v72
	v_add_f32_e32 v1, v2, v74
	v_pk_add_f32 v[72:73], v[0:1], v[78:79]
	s_nop 0
	v_pk_add_f32 v[76:77], v[72:73], v[72:73] op_sel_hi:[0,1]
	v_sub_f32_e32 v72, v126, v96
	v_mul_f32_e32 v72, 0x3fb8aa3b, v72
	v_exp_f32_e32 v75, v72
	v_sub_f32_e32 v72, v131, v96
	v_sub_f32_e32 v1, v130, v96
	v_mul_f32_e32 v72, 0x3fb8aa3b, v72
	v_mul_f32_e32 v1, 0x3fb8aa3b, v1
	v_exp_f32_e32 v80, v72
	v_sub_f32_e32 v72, v127, v96
	v_exp_f32_e32 v1, v1
	v_mul_f32_e32 v72, 0x3fb8aa3b, v72
	v_exp_f32_e32 v76, v72
	v_add_f32_e32 v81, v1, v75
	v_pk_add_f32 v[72:73], v[80:81], v[76:77]
	s_nop 0
	v_pk_add_f32 v[82:83], v[72:73], v[72:73] op_sel_hi:[0,1]
	v_cvt_pk_bf16_f32 v73, v0, v78
	v_sub_f32_e32 v0, v120, v96
	v_mul_f32_e32 v0, 0x3fb8aa3b, v0
	v_cvt_pk_bf16_f32 v72, v2, v74
	v_exp_f32_e32 v2, v0
	v_sub_f32_e32 v0, v116, v96
	v_mul_f32_e32 v0, 0x3fb8aa3b, v0
	v_cvt_pk_bf16_f32 v74, v1, v75
	v_cvt_pk_bf16_f32 v75, v80, v76
	v_exp_f32_e32 v78, v0
	v_sub_f32_e32 v0, v121, v96
	v_sub_f32_e32 v76, v117, v96
	v_mul_f32_e32 v0, 0x3fb8aa3b, v0
	v_mul_f32_e32 v76, 0x3fb8aa3b, v76
	v_exp_f32_e32 v0, v0
	v_exp_f32_e32 v82, v76
	v_add_f32_e32 v1, v2, v78
	v_pk_add_f32 v[76:77], v[0:1], v[82:83]
	s_nop 0
	v_pk_add_f32 v[80:81], v[76:77], v[76:77] op_sel_hi:[0,1]
	v_sub_f32_e32 v76, v118, v96
	v_mul_f32_e32 v76, 0x3fb8aa3b, v76
	v_exp_f32_e32 v79, v76
	v_sub_f32_e32 v76, v123, v96
	v_sub_f32_e32 v1, v122, v96
	v_mul_f32_e32 v76, 0x3fb8aa3b, v76
	v_mul_f32_e32 v1, 0x3fb8aa3b, v1
	v_exp_f32_e32 v84, v76
	v_sub_f32_e32 v76, v119, v96
	v_exp_f32_e32 v1, v1
	v_mul_f32_e32 v76, 0x3fb8aa3b, v76
	v_exp_f32_e32 v80, v76
	v_add_f32_e32 v85, v1, v79
	v_pk_add_f32 v[76:77], v[84:85], v[80:81]
	s_nop 0
	v_pk_add_f32 v[86:87], v[76:77], v[76:77] op_sel_hi:[0,1]
	v_cvt_pk_bf16_f32 v77, v0, v82
	v_sub_f32_e32 v0, v112, v96
	v_mul_f32_e32 v0, 0x3fb8aa3b, v0
	v_cvt_pk_bf16_f32 v76, v2, v78
	v_exp_f32_e32 v2, v0
	v_sub_f32_e32 v0, v108, v96
	v_mul_f32_e32 v0, 0x3fb8aa3b, v0
	v_cvt_pk_bf16_f32 v78, v1, v79
	v_cvt_pk_bf16_f32 v79, v84, v80
	v_exp_f32_e32 v82, v0
	v_sub_f32_e32 v0, v113, v96
	v_sub_f32_e32 v80, v109, v96
	v_mul_f32_e32 v0, 0x3fb8aa3b, v0
	v_mul_f32_e32 v80, 0x3fb8aa3b, v80
	v_exp_f32_e32 v0, v0
	v_exp_f32_e32 v86, v80
	v_add_f32_e32 v1, v2, v82
	v_pk_add_f32 v[80:81], v[0:1], v[86:87]
	s_nop 0
	v_pk_add_f32 v[84:85], v[80:81], v[80:81] op_sel_hi:[0,1]
	v_sub_f32_e32 v80, v110, v96
	v_mul_f32_e32 v80, 0x3fb8aa3b, v80
	v_exp_f32_e32 v83, v80
	v_sub_f32_e32 v80, v115, v96
	v_sub_f32_e32 v1, v114, v96
	v_mul_f32_e32 v80, 0x3fb8aa3b, v80
	v_mul_f32_e32 v1, 0x3fb8aa3b, v1
	v_exp_f32_e32 v88, v80
	v_sub_f32_e32 v80, v152, v96
	v_exp_f32_e32 v1, v1
	v_mul_f32_e32 v80, 0x3fb8aa3b, v80
	v_exp_f32_e32 v84, v80
	v_add_f32_e32 v89, v1, v83
	v_pk_add_f32 v[80:81], v[88:89], v[84:85]
	s_nop 0
	v_pk_add_f32 v[90:91], v[80:81], v[80:81] op_sel_hi:[0,1]
	v_cvt_pk_bf16_f32 v81, v0, v86
	v_sub_f32_e32 v0, v104, v96
	v_mul_f32_e32 v0, 0x3fb8aa3b, v0
	v_cvt_pk_bf16_f32 v80, v2, v82
	v_exp_f32_e32 v2, v0
	v_sub_f32_e32 v0, v100, v96
	v_mul_f32_e32 v0, 0x3fb8aa3b, v0
	v_cvt_pk_bf16_f32 v82, v1, v83
	v_cvt_pk_bf16_f32 v83, v88, v84
	v_exp_f32_e32 v86, v0
	v_sub_f32_e32 v0, v105, v96
	v_sub_f32_e32 v84, v111, v96
	v_mul_f32_e32 v0, 0x3fb8aa3b, v0
	v_mul_f32_e32 v84, 0x3fb8aa3b, v84
	v_exp_f32_e32 v0, v0
	v_exp_f32_e32 v90, v84
	v_add_f32_e32 v1, v2, v86
	v_pk_add_f32 v[84:85], v[0:1], v[90:91]
	s_nop 0
	v_pk_add_f32 v[88:89], v[84:85], v[84:85] op_sel_hi:[0,1]
	v_sub_f32_e32 v84, v102, v96
	v_mul_f32_e32 v84, 0x3fb8aa3b, v84
	v_exp_f32_e32 v87, v84
	v_sub_f32_e32 v84, v107, v96
	v_sub_f32_e32 v1, v106, v96
	v_mul_f32_e32 v84, 0x3fb8aa3b, v84
	v_mul_f32_e32 v1, 0x3fb8aa3b, v1
	v_exp_f32_e32 v104, v84
	v_sub_f32_e32 v84, v153, v96
	v_exp_f32_e32 v1, v1
	v_mul_f32_e32 v84, 0x3fb8aa3b, v84
	v_exp_f32_e32 v88, v84
	v_add_f32_e32 v105, v1, v87
	v_pk_add_f32 v[84:85], v[104:105], v[88:89]
	s_nop 0
	v_pk_add_f32 v[106:107], v[84:85], v[84:85] op_sel_hi:[0,1]
	v_cvt_pk_bf16_f32 v85, v0, v90
	v_sub_f32_e32 v0, v101, v96
	v_mul_f32_e32 v0, 0x3fb8aa3b, v0
	v_cvt_pk_bf16_f32 v84, v2, v86
	v_exp_f32_e32 v2, v0
	v_sub_f32_e32 v0, v92, v96
	v_mul_f32_e32 v0, 0x3fb8aa3b, v0
	v_cvt_pk_bf16_f32 v86, v1, v87
	v_cvt_pk_bf16_f32 v87, v104, v88
	v_exp_f32_e32 v90, v0
	v_sub_f32_e32 v0, v97, v96
	v_sub_f32_e32 v88, v103, v96
	v_mul_f32_e32 v0, 0x3fb8aa3b, v0
	v_mul_f32_e32 v88, 0x3fb8aa3b, v88
	v_exp_f32_e32 v0, v0
	v_exp_f32_e32 v106, v88
	v_add_f32_e32 v1, v2, v90
	v_sub_f32_e32 v92, v99, v96
	v_mul_f32_e32 v92, 0x3fb8aa3b, v92
	v_pk_add_f32 v[88:89], v[0:1], v[106:107]
	v_sub_f32_e32 v1, v98, v96
	v_pk_add_f32 v[100:101], v[88:89], v[88:89] op_sel_hi:[0,1]
	v_sub_f32_e32 v88, v154, v96
	v_mul_f32_e32 v88, 0x3fb8aa3b, v88
	v_exp_f32_e32 v91, v88
	v_sub_f32_e32 v88, v159, v96
	v_mul_f32_e32 v88, 0x3fb8aa3b, v88
	v_mul_f32_e32 v1, 0x3fb8aa3b, v1
	v_exp_f32_e32 v102, v88
	v_sub_f32_e32 v88, v161, v96
	v_exp_f32_e32 v1, v1
	v_mul_f32_e32 v88, 0x3fb8aa3b, v88
	v_exp_f32_e32 v100, v88
	v_add_f32_e32 v103, v1, v91
	v_pk_add_f32 v[88:89], v[102:103], v[100:101]
	s_nop 0
	v_pk_add_f32 v[104:105], v[88:89], v[88:89] op_sel_hi:[0,1]
	v_cvt_pk_bf16_f32 v89, v0, v106
	v_sub_f32_e32 v0, v93, v96
	v_mul_f32_e32 v0, 0x3fb8aa3b, v0
	v_cvt_pk_bf16_f32 v88, v2, v90
	v_exp_f32_e32 v2, v0
	v_sub_f32_e32 v0, v94, v96
	v_mul_f32_e32 v0, 0x3fb8aa3b, v0
	v_exp_f32_e32 v94, v0
	v_sub_f32_e32 v0, v95, v96
	v_mul_f32_e32 v0, 0x3fb8aa3b, v0
	v_exp_f32_e32 v0, v0
	v_exp_f32_e32 v104, v92
	v_cvt_pk_bf16_f32 v90, v1, v91
	v_add_f32_e32 v1, v2, v94
	v_cvt_pk_bf16_f32 v91, v102, v100
	v_pk_add_f32 v[92:93], v[0:1], v[104:105]
	v_sub_f32_e32 v1, v160, v96
	v_pk_add_f32 v[98:99], v[92:93], v[92:93] op_sel_hi:[0,1]
	v_sub_f32_e32 v92, v162, v96
	v_mul_f32_e32 v92, 0x3fb8aa3b, v92
	v_exp_f32_e32 v95, v92
	v_sub_f32_e32 v92, v177, v96
	v_mul_f32_e32 v92, 0x3fb8aa3b, v92
	v_mul_f32_e32 v1, 0x3fb8aa3b, v1
	v_exp_f32_e32 v100, v92
	v_sub_f32_e32 v92, v178, v96
	v_exp_f32_e32 v1, v1
	v_mul_f32_e32 v92, 0x3fb8aa3b, v92
	v_exp_f32_e32 v98, v92
	v_add_f32_e32 v101, v1, v95
	v_pk_add_f32 v[92:93], v[100:101], v[98:99]
	s_nop 0
	v_pk_add_f32 v[102:103], v[92:93], v[92:93] op_sel_hi:[0,1]
	v_cvt_pk_bf16_f32 v93, v0, v104
	v_sub_f32_e32 v0, v155, v96
	v_mul_f32_e32 v0, 0x3fb8aa3b, v0
	v_cvt_pk_bf16_f32 v92, v2, v94
	v_exp_f32_e32 v2, v0
	v_sub_f32_e32 v0, v158, v96
	v_mul_f32_e32 v0, 0x3fb8aa3b, v0
	v_cvt_pk_bf16_f32 v94, v1, v95
	v_cvt_pk_bf16_f32 v95, v100, v98
	v_exp_f32_e32 v97, v0
	v_sub_f32_e32 v0, v163, v96
	v_sub_f32_e32 v98, v176, v96
	v_mul_f32_e32 v0, 0x3fb8aa3b, v0
	v_mul_f32_e32 v98, 0x3fb8aa3b, v98
	v_exp_f32_e32 v0, v0
	v_exp_f32_e32 v102, v98
	v_add_f32_e32 v1, v2, v97
	v_pk_add_f32 v[98:99], v[0:1], v[102:103]
	s_nop 0
	v_pk_add_f32 v[104:105], v[98:99], v[98:99] op_sel_hi:[0,1]
	v_sub_f32_e32 v98, v180, v96
	v_mul_f32_e32 v98, 0x3fb8aa3b, v98
	v_exp_f32_e32 v100, v98
	v_sub_f32_e32 v98, v151, v96
	v_sub_f32_e32 v1, v179, v96
	v_mul_f32_e32 v98, 0x3fb8aa3b, v98
	v_mul_f32_e32 v1, 0x3fb8aa3b, v1
	v_exp_f32_e32 v106, v98
	v_sub_f32_e32 v98, v181, v96
	v_exp_f32_e32 v1, v1
	v_mul_f32_e32 v98, 0x3fb8aa3b, v98
	v_exp_f32_e32 v104, v98
	v_add_f32_e32 v107, v1, v100
	v_cvt_pk_bf16_f32 v100, v1, v100
	v_pk_add_f32 v[98:99], v[106:107], v[104:105]
	v_cvt_pk_bf16_f32 v101, v106, v104
	v_add_f32_e32 v103, v98, v99
	v_cvt_pk_bf16_f32 v99, v0, v102
	v_sub_f32_e32 v0, v64, v96
	v_cvt_pk_bf16_f32 v98, v2, v97
	v_mul_f32_e32 v0, 0x3fb8aa3b, v0
	v_sub_f32_e32 v2, v65, v96
	v_exp_f32_e32 v0, v0
	v_mul_f32_e32 v2, 0x3fb8aa3b, v2
	v_sub_f32_e32 v64, v66, v96
	v_exp_f32_e32 v2, v2
	v_mul_f32_e32 v64, 0x3fb8aa3b, v64
	v_sub_f32_e32 v65, v67, v96
	v_exp_f32_e32 v64, v64
	v_mul_f32_e32 v65, 0x3fb8aa3b, v65
	v_exp_f32_e32 v65, v65
	v_add_f32_e32 v1, v0, v103
	v_add_f32_e32 v1, v2, v1
	v_add_f32_e32 v1, v64, v1
	v_add_f32_e32 v66, v65, v1
	v_cvt_pk_bf16_f32 v0, v0, v2
	ds_bpermute_b32 v2, v157, v66
	v_cvt_pk_bf16_f32 v1, v64, v65
	v_sub_f32_e32 v65, v145, v96
	v_mul_f32_e32 v65, 0x3fb8aa3b, v65
	v_exp_f32_e32 v96, v65
	s_waitcnt lgkmcnt(0)
	v_add_f32_e32 v2, v66, v2
	ds_bpermute_b32 v64, v156, v2
	v_readlane_b32 s0, v254, 58
	s_waitcnt lgkmcnt(0)
	v_add_f32_e32 v97, v2, v64
	v_mov_b32_e32 v2, s0
	s_movk_i32 s0, 0x320
	v_mad_u32_u24 v138, v142, s0, v2
	v_add_u32_e32 v2, v138, v144
	ds_read_b128 v[64:67], v2
	ds_read_b128 v[102:105], v2 offset:12800
	ds_read_b128 v[106:109], v2 offset:25600
	ds_read_b128 v[110:113], v2 offset:38400
	ds_read_b128 v[114:117], v2 offset:64
	ds_read_b128 v[118:121], v2 offset:12864
	ds_read_b128 v[122:125], v2 offset:25664
	ds_read_b128 v[126:129], v2 offset:38464
	ds_read_b128 v[130:133], v2 offset:128
	ds_read_b128 v[134:137], v2 offset:12928
	ds_read_b128 v[144:147], v2 offset:25728
	ds_read_b128 v[148:151], v2 offset:38528
	s_waitcnt lgkmcnt(11)
	v_mfma_f32_16x16x32_bf16 v[64:67], v[64:67], v[60:63], 0
	s_waitcnt lgkmcnt(10)
	v_mfma_f32_16x16x32_bf16 v[102:105], v[102:105], v[60:63], 0
	s_waitcnt lgkmcnt(9)
	v_mfma_f32_16x16x32_bf16 v[106:109], v[106:109], v[60:63], 0
	s_waitcnt lgkmcnt(8)
	v_mfma_f32_16x16x32_bf16 v[60:63], v[110:113], v[60:63], 0
	s_waitcnt lgkmcnt(7)
	v_mfma_f32_16x16x32_bf16 v[64:67], v[114:117], v[68:71], v[64:67]
	s_waitcnt lgkmcnt(6)
	v_mfma_f32_16x16x32_bf16 v[102:105], v[118:121], v[68:71], v[102:105]
	s_waitcnt lgkmcnt(5)
	v_mfma_f32_16x16x32_bf16 v[106:109], v[122:125], v[68:71], v[106:109]
	s_waitcnt lgkmcnt(4)
	v_mfma_f32_16x16x32_bf16 v[60:63], v[126:129], v[68:71], v[60:63]
	s_waitcnt lgkmcnt(3)
	v_mfma_f32_16x16x32_bf16 v[64:67], v[130:133], v[72:75], v[64:67]
	s_waitcnt lgkmcnt(2)
	v_mfma_f32_16x16x32_bf16 v[68:71], v[134:137], v[72:75], v[102:105]
	s_waitcnt lgkmcnt(1)
	v_mfma_f32_16x16x32_bf16 v[102:105], v[144:147], v[72:75], v[106:109]
	s_waitcnt lgkmcnt(0)
	v_mfma_f32_16x16x32_bf16 v[60:63], v[148:151], v[72:75], v[60:63]
	ds_read_b128 v[72:75], v2 offset:12992
	ds_read_b128 v[106:109], v2 offset:13056
	ds_read_b128 v[110:113], v2 offset:38592
	ds_read_b128 v[114:117], v2 offset:38656
	ds_read_b128 v[118:121], v2 offset:256
	ds_read_b128 v[122:125], v2 offset:320
	ds_read_b128 v[126:129], v2 offset:25792
	ds_read_b128 v[130:133], v2 offset:13120
	ds_read_b128 v[134:137], v2 offset:25856
	ds_read_b128 v[144:147], v2 offset:25920
	ds_read_b128 v[148:151], v2 offset:192
	ds_read_b128 v[152:155], v2 offset:38720
	s_waitcnt lgkmcnt(1)
	v_mfma_f32_16x16x32_bf16 v[64:67], v[148:151], v[76:79], v[64:67]
	v_mfma_f32_16x16x32_bf16 v[68:71], v[72:75], v[76:79], v[68:71]
	v_mfma_f32_16x16x32_bf16 v[72:75], v[126:129], v[76:79], v[102:105]
	v_mfma_f32_16x16x32_bf16 v[60:63], v[110:113], v[76:79], v[60:63]
	v_mfma_f32_16x16x32_bf16 v[64:67], v[118:121], v[80:83], v[64:67]
	v_mfma_f32_16x16x32_bf16 v[68:71], v[106:109], v[80:83], v[68:71]
	v_mfma_f32_16x16x32_bf16 v[72:75], v[134:137], v[80:83], v[72:75]
	v_mfma_f32_16x16x32_bf16 v[60:63], v[114:117], v[80:83], v[60:63]
	v_mfma_f32_16x16x32_bf16 v[64:67], v[122:125], v[84:87], v[64:67]
	v_mfma_f32_16x16x32_bf16 v[68:71], v[130:133], v[84:87], v[68:71]
	v_mfma_f32_16x16x32_bf16 v[72:75], v[144:147], v[84:87], v[72:75]
	s_waitcnt lgkmcnt(0)
	v_mfma_f32_16x16x32_bf16 v[60:63], v[152:155], v[84:87], v[60:63]
	ds_read_b128 v[76:79], v2 offset:13184
	ds_read_b128 v[80:83], v2 offset:13248
	ds_read_b128 v[84:87], v2 offset:38784
	ds_read_b128 v[102:105], v2 offset:38848
	ds_read_b128 v[106:109], v2 offset:448
	ds_read_b128 v[110:113], v2 offset:512
	ds_read_b128 v[114:117], v2 offset:25984
	ds_read_b128 v[118:121], v2 offset:13312
	ds_read_b128 v[122:125], v2 offset:26048
	ds_read_b128 v[126:129], v2 offset:26112
	ds_read_b128 v[130:133], v2 offset:384
	ds_read_b128 v[134:137], v2 offset:38912
	s_waitcnt lgkmcnt(1)
	v_mfma_f32_16x16x32_bf16 v[64:67], v[130:133], v[88:91], v[64:67]
	v_mfma_f32_16x16x32_bf16 v[68:71], v[76:79], v[88:91], v[68:71]
	v_mfma_f32_16x16x32_bf16 v[72:75], v[114:117], v[88:91], v[72:75]
	v_mfma_f32_16x16x32_bf16 v[60:63], v[84:87], v[88:91], v[60:63]
	v_mfma_f32_16x16x32_bf16 v[64:67], v[106:109], v[92:95], v[64:67]
	v_mfma_f32_16x16x32_bf16 v[68:71], v[80:83], v[92:95], v[68:71]
	v_mfma_f32_16x16x32_bf16 v[72:75], v[122:125], v[92:95], v[72:75]
	v_mfma_f32_16x16x32_bf16 v[60:63], v[102:105], v[92:95], v[60:63]
	v_mfma_f32_16x16x32_bf16 v[64:67], v[110:113], v[98:101], v[64:67]
	v_mfma_f32_16x16x32_bf16 v[68:71], v[118:121], v[98:101], v[68:71]
	v_mfma_f32_16x16x32_bf16 v[72:75], v[126:129], v[98:101], v[72:75]
	s_waitcnt lgkmcnt(0)
	v_mfma_f32_16x16x32_bf16 v[60:63], v[134:137], v[98:101], v[60:63]
	v_add_u32_e32 v76, v138, v143
	v_add_u32_e32 v84, 0x100, v76
	ds_read2st64_b64 v[76:79], v84 offset0:1 offset1:26
	v_mov_b32_e32 v2, v3
	v_mov_b32_e32 v82, v3
	v_mov_b32_e32 v83, v3
	s_waitcnt lgkmcnt(0)
	v_mov_b32_e32 v80, v76
	v_mov_b32_e32 v81, v77
	v_mov_b32_e32 v76, v78
	v_mov_b32_e32 v77, v79
	v_mov_b32_e32 v78, v3
	v_mov_b32_e32 v79, v3
	v_mfma_f32_16x16x32_bf16 v[64:67], v[80:83], v[0:3], v[64:67]
	s_nop 0
	v_mfma_f32_16x16x32_bf16 v[68:71], v[76:79], v[0:3], v[68:71]
	ds_read2st64_b64 v[76:79], v84 offset0:51 offset1:76
	s_waitcnt lgkmcnt(0)
	v_mov_b32_e32 v80, v76
	v_mov_b32_e32 v81, v77
	v_mov_b32_e32 v76, v78
	v_mov_b32_e32 v77, v79
	v_mov_b32_e32 v78, v3
	v_mov_b32_e32 v79, v3
	v_mfma_f32_16x16x32_bf16 v[72:75], v[80:83], v[0:3], v[72:75]
	v_and_b32_e32 v80, 16, v140
	v_mfma_f32_16x16x32_bf16 v[60:63], v[76:79], v[0:3], v[60:63]
	v_add_f32_e32 v0, v96, v97
	v_div_scale_f32 v2, s[0:1], v0, v0, 1.0
	v_rcp_f32_e32 v76, v2
	v_or_b32_e32 v1, s2, v142
	v_mul_u32_u24_e32 v1, 0x600, v1
	s_mov_b32 s0, 0x3000000
	v_fma_f32 v77, -v2, v76, 1.0
	v_fmac_f32_e32 v76, v77, v76
	v_div_scale_f32 v77, vcc, 1.0, v0, 1.0
	v_mul_f32_e32 v78, v77, v76
	v_fma_f32 v79, -v2, v78, v77
	v_fmac_f32_e32 v78, v79, v76
	v_fma_f32 v2, -v2, v78, v77
	v_div_fmas_f32 v2, v2, v76, v78
	v_div_fixup_f32 v0, v2, v0, 1.0
	v_lshlrev_b32_e32 v2, 2, v141
	v_and_b32_e32 v76, -8, v2
	v_lshlrev_b32_e32 v2, 1, v1
	v_lshl_add_u64 v[78:79], s[96:97], 0, v[2:3]
	v_pk_mul_f32 v[66:67], v[66:67], v[0:1] op_sel_hi:[1,0]
	v_pk_mul_f32 v[64:65], v[64:65], v[0:1] op_sel_hi:[1,0]
	v_pk_mul_f32 v[68:69], v[68:69], v[0:1] op_sel_hi:[1,0]
	v_cvt_pk_bf16_f32 v64, v64, v65
	v_cvt_pk_bf16_f32 v65, v66, v67
	v_cvt_pk_bf16_f32 v66, v68, v69
	v_lshlrev_b32_e32 v2, 1, v80
	v_lshl_add_u64 v[68:69], v[78:79], 0, s[46:47]
	v_ashrrev_i32_e32 v77, 31, v76
	v_lshl_add_u64 v[68:69], v[68:69], 0, v[2:3]
	v_pk_mul_f32 v[70:71], v[70:71], v[0:1] op_sel_hi:[1,0]
	v_lshl_add_u64 v[68:69], v[76:77], 1, v[68:69]
	v_cvt_pk_bf16_f32 v67, v70, v71
	v_add_co_u32_e32 v68, vcc, s0, v68
	v_permlane16_swap_b32_e32 v64, v66
	v_permlane16_swap_b32_e32 v65, v67
	v_addc_co_u32_e32 v69, vcc, 0, v69, vcc
	global_store_dwordx4 v[68:69], v[64:67], off offset:2048
	v_pk_mul_f32 v[70:71], v[0:1], v[62:63] op_sel_hi:[0,1]
	v_cvt_pk_bf16_f32 v63, v70, v71
	v_pk_mul_f32 v[64:65], v[74:75], v[0:1] op_sel_hi:[1,0]
	v_pk_mul_f32 v[66:67], v[72:73], v[0:1] op_sel_hi:[1,0]
	v_pk_mul_f32 v[0:1], v[0:1], v[60:61] op_sel_hi:[0,1]
	v_cvt_pk_bf16_f32 v60, v66, v67
	v_cvt_pk_bf16_f32 v61, v64, v65
	v_cvt_pk_bf16_f32 v62, v0, v1
	s_nop 1
	v_permlane16_swap_b32_e32 v60, v62
	v_permlane16_swap_b32_e32 v61, v63
	global_store_dwordx4 v[68:69], v[60:63], off offset:2112
	s_branch .LBB0_410
